# leading wave half's extra align barrier issued after its second epilogue store instead of at the epilogue start (4 compiler epilogues)
# speedup vs baseline: 1.0001x; 1.0001x over previous
; #define PG8_STAGE(bufoff, gbase, voff) do { _Pragma("unroll") for (int _i = 0; _i < 2; ++_i) \
;         __builtin_amdgcn_global_load_lds((const unsigned*)((const char*)(gbase) + (voff)[_i]), (PG8_LAS unsigned*)(lds + (bufoff) + ldsw + _i * 8192), 16, 0, 0); } while (0)
; #define PG8_LDA(dst, b, h) do { _Pragma("unroll") for (int m = 0; m < 4; ++m) _Pragma("unroll") for (int k = 0; k < 2; ++k) dst[m][k] = *(const PG8_LAS bf16x8*)(lds + PG8_SA(b, h) + aoff + m * 2048 + k * 1024); } while (0)
; #define PG8_LDB(dst, b, h) do { _Pragma("unroll") for (int n = 0; n < 2; ++n) _Pragma("unroll") for (int k = 0; k < 2; ++k) dst[n][k] = *(const PG8_LAS bf16x8*)(lds + PG8_SB(b, h) + boff + n * 2048 + k * 1024); } while (0)
; #define PG8_MMA(ai, bj, At, Bt) do { __builtin_amdgcn_s_setprio(1); _Pragma("unroll") for (int m = 0; m < 4; ++m) _Pragma("unroll") for (int n = 0; n < 2; ++n) _Pragma("unroll") for (int k = 0; k < 2; ++k) \
;         acc[ai][bj][m][n] = __builtin_amdgcn_mfma_f32_16x16x32_bf16(Bt[n][k], At[m][k], acc[ai][bj][m][n], 0, 0, 0); __builtin_amdgcn_s_setprio(0); } while (0)
; #define PG8_WAIT_V(n) asm volatile("s_waitcnt vmcnt(" #n ")" ::: "memory")
; #define PG8_WAIT_L(n) asm volatile("s_waitcnt lgkmcnt(" #n ")" ::: "memory")
; #define PG8_BAR __builtin_amdgcn_s_barrier()
; #define PG8_SCHED __builtin_amdgcn_sched_barrier(0)
; template <class Epi, class Sched, bool ALIGN_EPI = false, bool SP2 = false>
; __device__ __forceinline__ void gemm_phase(PG8_LAS unsigned char* lds, const Gemm g, const Sched& S, const Epi& E) {
;     ...
;             PG8_LDB(B0, 0, 0); PG8_LDB(B1, 0, 1); PG8_SCHED; PG8_LDA(At, 0, 0); PG8_STAGE(PG8_SA(1, 1), a1 + hstep, voffA);
;             PG8_WAIT_V(8); PG8_WAIT_L(0); PG8_BAR; PG8_MMA(0, 0, At, B0); PG8_MMA(0, 1, At, B1); PG8_BAR; PG8_SCHED;
;             PG8_LDA(At, 0, 1); PG8_STAGE(PG8_SB(0, 0), b2, voffB); PG8_STAGE(PG8_SB(0, 1), b2 + hstep, voffB); PG8_STAGE(PG8_SA(0, 0), a2, voffA);
;             PG8_WAIT_V(8); PG8_WAIT_L(0); PG8_BAR; PG8_MMA(1, 0, At, B0); PG8_MMA(1, 1, At, B1); PG8_BAR; PG8_SCHED;
.LBB0_36:
	s_add_u32 s18, s58, 0xffe00080
	s_addc_u32 s19, s59, -1
	s_add_i32 s47, 0, 0x10000
	s_cmpk_eq_i32 s46, 0x7c
	s_cselect_b32 s63, s45, s19
	s_cselect_b32 s62, s73, s18
	v_add_u32_e32 v160, s47, v143
	s_cselect_b32 s19, s37, s79
	s_cselect_b32 s18, s84, s78
	s_add_i32 s80, 0, 0x14000
	ds_read_b128 v[156:159], v160
	ds_read_b128 v[164:167], v160 offset:1024
	ds_read_b128 v[168:171], v160 offset:2048
	ds_read_b128 v[172:175], v160 offset:3072
	v_add_u32_e32 v160, s80, v143
	ds_read_b128 v[176:179], v160
	ds_read_b128 v[180:183], v160 offset:1024
	ds_read_b128 v[184:187], v160 offset:2048
	ds_read_b128 v[204:207], v160 offset:3072
	v_lshl_add_u64 v[160:161], s[58:59], 0, v[152:153]
	s_add_i32 m0, s5, 0xc000
	ds_read_b128 v[208:211], v163
	ds_read_b128 v[212:215], v163 offset:1024
	ds_read_b128 v[216:219], v163 offset:2048
	ds_read_b128 v[220:223], v163 offset:3072
	ds_read_b128 v[224:227], v163 offset:4096
	ds_read_b128 v[228:231], v163 offset:5120
	ds_read_b128 v[232:235], v163 offset:6144
	ds_read_b128 v[236:239], v163 offset:7168
	global_load_lds_dwordx4 v[160:161], off
	v_lshl_add_u64 v[160:161], s[58:59], 0, v[154:155]
	s_add_i32 m0, s5, 0xe000
	s_nop 0
	global_load_lds_dwordx4 v[160:161], off
	s_nop 0
	s_waitcnt vmcnt(8)
	s_waitcnt lgkmcnt(0)
	s_setprio 1
	s_barrier
	v_mfma_f32_16x16x32_bf16 v[126:129], v[156:159], v[208:211], v[126:129]
	v_mfma_f32_16x16x32_bf16 v[122:125], v[168:171], v[208:211], v[122:125]
	v_mfma_f32_16x16x32_bf16 v[110:113], v[156:159], v[216:219], v[110:113]
	v_mfma_f32_16x16x32_bf16 v[106:109], v[168:171], v[216:219], v[106:109]
	v_mfma_f32_16x16x32_bf16 v[94:97], v[156:159], v[224:227], v[94:97]
	v_mfma_f32_16x16x32_bf16 v[90:93], v[168:171], v[224:227], v[90:93]
	v_mfma_f32_16x16x32_bf16 v[78:81], v[156:159], v[232:235], v[78:81]
	v_mfma_f32_16x16x32_bf16 v[74:77], v[168:171], v[232:235], v[74:77]
	s_setprio 0
	s_setprio 1
	v_mfma_f32_16x16x32_bf16 v[126:129], v[164:167], v[212:215], v[126:129]
	v_mfma_f32_16x16x32_bf16 v[122:125], v[172:175], v[212:215], v[122:125]
	v_mfma_f32_16x16x32_bf16 v[110:113], v[164:167], v[220:223], v[110:113]
	v_mfma_f32_16x16x32_bf16 v[106:109], v[172:175], v[220:223], v[106:109]
	v_mfma_f32_16x16x32_bf16 v[94:97], v[164:167], v[228:231], v[94:97]
	v_mfma_f32_16x16x32_bf16 v[90:93], v[172:175], v[228:231], v[90:93]
	v_mfma_f32_16x16x32_bf16 v[78:81], v[164:167], v[236:239], v[78:81]
	v_mfma_f32_16x16x32_bf16 v[74:77], v[172:175], v[236:239], v[74:77]
	s_setprio 0
	s_setprio 1
	v_mfma_f32_16x16x32_bf16 v[118:121], v[176:179], v[208:211], v[118:121]
	v_mfma_f32_16x16x32_bf16 v[114:117], v[184:187], v[208:211], v[114:117]
	v_mfma_f32_16x16x32_bf16 v[102:105], v[176:179], v[216:219], v[102:105]
	v_mfma_f32_16x16x32_bf16 v[98:101], v[184:187], v[216:219], v[98:101]
	v_mfma_f32_16x16x32_bf16 v[86:89], v[176:179], v[224:227], v[86:89]
	v_mfma_f32_16x16x32_bf16 v[82:85], v[184:187], v[224:227], v[82:85]
	v_mfma_f32_16x16x32_bf16 v[70:73], v[176:179], v[232:235], v[70:73]
	v_mfma_f32_16x16x32_bf16 v[66:69], v[184:187], v[232:235], v[66:69]
	s_setprio 0
	s_setprio 1
	v_mfma_f32_16x16x32_bf16 v[118:121], v[180:183], v[212:215], v[118:121]
	v_mfma_f32_16x16x32_bf16 v[114:117], v[204:207], v[212:215], v[114:117]
	v_mfma_f32_16x16x32_bf16 v[102:105], v[180:183], v[220:223], v[102:105]
	v_mfma_f32_16x16x32_bf16 v[98:101], v[204:207], v[220:223], v[98:101]
	v_mfma_f32_16x16x32_bf16 v[86:89], v[180:183], v[228:231], v[86:89]
	v_mfma_f32_16x16x32_bf16 v[82:85], v[204:207], v[228:231], v[82:85]
	v_mfma_f32_16x16x32_bf16 v[70:73], v[180:183], v[236:239], v[70:73]
	v_mfma_f32_16x16x32_bf16 v[66:69], v[204:207], v[236:239], v[66:69]
	s_setprio 0
	s_barrier
	s_add_i32 s47, s47, s4
	v_lshl_add_u64 v[160:161], s[18:19], 0, v[148:149]
	s_mov_b32 m0, s47
	ds_read_b128 v[208:211], v163 offset:16384
	ds_read_b128 v[212:215], v163 offset:17408
	ds_read_b128 v[216:219], v163 offset:18432
	ds_read_b128 v[220:223], v163 offset:19456
	ds_read_b128 v[224:227], v163 offset:20480
	ds_read_b128 v[228:231], v163 offset:21504
	ds_read_b128 v[232:235], v163 offset:22528
	ds_read_b128 v[236:239], v163 offset:23552
	global_load_lds_dwordx4 v[160:161], off
	s_add_i32 m0, s47, 0x2000
	s_add_u32 s76, s18, 0x200000
	v_lshl_add_u64 v[240:241], s[18:19], 0, v[144:145]
	s_addc_u32 s77, s19, 0
	s_add_i32 s47, s80, s4
	global_load_lds_dwordx4 v[240:241], off
	v_lshl_add_u64 v[242:243], s[76:77], 0, v[148:149]
	s_mov_b32 m0, s47
	v_lshl_add_u64 v[244:245], s[62:63], 0, v[146:147]
	global_load_lds_dwordx4 v[242:243], off
	v_lshl_add_u64 v[242:243], s[76:77], 0, v[144:145]
	s_add_i32 m0, s47, 0x2000
	s_nop 0
	global_load_lds_dwordx4 v[242:243], off
	v_lshl_add_u64 v[242:243], s[62:63], 0, v[150:151]
	s_mov_b32 m0, s5
	s_nop 0
	global_load_lds_dwordx4 v[242:243], off
	s_mov_b32 m0, s30
	s_nop 0
	global_load_lds_dwordx4 v[244:245], off
	s_waitcnt vmcnt(8)
	s_waitcnt lgkmcnt(0)
	s_setprio 1
	s_barrier
; #define PG8_STAGE(bufoff, gbase, voff) do { _Pragma("unroll") for (int _i = 0; _i < 2; ++_i) \
;         __builtin_amdgcn_global_load_lds((const unsigned*)((const char*)(gbase) + (voff)[_i]), (PG8_LAS unsigned*)(lds + (bufoff) + ldsw + _i * 8192), 16, 0, 0); } while (0)
; #define PG8_LDA(dst, b, h) do { _Pragma("unroll") for (int m = 0; m < 4; ++m) _Pragma("unroll") for (int k = 0; k < 2; ++k) dst[m][k] = *(const PG8_LAS bf16x8*)(lds + PG8_SA(b, h) + aoff + m * 2048 + k * 1024); } while (0)
; #define PG8_LDB(dst, b, h) do { _Pragma("unroll") for (int n = 0; n < 2; ++n) _Pragma("unroll") for (int k = 0; k < 2; ++k) dst[n][k] = *(const PG8_LAS bf16x8*)(lds + PG8_SB(b, h) + boff + n * 2048 + k * 1024); } while (0)
; #define PG8_MMA(ai, bj, At, Bt) do { __builtin_amdgcn_s_setprio(1); _Pragma("unroll") for (int m = 0; m < 4; ++m) _Pragma("unroll") for (int n = 0; n < 2; ++n) _Pragma("unroll") for (int k = 0; k < 2; ++k) \
;         acc[ai][bj][m][n] = __builtin_amdgcn_mfma_f32_16x16x32_bf16(Bt[n][k], At[m][k], acc[ai][bj][m][n], 0, 0, 0); __builtin_amdgcn_s_setprio(0); } while (0)
; #define PG8_WAIT_V(n) asm volatile("s_waitcnt vmcnt(" #n ")" ::: "memory")
; #define PG8_WAIT_L(n) asm volatile("s_waitcnt lgkmcnt(" #n ")" ::: "memory")
; #define PG8_BAR __builtin_amdgcn_s_barrier()
; #define PG8_SCHED __builtin_amdgcn_sched_barrier(0)
; template <class Epi, class Sched, bool ALIGN_EPI = false, bool SP2 = false>
; __device__ __forceinline__ void gemm_phase(PG8_LAS unsigned char* lds, const Gemm g, const Sched& S, const Epi& E) {
;     ...
;             PG8_WAIT_V(8); PG8_WAIT_L(0); PG8_BAR; PG8_MMA(1, 0, At, B0); PG8_MMA(1, 1, At, B1); PG8_BAR; PG8_SCHED;
;             PG8_LDB(B0, 1, 0); PG8_LDB(B1, 1, 1); PG8_SCHED; PG8_LDA(At, 1, 0); PG8_STAGE(PG8_SA(0, 1), a2 + hstep, voffA);
;             PG8_WAIT_V(8); PG8_WAIT_L(0); PG8_BAR; PG8_MMA(0, 0, At, B0); PG8_MMA(0, 1, At, B1); PG8_BAR; PG8_SCHED;
	v_mfma_f32_16x16x32_bf16 v[62:65], v[156:159], v[208:211], v[62:65]
	v_mfma_f32_16x16x32_bf16 v[58:61], v[168:171], v[208:211], v[58:61]
	v_mfma_f32_16x16x32_bf16 v[46:49], v[156:159], v[216:219], v[46:49]
	v_mfma_f32_16x16x32_bf16 v[42:45], v[168:171], v[216:219], v[42:45]
	v_mfma_f32_16x16x32_bf16 v[30:33], v[156:159], v[224:227], v[30:33]
	v_mfma_f32_16x16x32_bf16 v[26:29], v[168:171], v[224:227], v[26:29]
	v_mfma_f32_16x16x32_bf16 v[14:17], v[156:159], v[232:235], v[14:17]
	v_mfma_f32_16x16x32_bf16 v[10:13], v[168:171], v[232:235], v[10:13]
	v_mfma_f32_16x16x32_bf16 v[62:65], v[164:167], v[212:215], v[62:65]
	v_mfma_f32_16x16x32_bf16 v[58:61], v[172:175], v[212:215], v[58:61]
	v_mfma_f32_16x16x32_bf16 v[46:49], v[164:167], v[220:223], v[46:49]
	v_mfma_f32_16x16x32_bf16 v[42:45], v[172:175], v[220:223], v[42:45]
	v_mfma_f32_16x16x32_bf16 v[30:33], v[164:167], v[228:231], v[30:33]
	v_mfma_f32_16x16x32_bf16 v[26:29], v[172:175], v[228:231], v[26:29]
	v_mfma_f32_16x16x32_bf16 v[14:17], v[164:167], v[236:239], v[14:17]
	v_mfma_f32_16x16x32_bf16 v[10:13], v[172:175], v[236:239], v[10:13]
	v_mfma_f32_16x16x32_bf16 v[54:57], v[176:179], v[208:211], v[54:57]
	v_mfma_f32_16x16x32_bf16 v[50:53], v[184:187], v[208:211], v[50:53]
	v_mfma_f32_16x16x32_bf16 v[38:41], v[176:179], v[216:219], v[38:41]
	v_mfma_f32_16x16x32_bf16 v[34:37], v[184:187], v[216:219], v[34:37]
	v_mfma_f32_16x16x32_bf16 v[22:25], v[176:179], v[224:227], v[22:25]
	v_mfma_f32_16x16x32_bf16 v[18:21], v[184:187], v[224:227], v[18:21]
	v_mfma_f32_16x16x32_bf16 v[6:9], v[176:179], v[232:235], v[6:9]
	v_mfma_f32_16x16x32_bf16 v[2:5], v[184:187], v[232:235], v[2:5]
	v_mfma_f32_16x16x32_bf16 v[54:57], v[180:183], v[212:215], v[54:57]
	v_mfma_f32_16x16x32_bf16 v[50:53], v[204:207], v[212:215], v[50:53]
	v_mfma_f32_16x16x32_bf16 v[38:41], v[180:183], v[220:223], v[38:41]
	v_mfma_f32_16x16x32_bf16 v[34:37], v[204:207], v[220:223], v[34:37]
	v_mfma_f32_16x16x32_bf16 v[22:25], v[180:183], v[228:231], v[22:25]
	v_mfma_f32_16x16x32_bf16 v[18:21], v[204:207], v[228:231], v[18:21]
	v_mfma_f32_16x16x32_bf16 v[6:9], v[180:183], v[236:239], v[6:9]
	v_mfma_f32_16x16x32_bf16 v[2:5], v[204:207], v[236:239], v[2:5]
	s_setprio 0
	s_barrier
	s_add_i32 s47, 0, 0x18000
	s_add_i32 s76, 0, 0x1c000
	v_add_u32_e32 v172, s47, v143
	v_add_u32_e32 v203, s76, v143
	ds_read_b128 v[156:159], v172
	ds_read_b128 v[164:167], v172 offset:1024
	ds_read_b128 v[168:171], v172 offset:2048
	ds_read_b128 v[172:175], v172 offset:3072
	ds_read_b128 v[176:179], v203
	ds_read_b128 v[180:183], v203 offset:1024
	ds_read_b128 v[184:187], v203 offset:2048
	ds_read_b128 v[204:207], v203 offset:3072
	s_add_u32 s62, s62, 0x200000
	s_addc_u32 s63, s63, 0
	s_mov_b32 m0, s57
	v_lshl_add_u64 v[246:247], s[62:63], 0, v[150:151]
	ds_read_b128 v[208:211], v163 offset:32768
	ds_read_b128 v[212:215], v163 offset:33792
	ds_read_b128 v[216:219], v163 offset:34816
	ds_read_b128 v[220:223], v163 offset:35840
	ds_read_b128 v[224:227], v163 offset:36864
	ds_read_b128 v[228:231], v163 offset:37888
	ds_read_b128 v[232:235], v163 offset:38912
	ds_read_b128 v[236:239], v163 offset:39936
	global_load_lds_dwordx4 v[246:247], off
	v_lshl_add_u64 v[246:247], s[62:63], 0, v[146:147]
	s_mov_b32 m0, s67
	s_nop 0
	global_load_lds_dwordx4 v[246:247], off
	s_waitcnt vmcnt(8)
	s_waitcnt lgkmcnt(0)
	s_setprio 1
	s_barrier
	v_mfma_f32_16x16x32_bf16 v[126:129], v[156:159], v[208:211], v[126:129]
	v_mfma_f32_16x16x32_bf16 v[122:125], v[168:171], v[208:211], v[122:125]
	v_mfma_f32_16x16x32_bf16 v[110:113], v[156:159], v[216:219], v[110:113]
	v_mfma_f32_16x16x32_bf16 v[106:109], v[168:171], v[216:219], v[106:109]
	v_mfma_f32_16x16x32_bf16 v[94:97], v[156:159], v[224:227], v[94:97]
	v_mfma_f32_16x16x32_bf16 v[90:93], v[168:171], v[224:227], v[90:93]
	v_mfma_f32_16x16x32_bf16 v[78:81], v[156:159], v[232:235], v[78:81]
	v_mfma_f32_16x16x32_bf16 v[74:77], v[168:171], v[232:235], v[74:77]
	s_setprio 0
	s_setprio 1
	v_mfma_f32_16x16x32_bf16 v[126:129], v[164:167], v[212:215], v[126:129]
	v_mfma_f32_16x16x32_bf16 v[122:125], v[172:175], v[212:215], v[122:125]
	v_mfma_f32_16x16x32_bf16 v[110:113], v[164:167], v[220:223], v[110:113]
	v_mfma_f32_16x16x32_bf16 v[106:109], v[172:175], v[220:223], v[106:109]
	v_mfma_f32_16x16x32_bf16 v[94:97], v[164:167], v[228:231], v[94:97]
	v_mfma_f32_16x16x32_bf16 v[90:93], v[172:175], v[228:231], v[90:93]
	v_mfma_f32_16x16x32_bf16 v[78:81], v[164:167], v[236:239], v[78:81]
	v_mfma_f32_16x16x32_bf16 v[74:77], v[172:175], v[236:239], v[74:77]
	s_setprio 0
	s_setprio 1
	v_mfma_f32_16x16x32_bf16 v[118:121], v[176:179], v[208:211], v[118:121]
	v_mfma_f32_16x16x32_bf16 v[114:117], v[184:187], v[208:211], v[114:117]
	v_mfma_f32_16x16x32_bf16 v[102:105], v[176:179], v[216:219], v[102:105]
	v_mfma_f32_16x16x32_bf16 v[98:101], v[184:187], v[216:219], v[98:101]
	v_mfma_f32_16x16x32_bf16 v[86:89], v[176:179], v[224:227], v[86:89]
	v_mfma_f32_16x16x32_bf16 v[82:85], v[184:187], v[224:227], v[82:85]
	v_mfma_f32_16x16x32_bf16 v[70:73], v[176:179], v[232:235], v[70:73]
	v_mfma_f32_16x16x32_bf16 v[66:69], v[184:187], v[232:235], v[66:69]
	s_setprio 0
	s_setprio 1
	v_mfma_f32_16x16x32_bf16 v[118:121], v[180:183], v[212:215], v[118:121]
	v_mfma_f32_16x16x32_bf16 v[114:117], v[204:207], v[212:215], v[114:117]
	v_mfma_f32_16x16x32_bf16 v[102:105], v[180:183], v[220:223], v[102:105]
	v_mfma_f32_16x16x32_bf16 v[98:101], v[204:207], v[220:223], v[98:101]
	v_mfma_f32_16x16x32_bf16 v[86:89], v[180:183], v[228:231], v[86:89]
	v_mfma_f32_16x16x32_bf16 v[82:85], v[204:207], v[228:231], v[82:85]
	v_mfma_f32_16x16x32_bf16 v[70:73], v[180:183], v[236:239], v[70:73]
	v_mfma_f32_16x16x32_bf16 v[66:69], v[204:207], v[236:239], v[66:69]
	s_setprio 0
	s_barrier
; #define PG8_STAGE(bufoff, gbase, voff) do { _Pragma("unroll") for (int _i = 0; _i < 2; ++_i) \
;         __builtin_amdgcn_global_load_lds((const unsigned*)((const char*)(gbase) + (voff)[_i]), (PG8_LAS unsigned*)(lds + (bufoff) + ldsw + _i * 8192), 16, 0, 0); } while (0)
; #define PG8_LDA(dst, b, h) do { _Pragma("unroll") for (int m = 0; m < 4; ++m) _Pragma("unroll") for (int k = 0; k < 2; ++k) dst[m][k] = *(const PG8_LAS bf16x8*)(lds + PG8_SA(b, h) + aoff + m * 2048 + k * 1024); } while (0)
; #define PG8_MMA(ai, bj, At, Bt) do { __builtin_amdgcn_s_setprio(1); _Pragma("unroll") for (int m = 0; m < 4; ++m) _Pragma("unroll") for (int n = 0; n < 2; ++n) _Pragma("unroll") for (int k = 0; k < 2; ++k) \
;         acc[ai][bj][m][n] = __builtin_amdgcn_mfma_f32_16x16x32_bf16(Bt[n][k], At[m][k], acc[ai][bj][m][n], 0, 0, 0); __builtin_amdgcn_s_setprio(0); } while (0)
; #define PG8_WAIT_V(n) asm volatile("s_waitcnt vmcnt(" #n ")" ::: "memory")
; #define PG8_WAIT_L(n) asm volatile("s_waitcnt lgkmcnt(" #n ")" ::: "memory")
; #define PG8_BAR __builtin_amdgcn_s_barrier()
; #define PG8_SCHED __builtin_amdgcn_sched_barrier(0)
; template <class Epi, class Sched, bool ALIGN_EPI = false, bool SP2 = false>
; __device__ __forceinline__ void gemm_phase(PG8_LAS unsigned char* lds, const Gemm g, const Sched& S, const Epi& E) {
;     ...
;             PG8_LDA(At, 1, 1); PG8_STAGE(PG8_SB(1, 0), b3, voffB); PG8_STAGE(PG8_SB(1, 1), b3 + hstep, voffB); PG8_STAGE(PG8_SA(1, 0), a3, voffA);
;             PG8_WAIT_V(8); PG8_WAIT_L(0); PG8_BAR; PG8_MMA(1, 0, At, B0); PG8_MMA(1, 1, At, B1); PG8_BAR; PG8_SCHED;
;     ...
;         if constexpr (ALIGN_EPI) { if (wr == 0) PG8_BAR; }
	s_add_i32 s47, s47, s4
	v_lshl_add_u64 v[160:161], v[160:161], 0, s[68:69]
	s_mov_b32 m0, s47
	ds_read_b128 v[208:211], v163 offset:49152
	ds_read_b128 v[212:215], v163 offset:50176
	ds_read_b128 v[216:219], v163 offset:51200
	ds_read_b128 v[220:223], v163 offset:52224
	ds_read_b128 v[224:227], v163 offset:53248
	ds_read_b128 v[228:231], v163 offset:54272
	ds_read_b128 v[232:235], v163 offset:55296
	ds_read_b128 v[236:239], v163 offset:56320
	global_load_lds_dwordx4 v[160:161], off
	s_add_i32 m0, s47, 0x2000
	s_add_u32 s18, s18, 0x200080
	v_lshl_add_u64 v[160:161], v[240:241], 0, s[68:69]
	s_addc_u32 s19, s19, 0
	s_add_i32 s47, s76, s4
	global_load_lds_dwordx4 v[160:161], off
	v_lshl_add_u64 v[160:161], s[18:19], 0, v[148:149]
	s_mov_b32 m0, s47
	s_nop 0
	global_load_lds_dwordx4 v[160:161], off
	v_lshl_add_u64 v[160:161], s[18:19], 0, v[144:145]
	s_add_i32 m0, s47, 0x2000
	s_nop 0
	global_load_lds_dwordx4 v[160:161], off
	v_lshl_add_u64 v[160:161], v[242:243], 0, s[68:69]
	s_mov_b32 m0, s1
	s_nop 0
	global_load_lds_dwordx4 v[160:161], off
	v_lshl_add_u64 v[160:161], v[244:245], 0, s[68:69]
	s_mov_b32 m0, s60
	s_nop 0
	global_load_lds_dwordx4 v[160:161], off
	s_nop 0
	s_waitcnt vmcnt(8)
	s_waitcnt lgkmcnt(0)
	s_setprio 1
	s_barrier
	v_mfma_f32_16x16x32_bf16 v[62:65], v[156:159], v[208:211], v[62:65]
	v_mfma_f32_16x16x32_bf16 v[58:61], v[168:171], v[208:211], v[58:61]
	v_mfma_f32_16x16x32_bf16 v[46:49], v[156:159], v[216:219], v[46:49]
	v_mfma_f32_16x16x32_bf16 v[42:45], v[168:171], v[216:219], v[42:45]
	v_mfma_f32_16x16x32_bf16 v[30:33], v[156:159], v[224:227], v[30:33]
	v_mfma_f32_16x16x32_bf16 v[26:29], v[168:171], v[224:227], v[26:29]
	v_mfma_f32_16x16x32_bf16 v[14:17], v[156:159], v[232:235], v[14:17]
	v_mfma_f32_16x16x32_bf16 v[10:13], v[168:171], v[232:235], v[10:13]
	v_mfma_f32_16x16x32_bf16 v[62:65], v[164:167], v[212:215], v[62:65]
	v_mfma_f32_16x16x32_bf16 v[58:61], v[172:175], v[212:215], v[58:61]
	v_mfma_f32_16x16x32_bf16 v[46:49], v[164:167], v[220:223], v[46:49]
	v_mfma_f32_16x16x32_bf16 v[42:45], v[172:175], v[220:223], v[42:45]
	v_mfma_f32_16x16x32_bf16 v[30:33], v[164:167], v[228:231], v[30:33]
	v_mfma_f32_16x16x32_bf16 v[26:29], v[172:175], v[228:231], v[26:29]
	v_mfma_f32_16x16x32_bf16 v[14:17], v[164:167], v[236:239], v[14:17]
	v_mfma_f32_16x16x32_bf16 v[10:13], v[172:175], v[236:239], v[10:13]
	v_mfma_f32_16x16x32_bf16 v[54:57], v[176:179], v[208:211], v[54:57]
	v_mfma_f32_16x16x32_bf16 v[50:53], v[184:187], v[208:211], v[50:53]
	v_mfma_f32_16x16x32_bf16 v[38:41], v[176:179], v[216:219], v[38:41]
	v_mfma_f32_16x16x32_bf16 v[34:37], v[184:187], v[216:219], v[34:37]
	v_mfma_f32_16x16x32_bf16 v[22:25], v[176:179], v[224:227], v[22:25]
	v_mfma_f32_16x16x32_bf16 v[18:21], v[184:187], v[224:227], v[18:21]
	v_mfma_f32_16x16x32_bf16 v[6:9], v[176:179], v[232:235], v[6:9]
	v_mfma_f32_16x16x32_bf16 v[2:5], v[184:187], v[232:235], v[2:5]
	v_mfma_f32_16x16x32_bf16 v[54:57], v[180:183], v[212:215], v[54:57]
	v_mfma_f32_16x16x32_bf16 v[50:53], v[204:207], v[212:215], v[50:53]
	v_mfma_f32_16x16x32_bf16 v[38:41], v[180:183], v[220:223], v[38:41]
	v_mfma_f32_16x16x32_bf16 v[34:37], v[204:207], v[220:223], v[34:37]
	v_mfma_f32_16x16x32_bf16 v[22:25], v[180:183], v[228:231], v[22:25]
	v_mfma_f32_16x16x32_bf16 v[18:21], v[204:207], v[228:231], v[18:21]
	v_mfma_f32_16x16x32_bf16 v[6:9], v[180:183], v[236:239], v[6:9]
	v_mfma_f32_16x16x32_bf16 v[2:5], v[204:207], v[236:239], v[2:5]
	s_setprio 0
	s_barrier
	s_add_i32 s46, s46, 2
	s_add_u32 s58, s58, 0x100
	s_addc_u32 s59, s59, 0
	s_add_u32 s78, s78, 0x100
	s_addc_u32 s79, s79, 0
	s_cmpk_gt_u32 s46, 0x7d
	s_cbranch_scc0 .LBB0_36
	s_cmp_lg_u64 s[12:13], 0
	s_cselect_b32 s32, 3, 1
; __device__ __forceinline__ unsigned cvt_pk_bf16(float lo, float hi) { const f32x2c_t v = {lo, hi}; const bf16x2c_t b = __builtin_convertvector(v, bf16x2c_t); return __builtin_bit_cast(unsigned, b); }
; __device__ __forceinline__ float bf_lo(unsigned w) { return __uint_as_float(w << 16); }
; __device__ __forceinline__ float bf_hi(unsigned w) { return __uint_as_float(w & 0xffff0000u); }
;     __device__ __forceinline__ void operator()(const f32x4 (&acc)[2][2][4][2], const Unit& u, int wr, int wc, int fr, int fq) const {
;     ...
;             for (int m = 0; m < 4; ++m) { const size_t row = (size_t)(row0 + ai * HALF + m * 16); float ss = 0.f;
; #pragma unroll
;                 for (int bj = 0; bj < 2; ++bj) { const size_t off = row * DM + col0 + bj * HALF;
;                     const u32x4 pw = *(const u32x4*)(XN + off);
;                     f32x4 v0 = acc[ai][bj][m][0] + (f32x4){bf_lo(pw.x), bf_hi(pw.x), bf_lo(pw.y), bf_hi(pw.y)}, v1 = acc[ai][bj][m][1] + (f32x4){bf_lo(pw.z), bf_hi(pw.z), bf_lo(pw.w), bf_hi(pw.w)};
;                     u32x4 w; w.x = cvt_pk_bf16(v0[0], v0[1]); w.y = cvt_pk_bf16(v0[2], v0[3]); w.z = cvt_pk_bf16(v1[0], v1[1]); w.w = cvt_pk_bf16(v1[2], v1[3]);
;                     *(u32x4*)(X2 + off) = w;
;                     v0 = (f32x4){bf_lo(w.x), bf_hi(w.x), bf_lo(w.y), bf_hi(w.y)}; v1 = (f32x4){bf_lo(w.z), bf_hi(w.z), bf_lo(w.w), bf_hi(w.w)};
;                     ss += (v0[0] * v0[0] + v0[1] * v0[1]) + (v0[2] * v0[2] + v0[3] * v0[3]) + (v1[0] * v1[0] + v1[1] * v1[1]) + (v1[2] * v1[2] + v1[3] * v1[3]); }
;                 ss += __shfl_xor(ss, 16); ss += __shfl_xor(ss, 32);
;                 if (fq == 0) SS[row * 32 + u.pn * 4 + wc] = ss; }
.LBB0_39:
	v_xor_b32_e32 v159, 16, v192
	v_add_u32_e32 v160, 64, v193
	v_cmp_lt_i32_e32 vcc, v159, v160
	v_lshl_add_u32 v158, s54, 8, v1
	v_lshl_or_b32 v156, s28, 8, v162
	v_cndmask_b32_e32 v159, v192, v159, vcc
	v_lshlrev_b32_e32 v164, 2, v159
	v_xor_b32_e32 v159, 32, v192
	v_cmp_lt_i32_e32 vcc, v159, v160
	v_ashrrev_i32_e32 v157, 31, v156
	s_lshl_b32 s58, s28, 2
	v_cndmask_b32_e32 v159, v192, v159, vcc
	v_lshlrev_b32_e32 v165, 2, v159
	v_ashrrev_i32_e32 v159, 31, v158
	v_lshlrev_b64 v[160:161], 11, v[158:159]
	v_lshl_add_u64 v[160:161], v[160:161], 0, v[156:157]
	v_lshlrev_b64 v[160:161], 1, v[160:161]
	v_lshl_add_u64 v[166:167], s[70:71], 0, v[160:161]
	global_load_dwordx4 v[166:169], v[166:167], off
	s_ashr_i32 s59, s58, 31
	s_waitcnt vmcnt(0)
	v_lshlrev_b32_e32 v170, 16, v166
	v_and_b32_e32 v171, 0xffff0000, v166
	v_lshlrev_b32_e32 v166, 16, v167
	v_and_b32_e32 v167, 0xffff0000, v167
	v_pk_add_f32 v[128:129], v[128:129], v[166:167]
	v_lshlrev_b32_e32 v166, 16, v168
	v_and_b32_e32 v167, 0xffff0000, v168
	v_lshlrev_b32_e32 v168, 16, v169
	v_and_b32_e32 v169, 0xffff0000, v169
	v_pk_add_f32 v[126:127], v[126:127], v[170:171]
	v_pk_add_f32 v[168:169], v[124:125], v[168:169]
	v_pk_add_f32 v[124:125], v[122:123], v[166:167]
	v_cvt_pk_bf16_f32 v122, v126, v127
	v_cvt_pk_bf16_f32 v123, v128, v129
	v_cvt_pk_bf16_f32 v124, v124, v125
	v_cvt_pk_bf16_f32 v125, v168, v169
	v_lshl_add_u64 v[126:127], s[6:7], 0, v[160:161]
	global_store_dwordx4 v[126:127], v[122:125], off
	v_lshlrev_b32_e32 v126, 16, v122
	v_lshlrev_b32_e32 v127, 16, v123
	v_and_b32_e32 v122, 0xffff0000, v122
	v_and_b32_e32 v123, 0xffff0000, v123
	v_mul_f32_e32 v122, v122, v122
	v_mul_f32_e32 v123, v123, v123
	v_lshlrev_b32_e32 v128, 16, v124
	v_and_b32_e32 v124, 0xffff0000, v124
	v_fmac_f32_e32 v122, v126, v126
	v_fmac_f32_e32 v123, v127, v127
	v_add_f32_e32 v122, v122, v123
	v_mul_f32_e32 v123, v124, v124
	v_lshlrev_b32_e32 v129, 16, v125
	v_and_b32_e32 v125, 0xffff0000, v125
	v_fmac_f32_e32 v123, v128, v128
	v_add_f32_e32 v122, v123, v122
	v_mul_f32_e32 v123, v125, v125
	v_fmac_f32_e32 v123, v129, v129
	v_or_b32_e32 v160, 0x100, v160
	v_add_f32_e32 v128, v123, v122
	v_lshl_add_u64 v[122:123], s[70:71], 0, v[160:161]
	global_load_dwordx4 v[122:125], v[122:123], off
	s_waitcnt vmcnt(0)
	v_lshlrev_b32_e32 v126, 16, v122
	v_and_b32_e32 v127, 0xffff0000, v122
	v_lshlrev_b32_e32 v122, 16, v123
	v_and_b32_e32 v123, 0xffff0000, v123
	v_pk_add_f32 v[120:121], v[120:121], v[122:123]
	v_lshlrev_b32_e32 v122, 16, v124
	v_and_b32_e32 v123, 0xffff0000, v124
	v_lshlrev_b32_e32 v124, 16, v125
	v_and_b32_e32 v125, 0xffff0000, v125
	v_pk_add_f32 v[118:119], v[118:119], v[126:127]
	v_pk_add_f32 v[124:125], v[116:117], v[124:125]
	v_pk_add_f32 v[116:117], v[114:115], v[122:123]
	v_cvt_pk_bf16_f32 v114, v118, v119
	v_cvt_pk_bf16_f32 v115, v120, v121
	v_cvt_pk_bf16_f32 v116, v116, v117
	v_cvt_pk_bf16_f32 v117, v124, v125
	v_lshl_add_u64 v[118:119], s[6:7], 0, v[160:161]
	global_store_dwordx4 v[118:119], v[114:117], off
	s_bitcmp1_b32 s32, 1
	s_cbranch_scc0 .Lalign36
	s_barrier
.Lalign36:
	v_lshlrev_b32_e32 v118, 16, v114
	v_lshlrev_b32_e32 v119, 16, v115
	v_and_b32_e32 v114, 0xffff0000, v114
	v_and_b32_e32 v115, 0xffff0000, v115
	v_mul_f32_e32 v114, v114, v114
	v_mul_f32_e32 v115, v115, v115
	v_lshlrev_b32_e32 v120, 16, v116
	v_and_b32_e32 v116, 0xffff0000, v116
	v_fmac_f32_e32 v114, v118, v118
	v_fmac_f32_e32 v115, v119, v119
	v_add_f32_e32 v114, v114, v115
	v_mul_f32_e32 v115, v116, v116
	v_lshlrev_b32_e32 v121, 16, v117
	v_and_b32_e32 v117, 0xffff0000, v117
	v_fmac_f32_e32 v115, v120, v120
	v_add_f32_e32 v114, v115, v114
	v_mul_f32_e32 v115, v117, v117
	v_fmac_f32_e32 v115, v121, v121
	v_add_f32_e32 v114, v115, v114
	v_add_f32_e32 v114, v128, v114
	ds_bpermute_b32 v115, v164, v114
	s_waitcnt lgkmcnt(0)
	v_add_f32_e32 v114, v114, v115
	ds_bpermute_b32 v115, v165, v114
	s_and_saveexec_b64 s[18:19], s[40:41]
	s_cbranch_execz .LBB0_41
	v_lshlrev_b64 v[116:117], 7, v[158:159]
	v_lshl_add_u64 v[116:117], s[10:11], 0, v[116:117]
	v_lshl_add_u64 v[116:117], s[58:59], 2, v[116:117]
	s_lshl_b32 s54, s0, 2
	v_lshl_add_u64 v[116:117], v[116:117], 0, s[54:55]
	s_waitcnt lgkmcnt(0)
	v_add_f32_e32 v114, v114, v115
	global_store_dword v[116:117], v114, off

; #define PG8_STAGE(bufoff, gbase, voff) do { _Pragma("unroll") for (int _i = 0; _i < 2; ++_i) \
;         __builtin_amdgcn_global_load_lds((const unsigned*)((const char*)(gbase) + (voff)[_i]), (PG8_LAS unsigned*)(lds + (bufoff) + ldsw + _i * 8192), 16, 0, 0); } while (0)
; #define PG8_LDA(dst, b, h) do { _Pragma("unroll") for (int m = 0; m < 4; ++m) _Pragma("unroll") for (int k = 0; k < 2; ++k) dst[m][k] = *(const PG8_LAS bf16x8*)(lds + PG8_SA(b, h) + aoff + m * 2048 + k * 1024); } while (0)
; #define PG8_LDB(dst, b, h) do { _Pragma("unroll") for (int n = 0; n < 2; ++n) _Pragma("unroll") for (int k = 0; k < 2; ++k) dst[n][k] = *(const PG8_LAS bf16x8*)(lds + PG8_SB(b, h) + boff + n * 2048 + k * 1024); } while (0)
; #define PG8_MMA(ai, bj, At, Bt) do { __builtin_amdgcn_s_setprio(1); _Pragma("unroll") for (int m = 0; m < 4; ++m) _Pragma("unroll") for (int n = 0; n < 2; ++n) _Pragma("unroll") for (int k = 0; k < 2; ++k) \
;         acc[ai][bj][m][n] = __builtin_amdgcn_mfma_f32_16x16x32_bf16(Bt[n][k], At[m][k], acc[ai][bj][m][n], 0, 0, 0); __builtin_amdgcn_s_setprio(0); } while (0)
; #define PG8_WAIT_V(n) asm volatile("s_waitcnt vmcnt(" #n ")" ::: "memory")
; #define PG8_WAIT_L(n) asm volatile("s_waitcnt lgkmcnt(" #n ")" ::: "memory")
; #define PG8_BAR __builtin_amdgcn_s_barrier()
; #define PG8_SCHED __builtin_amdgcn_sched_barrier(0)
; template <class Epi, class Sched, bool ALIGN_EPI = false, bool SP2 = false>
; __device__ __forceinline__ void gemm_phase(PG8_LAS unsigned char* lds, const Gemm g, const Sched& S, const Epi& E) {
;     ...
;             PG8_LDB(B0, 0, 0); PG8_LDB(B1, 0, 1); PG8_SCHED; PG8_LDA(At, 0, 0); PG8_STAGE(PG8_SA(1, 1), a1 + hstep, voffA);
;             PG8_WAIT_V(8); PG8_WAIT_L(0); PG8_BAR; PG8_MMA(0, 0, At, B0); PG8_MMA(0, 1, At, B1); PG8_BAR; PG8_SCHED;
;             PG8_LDA(At, 0, 1); PG8_STAGE(PG8_SB(0, 0), b2, voffB); PG8_STAGE(PG8_SB(0, 1), b2 + hstep, voffB); PG8_STAGE(PG8_SA(0, 0), a2, voffA);
;             PG8_WAIT_V(8); PG8_WAIT_L(0); PG8_BAR; PG8_MMA(1, 0, At, B0); PG8_MMA(1, 1, At, B1); PG8_BAR; PG8_SCHED;
.Lpw3_j:
	s_nop 0
	s_nop 0
	s_nop 0
	s_waitcnt lgkmcnt(0)
	s_setprio 1
	s_barrier
	v_mfma_f32_16x16x32_bf16 v[126:129], v[162:165], v[212:215], 0
	v_mfma_f32_16x16x32_bf16 v[122:125], v[170:173], v[212:215], 0
	v_mfma_f32_16x16x32_bf16 v[110:113], v[162:165], v[220:223], 0
	v_mfma_f32_16x16x32_bf16 v[106:109], v[170:173], v[220:223], 0
	v_mfma_f32_16x16x32_bf16 v[94:97], v[162:165], v[228:231], 0
	v_mfma_f32_16x16x32_bf16 v[90:93], v[170:173], v[228:231], 0
	v_mfma_f32_16x16x32_bf16 v[78:81], v[162:165], v[236:239], 0
	v_mfma_f32_16x16x32_bf16 v[74:77], v[170:173], v[236:239], 0
	s_setprio 0
	s_setprio 1
	v_mfma_f32_16x16x32_bf16 v[126:129], v[166:169], v[216:219], v[126:129]
	v_mfma_f32_16x16x32_bf16 v[122:125], v[174:177], v[216:219], v[122:125]
	v_mfma_f32_16x16x32_bf16 v[110:113], v[166:169], v[224:227], v[110:113]
	v_mfma_f32_16x16x32_bf16 v[106:109], v[174:177], v[224:227], v[106:109]
	v_mfma_f32_16x16x32_bf16 v[94:97], v[166:169], v[232:235], v[94:97]
	v_mfma_f32_16x16x32_bf16 v[90:93], v[174:177], v[232:235], v[90:93]
	v_mfma_f32_16x16x32_bf16 v[78:81], v[166:169], v[240:243], v[78:81]
	v_mfma_f32_16x16x32_bf16 v[74:77], v[174:177], v[240:243], v[74:77]
	s_setprio 0
	s_setprio 1
	v_mfma_f32_16x16x32_bf16 v[118:121], v[178:181], v[212:215], 0
	v_mfma_f32_16x16x32_bf16 v[114:117], v[204:207], v[212:215], 0
	v_mfma_f32_16x16x32_bf16 v[102:105], v[178:181], v[220:223], 0
	v_mfma_f32_16x16x32_bf16 v[98:101], v[204:207], v[220:223], 0
	v_mfma_f32_16x16x32_bf16 v[86:89], v[178:181], v[228:231], 0
	v_mfma_f32_16x16x32_bf16 v[82:85], v[204:207], v[228:231], 0
	v_mfma_f32_16x16x32_bf16 v[70:73], v[178:181], v[236:239], 0
	v_mfma_f32_16x16x32_bf16 v[66:69], v[204:207], v[236:239], 0
	s_setprio 0
	s_setprio 1
	v_mfma_f32_16x16x32_bf16 v[118:121], v[182:185], v[216:219], v[118:121]
	v_mfma_f32_16x16x32_bf16 v[114:117], v[208:211], v[216:219], v[114:117]
	v_mfma_f32_16x16x32_bf16 v[102:105], v[182:185], v[224:227], v[102:105]
	v_mfma_f32_16x16x32_bf16 v[98:101], v[208:211], v[224:227], v[98:101]
	v_mfma_f32_16x16x32_bf16 v[86:89], v[182:185], v[232:235], v[86:89]
	v_mfma_f32_16x16x32_bf16 v[82:85], v[208:211], v[232:235], v[82:85]
	v_mfma_f32_16x16x32_bf16 v[70:73], v[182:185], v[240:243], v[70:73]
	v_mfma_f32_16x16x32_bf16 v[66:69], v[208:211], v[240:243], v[66:69]
	s_setprio 0
	s_barrier
	s_add_i32 s47, s47, s54
	v_lshl_add_u64 v[158:159], s[18:19], 0, v[148:149]
	s_mov_b32 m0, s47
	ds_read_b128 v[212:215], v161 offset:16384
	ds_read_b128 v[216:219], v161 offset:17408
	ds_read_b128 v[220:223], v161 offset:18432
	ds_read_b128 v[224:227], v161 offset:19456
	ds_read_b128 v[228:231], v161 offset:20480
	ds_read_b128 v[232:235], v161 offset:21504
	ds_read_b128 v[236:239], v161 offset:22528
	ds_read_b128 v[240:243], v161 offset:23552
	global_load_lds_dwordx4 v[158:159], off
	s_add_i32 m0, s47, 0x2000
	s_add_u32 s76, s18, 0x80000
	v_lshl_add_u64 v[186:187], s[18:19], 0, v[144:145]
	s_addc_u32 s77, s19, 0
	s_add_i32 s47, s80, s54
	global_load_lds_dwordx4 v[186:187], off
	v_lshl_add_u64 v[244:245], s[76:77], 0, v[148:149]
	s_mov_b32 m0, s47
	v_lshl_add_u64 v[246:247], s[58:59], 0, v[146:147]
	global_load_lds_dwordx4 v[244:245], off
	v_lshl_add_u64 v[244:245], s[76:77], 0, v[144:145]
	s_add_i32 m0, s47, 0x2000
	s_nop 0
	global_load_lds_dwordx4 v[244:245], off
	v_lshl_add_u64 v[244:245], s[58:59], 0, v[150:151]
	s_mov_b32 m0, s62
	s_nop 0
	global_load_lds_dwordx4 v[244:245], off
	s_mov_b32 m0, s63
	s_nop 0
	global_load_lds_dwordx4 v[246:247], off
	s_cmp_eq_u32 s32, 0
	s_cbranch_scc1 .Lpw4_f
	s_waitcnt vmcnt(24)
	s_branch .Lpw4_j

; #define PG8_STAGE(bufoff, gbase, voff) do { _Pragma("unroll") for (int _i = 0; _i < 2; ++_i) \
;         __builtin_amdgcn_global_load_lds((const unsigned*)((const char*)(gbase) + (voff)[_i]), (PG8_LAS unsigned*)(lds + (bufoff) + ldsw + _i * 8192), 16, 0, 0); } while (0)
; #define PG8_LDA(dst, b, h) do { _Pragma("unroll") for (int m = 0; m < 4; ++m) _Pragma("unroll") for (int k = 0; k < 2; ++k) dst[m][k] = *(const PG8_LAS bf16x8*)(lds + PG8_SA(b, h) + aoff + m * 2048 + k * 1024); } while (0)
; #define PG8_LDB(dst, b, h) do { _Pragma("unroll") for (int n = 0; n < 2; ++n) _Pragma("unroll") for (int k = 0; k < 2; ++k) dst[n][k] = *(const PG8_LAS bf16x8*)(lds + PG8_SB(b, h) + boff + n * 2048 + k * 1024); } while (0)
; #define PG8_MMA(ai, bj, At, Bt) do { __builtin_amdgcn_s_setprio(1); _Pragma("unroll") for (int m = 0; m < 4; ++m) _Pragma("unroll") for (int n = 0; n < 2; ++n) _Pragma("unroll") for (int k = 0; k < 2; ++k) \
;         acc[ai][bj][m][n] = __builtin_amdgcn_mfma_f32_16x16x32_bf16(Bt[n][k], At[m][k], acc[ai][bj][m][n], 0, 0, 0); __builtin_amdgcn_s_setprio(0); } while (0)
; #define PG8_WAIT_V(n) asm volatile("s_waitcnt vmcnt(" #n ")" ::: "memory")
; template <class Epi, class Sched, bool ALIGN_EPI = false, bool SP2 = false>
; __device__ __forceinline__ void gemm_phase(PG8_LAS unsigned char* lds, const Gemm g, const Sched& S, const Epi& E) {
;     ...
;             PG8_LDB(B0, 0, 0); PG8_LDB(B1, 0, 1); PG8_SCHED; PG8_LDA(At, 0, 0); PG8_STAGE(PG8_SA(1, 1), a1 + hstep, voffA);
;             PG8_WAIT_V(8); PG8_WAIT_L(0); PG8_BAR; PG8_MMA(0, 0, At, B0); PG8_MMA(0, 1, At, B1); PG8_BAR; PG8_SCHED;
;             PG8_LDA(At, 0, 1); PG8_STAGE(PG8_SB(0, 0), b2, voffB); PG8_STAGE(PG8_SB(0, 1), b2 + hstep, voffB); PG8_STAGE(PG8_SA(0, 0), a2, voffA);
;             PG8_WAIT_V(8); PG8_WAIT_L(0); PG8_BAR; PG8_MMA(1, 0, At, B0); PG8_MMA(1, 1, At, B1); PG8_BAR; PG8_SCHED;
;             PG8_LDB(B0, 1, 0); PG8_LDB(B1, 1, 1); PG8_SCHED; PG8_LDA(At, 1, 0); PG8_STAGE(PG8_SA(0, 1), a2 + hstep, voffA);
;             PG8_WAIT_V(8); PG8_WAIT_L(0); PG8_BAR; PG8_MMA(0, 0, At, B0); PG8_MMA(0, 1, At, B1); PG8_BAR; PG8_SCHED;
;             PG8_LDA(At, 1, 1); PG8_STAGE(PG8_SB(1, 0), b3, voffB); PG8_STAGE(PG8_SB(1, 1), b3 + hstep, voffB); PG8_STAGE(PG8_SA(1, 0), a3, voffA);
;             PG8_WAIT_V(8); PG8_WAIT_L(0); PG8_BAR; PG8_MMA(1, 0, At, B0); PG8_MMA(1, 1, At, B1); PG8_BAR; PG8_SCHED;
.LBB0_76:
	s_add_u32 s18, s0, 0xfff80080
	s_addc_u32 s19, s1, -1
	s_add_i32 s47, 0, 0x10000
	s_cmp_eq_u32 s46, 28
	s_cselect_b32 s59, s60, s19
	s_cselect_b32 s58, s73, s18
	v_add_u32_e32 v158, s47, v143
	s_cselect_b32 s19, s45, s79
	s_cselect_b32 s18, s84, s78
	s_add_i32 s80, 0, 0x14000
	ds_read_b128 v[162:165], v158
	ds_read_b128 v[166:169], v158 offset:1024
	ds_read_b128 v[170:173], v158 offset:2048
	ds_read_b128 v[174:177], v158 offset:3072
	v_add_u32_e32 v158, s80, v143
	ds_read_b128 v[178:181], v158
	ds_read_b128 v[182:185], v158 offset:1024
	ds_read_b128 v[204:207], v158 offset:2048
	ds_read_b128 v[208:211], v158 offset:3072
	v_lshl_add_u64 v[158:159], s[0:1], 0, v[154:155]
	s_add_i32 m0, s62, 0xc000
	ds_read_b128 v[212:215], v161
	ds_read_b128 v[216:219], v161 offset:1024
	ds_read_b128 v[220:223], v161 offset:2048
	ds_read_b128 v[224:227], v161 offset:3072
	ds_read_b128 v[228:231], v161 offset:4096
	ds_read_b128 v[232:235], v161 offset:5120
	ds_read_b128 v[236:239], v161 offset:6144
	ds_read_b128 v[240:243], v161 offset:7168
	global_load_lds_dwordx4 v[158:159], off
	v_lshl_add_u64 v[158:159], s[0:1], 0, v[156:157]
	s_add_i32 m0, s62, 0xe000
	s_nop 0
	global_load_lds_dwordx4 v[158:159], off
	s_nop 0
	s_waitcnt vmcnt(8)
	s_waitcnt lgkmcnt(0)
	s_setprio 1
	s_barrier
	v_mfma_f32_16x16x32_bf16 v[126:129], v[162:165], v[212:215], v[126:129]
	v_mfma_f32_16x16x32_bf16 v[122:125], v[170:173], v[212:215], v[122:125]
	v_mfma_f32_16x16x32_bf16 v[110:113], v[162:165], v[220:223], v[110:113]
	v_mfma_f32_16x16x32_bf16 v[106:109], v[170:173], v[220:223], v[106:109]
	v_mfma_f32_16x16x32_bf16 v[94:97], v[162:165], v[228:231], v[94:97]
	v_mfma_f32_16x16x32_bf16 v[90:93], v[170:173], v[228:231], v[90:93]
	v_mfma_f32_16x16x32_bf16 v[78:81], v[162:165], v[236:239], v[78:81]
	v_mfma_f32_16x16x32_bf16 v[74:77], v[170:173], v[236:239], v[74:77]
	s_setprio 0
	s_setprio 1
	v_mfma_f32_16x16x32_bf16 v[126:129], v[166:169], v[216:219], v[126:129]
	v_mfma_f32_16x16x32_bf16 v[122:125], v[174:177], v[216:219], v[122:125]
	v_mfma_f32_16x16x32_bf16 v[110:113], v[166:169], v[224:227], v[110:113]
	v_mfma_f32_16x16x32_bf16 v[106:109], v[174:177], v[224:227], v[106:109]
	v_mfma_f32_16x16x32_bf16 v[94:97], v[166:169], v[232:235], v[94:97]
	v_mfma_f32_16x16x32_bf16 v[90:93], v[174:177], v[232:235], v[90:93]
	v_mfma_f32_16x16x32_bf16 v[78:81], v[166:169], v[240:243], v[78:81]
	v_mfma_f32_16x16x32_bf16 v[74:77], v[174:177], v[240:243], v[74:77]
	s_setprio 0
	s_setprio 1
	v_mfma_f32_16x16x32_bf16 v[118:121], v[178:181], v[212:215], v[118:121]
	v_mfma_f32_16x16x32_bf16 v[114:117], v[204:207], v[212:215], v[114:117]
	v_mfma_f32_16x16x32_bf16 v[102:105], v[178:181], v[220:223], v[102:105]
	v_mfma_f32_16x16x32_bf16 v[98:101], v[204:207], v[220:223], v[98:101]
	v_mfma_f32_16x16x32_bf16 v[86:89], v[178:181], v[228:231], v[86:89]
	v_mfma_f32_16x16x32_bf16 v[82:85], v[204:207], v[228:231], v[82:85]
	v_mfma_f32_16x16x32_bf16 v[70:73], v[178:181], v[236:239], v[70:73]
	v_mfma_f32_16x16x32_bf16 v[66:69], v[204:207], v[236:239], v[66:69]
	s_setprio 0
	s_setprio 1
	v_mfma_f32_16x16x32_bf16 v[118:121], v[182:185], v[216:219], v[118:121]
	v_mfma_f32_16x16x32_bf16 v[114:117], v[208:211], v[216:219], v[114:117]
	v_mfma_f32_16x16x32_bf16 v[102:105], v[182:185], v[224:227], v[102:105]
	v_mfma_f32_16x16x32_bf16 v[98:101], v[208:211], v[224:227], v[98:101]
	v_mfma_f32_16x16x32_bf16 v[86:89], v[182:185], v[232:235], v[86:89]
	v_mfma_f32_16x16x32_bf16 v[82:85], v[208:211], v[232:235], v[82:85]
	v_mfma_f32_16x16x32_bf16 v[70:73], v[182:185], v[240:243], v[70:73]
	v_mfma_f32_16x16x32_bf16 v[66:69], v[208:211], v[240:243], v[66:69]
	s_setprio 0
	s_barrier
	s_add_i32 s47, s47, s54
	v_lshl_add_u64 v[158:159], s[18:19], 0, v[148:149]
	s_mov_b32 m0, s47
	ds_read_b128 v[212:215], v161 offset:16384
	ds_read_b128 v[216:219], v161 offset:17408
	ds_read_b128 v[220:223], v161 offset:18432
	ds_read_b128 v[224:227], v161 offset:19456
	ds_read_b128 v[228:231], v161 offset:20480
	ds_read_b128 v[232:235], v161 offset:21504
	ds_read_b128 v[236:239], v161 offset:22528
	ds_read_b128 v[240:243], v161 offset:23552
	global_load_lds_dwordx4 v[158:159], off
	s_add_i32 m0, s47, 0x2000
	s_add_u32 s76, s18, 0x80000
	v_lshl_add_u64 v[186:187], s[18:19], 0, v[144:145]
	s_addc_u32 s77, s19, 0
	s_add_i32 s47, s80, s54
	global_load_lds_dwordx4 v[186:187], off
	v_lshl_add_u64 v[244:245], s[76:77], 0, v[148:149]
	s_mov_b32 m0, s47
	v_lshl_add_u64 v[246:247], s[58:59], 0, v[146:147]
	global_load_lds_dwordx4 v[244:245], off
	v_lshl_add_u64 v[244:245], s[76:77], 0, v[144:145]
	s_add_i32 m0, s47, 0x2000
	s_nop 0
	global_load_lds_dwordx4 v[244:245], off
	v_lshl_add_u64 v[244:245], s[58:59], 0, v[150:151]
	s_mov_b32 m0, s62
	s_nop 0
	global_load_lds_dwordx4 v[244:245], off
	s_mov_b32 m0, s63
	s_nop 0
	global_load_lds_dwordx4 v[246:247], off
	s_waitcnt vmcnt(8)
	s_waitcnt lgkmcnt(0)
	s_setprio 1
	s_barrier
; #define PG8_STAGE(bufoff, gbase, voff) do { _Pragma("unroll") for (int _i = 0; _i < 2; ++_i) \
;         __builtin_amdgcn_global_load_lds((const unsigned*)((const char*)(gbase) + (voff)[_i]), (PG8_LAS unsigned*)(lds + (bufoff) + ldsw + _i * 8192), 16, 0, 0); } while (0)
; #define PG8_LDA(dst, b, h) do { _Pragma("unroll") for (int m = 0; m < 4; ++m) _Pragma("unroll") for (int k = 0; k < 2; ++k) dst[m][k] = *(const PG8_LAS bf16x8*)(lds + PG8_SA(b, h) + aoff + m * 2048 + k * 1024); } while (0)
; #define PG8_LDB(dst, b, h) do { _Pragma("unroll") for (int n = 0; n < 2; ++n) _Pragma("unroll") for (int k = 0; k < 2; ++k) dst[n][k] = *(const PG8_LAS bf16x8*)(lds + PG8_SB(b, h) + boff + n * 2048 + k * 1024); } while (0)
; #define PG8_MMA(ai, bj, At, Bt) do { __builtin_amdgcn_s_setprio(1); _Pragma("unroll") for (int m = 0; m < 4; ++m) _Pragma("unroll") for (int n = 0; n < 2; ++n) _Pragma("unroll") for (int k = 0; k < 2; ++k) \
;         acc[ai][bj][m][n] = __builtin_amdgcn_mfma_f32_16x16x32_bf16(Bt[n][k], At[m][k], acc[ai][bj][m][n], 0, 0, 0); __builtin_amdgcn_s_setprio(0); } while (0)
; #define PG8_WAIT_V(n) asm volatile("s_waitcnt vmcnt(" #n ")" ::: "memory")
; template <class Epi, class Sched, bool ALIGN_EPI = false, bool SP2 = false>
; __device__ __forceinline__ void gemm_phase(PG8_LAS unsigned char* lds, const Gemm g, const Sched& S, const Epi& E) {
;     ...
;             PG8_LDB(B0, 0, 0); PG8_LDB(B1, 0, 1); PG8_SCHED; PG8_LDA(At, 0, 0); PG8_STAGE(PG8_SA(1, 1), a1 + hstep, voffA);
;             PG8_WAIT_V(8); PG8_WAIT_L(0); PG8_BAR; PG8_MMA(0, 0, At, B0); PG8_MMA(0, 1, At, B1); PG8_BAR; PG8_SCHED;
;             PG8_LDA(At, 0, 1); PG8_STAGE(PG8_SB(0, 0), b2, voffB); PG8_STAGE(PG8_SB(0, 1), b2 + hstep, voffB); PG8_STAGE(PG8_SA(0, 0), a2, voffA);
;             PG8_WAIT_V(8); PG8_WAIT_L(0); PG8_BAR; PG8_MMA(1, 0, At, B0); PG8_MMA(1, 1, At, B1); PG8_BAR; PG8_SCHED;
;             PG8_LDB(B0, 1, 0); PG8_LDB(B1, 1, 1); PG8_SCHED; PG8_LDA(At, 1, 0); PG8_STAGE(PG8_SA(0, 1), a2 + hstep, voffA);
;             PG8_WAIT_V(8); PG8_WAIT_L(0); PG8_BAR; PG8_MMA(0, 0, At, B0); PG8_MMA(0, 1, At, B1); PG8_BAR; PG8_SCHED;
;             PG8_LDA(At, 1, 1); PG8_STAGE(PG8_SB(1, 0), b3, voffB); PG8_STAGE(PG8_SB(1, 1), b3 + hstep, voffB); PG8_STAGE(PG8_SA(1, 0), a3, voffA);
;             PG8_WAIT_V(8); PG8_WAIT_L(0); PG8_BAR; PG8_MMA(1, 0, At, B0); PG8_MMA(1, 1, At, B1); PG8_BAR; PG8_SCHED;
	v_mfma_f32_16x16x32_bf16 v[62:65], v[162:165], v[212:215], v[62:65]
	v_mfma_f32_16x16x32_bf16 v[58:61], v[170:173], v[212:215], v[58:61]
	v_mfma_f32_16x16x32_bf16 v[46:49], v[162:165], v[220:223], v[46:49]
	v_mfma_f32_16x16x32_bf16 v[42:45], v[170:173], v[220:223], v[42:45]
	v_mfma_f32_16x16x32_bf16 v[30:33], v[162:165], v[228:231], v[30:33]
	v_mfma_f32_16x16x32_bf16 v[26:29], v[170:173], v[228:231], v[26:29]
	v_mfma_f32_16x16x32_bf16 v[14:17], v[162:165], v[236:239], v[14:17]
	v_mfma_f32_16x16x32_bf16 v[10:13], v[170:173], v[236:239], v[10:13]
	v_mfma_f32_16x16x32_bf16 v[62:65], v[166:169], v[216:219], v[62:65]
	v_mfma_f32_16x16x32_bf16 v[58:61], v[174:177], v[216:219], v[58:61]
	v_mfma_f32_16x16x32_bf16 v[46:49], v[166:169], v[224:227], v[46:49]
	v_mfma_f32_16x16x32_bf16 v[42:45], v[174:177], v[224:227], v[42:45]
	v_mfma_f32_16x16x32_bf16 v[30:33], v[166:169], v[232:235], v[30:33]
	v_mfma_f32_16x16x32_bf16 v[26:29], v[174:177], v[232:235], v[26:29]
	v_mfma_f32_16x16x32_bf16 v[14:17], v[166:169], v[240:243], v[14:17]
	v_mfma_f32_16x16x32_bf16 v[10:13], v[174:177], v[240:243], v[10:13]
	v_mfma_f32_16x16x32_bf16 v[54:57], v[178:181], v[212:215], v[54:57]
	v_mfma_f32_16x16x32_bf16 v[50:53], v[204:207], v[212:215], v[50:53]
	v_mfma_f32_16x16x32_bf16 v[38:41], v[178:181], v[220:223], v[38:41]
	v_mfma_f32_16x16x32_bf16 v[34:37], v[204:207], v[220:223], v[34:37]
	v_mfma_f32_16x16x32_bf16 v[22:25], v[178:181], v[228:231], v[22:25]
	v_mfma_f32_16x16x32_bf16 v[18:21], v[204:207], v[228:231], v[18:21]
	v_mfma_f32_16x16x32_bf16 v[6:9], v[178:181], v[236:239], v[6:9]
	v_mfma_f32_16x16x32_bf16 v[2:5], v[204:207], v[236:239], v[2:5]
	v_mfma_f32_16x16x32_bf16 v[54:57], v[182:185], v[216:219], v[54:57]
	v_mfma_f32_16x16x32_bf16 v[50:53], v[208:211], v[216:219], v[50:53]
	v_mfma_f32_16x16x32_bf16 v[38:41], v[182:185], v[224:227], v[38:41]
	v_mfma_f32_16x16x32_bf16 v[34:37], v[208:211], v[224:227], v[34:37]
	v_mfma_f32_16x16x32_bf16 v[22:25], v[182:185], v[232:235], v[22:25]
	v_mfma_f32_16x16x32_bf16 v[18:21], v[208:211], v[232:235], v[18:21]
	v_mfma_f32_16x16x32_bf16 v[6:9], v[182:185], v[240:243], v[6:9]
	v_mfma_f32_16x16x32_bf16 v[2:5], v[208:211], v[240:243], v[2:5]
	s_setprio 0
	s_barrier
	s_add_i32 s47, 0, 0x18000
	s_add_i32 s76, 0, 0x1c000
	v_add_u32_e32 v174, s47, v143
	v_add_u32_e32 v203, s76, v143
	ds_read_b128 v[162:165], v174
	ds_read_b128 v[166:169], v174 offset:1024
	ds_read_b128 v[170:173], v174 offset:2048
	ds_read_b128 v[174:177], v174 offset:3072
	ds_read_b128 v[178:181], v203
	ds_read_b128 v[182:185], v203 offset:1024
	ds_read_b128 v[204:207], v203 offset:2048
	ds_read_b128 v[208:211], v203 offset:3072
	s_add_u32 s58, s58, 0x80000
	s_addc_u32 s59, s59, 0
	s_mov_b32 m0, s67
	v_lshl_add_u64 v[248:249], s[58:59], 0, v[150:151]
	ds_read_b128 v[212:215], v161 offset:32768
	ds_read_b128 v[216:219], v161 offset:33792
	ds_read_b128 v[220:223], v161 offset:34816
	ds_read_b128 v[224:227], v161 offset:35840
	ds_read_b128 v[228:231], v161 offset:36864
	ds_read_b128 v[232:235], v161 offset:37888
	ds_read_b128 v[236:239], v161 offset:38912
	ds_read_b128 v[240:243], v161 offset:39936
	global_load_lds_dwordx4 v[248:249], off
	v_lshl_add_u64 v[248:249], s[58:59], 0, v[146:147]
	s_mov_b32 m0, s4
	s_nop 0
	global_load_lds_dwordx4 v[248:249], off
	s_waitcnt vmcnt(8)
	s_waitcnt lgkmcnt(0)
	s_setprio 1
	s_barrier
	v_mfma_f32_16x16x32_bf16 v[126:129], v[162:165], v[212:215], v[126:129]
	v_mfma_f32_16x16x32_bf16 v[122:125], v[170:173], v[212:215], v[122:125]
	v_mfma_f32_16x16x32_bf16 v[110:113], v[162:165], v[220:223], v[110:113]
	v_mfma_f32_16x16x32_bf16 v[106:109], v[170:173], v[220:223], v[106:109]
	v_mfma_f32_16x16x32_bf16 v[94:97], v[162:165], v[228:231], v[94:97]
	v_mfma_f32_16x16x32_bf16 v[90:93], v[170:173], v[228:231], v[90:93]
	v_mfma_f32_16x16x32_bf16 v[78:81], v[162:165], v[236:239], v[78:81]
	v_mfma_f32_16x16x32_bf16 v[74:77], v[170:173], v[236:239], v[74:77]
	s_setprio 0
	s_setprio 1
	v_mfma_f32_16x16x32_bf16 v[126:129], v[166:169], v[216:219], v[126:129]
	v_mfma_f32_16x16x32_bf16 v[122:125], v[174:177], v[216:219], v[122:125]
	v_mfma_f32_16x16x32_bf16 v[110:113], v[166:169], v[224:227], v[110:113]
	v_mfma_f32_16x16x32_bf16 v[106:109], v[174:177], v[224:227], v[106:109]
	v_mfma_f32_16x16x32_bf16 v[94:97], v[166:169], v[232:235], v[94:97]
	v_mfma_f32_16x16x32_bf16 v[90:93], v[174:177], v[232:235], v[90:93]
	v_mfma_f32_16x16x32_bf16 v[78:81], v[166:169], v[240:243], v[78:81]
	v_mfma_f32_16x16x32_bf16 v[74:77], v[174:177], v[240:243], v[74:77]
	s_setprio 0
	s_setprio 1
	v_mfma_f32_16x16x32_bf16 v[118:121], v[178:181], v[212:215], v[118:121]
	v_mfma_f32_16x16x32_bf16 v[114:117], v[204:207], v[212:215], v[114:117]
	v_mfma_f32_16x16x32_bf16 v[102:105], v[178:181], v[220:223], v[102:105]
	v_mfma_f32_16x16x32_bf16 v[98:101], v[204:207], v[220:223], v[98:101]
	v_mfma_f32_16x16x32_bf16 v[86:89], v[178:181], v[228:231], v[86:89]
	v_mfma_f32_16x16x32_bf16 v[82:85], v[204:207], v[228:231], v[82:85]
	v_mfma_f32_16x16x32_bf16 v[70:73], v[178:181], v[236:239], v[70:73]
	v_mfma_f32_16x16x32_bf16 v[66:69], v[204:207], v[236:239], v[66:69]
	s_setprio 0
	s_setprio 1
	v_mfma_f32_16x16x32_bf16 v[118:121], v[182:185], v[216:219], v[118:121]
	v_mfma_f32_16x16x32_bf16 v[114:117], v[208:211], v[216:219], v[114:117]
	v_mfma_f32_16x16x32_bf16 v[102:105], v[182:185], v[224:227], v[102:105]
	v_mfma_f32_16x16x32_bf16 v[98:101], v[208:211], v[224:227], v[98:101]
	v_mfma_f32_16x16x32_bf16 v[86:89], v[182:185], v[232:235], v[86:89]
	v_mfma_f32_16x16x32_bf16 v[82:85], v[208:211], v[232:235], v[82:85]
	v_mfma_f32_16x16x32_bf16 v[70:73], v[182:185], v[240:243], v[70:73]
	v_mfma_f32_16x16x32_bf16 v[66:69], v[208:211], v[240:243], v[66:69]
	s_setprio 0
	s_barrier
; #define PG8_STAGE(bufoff, gbase, voff) do { _Pragma("unroll") for (int _i = 0; _i < 2; ++_i) \
;         __builtin_amdgcn_global_load_lds((const unsigned*)((const char*)(gbase) + (voff)[_i]), (PG8_LAS unsigned*)(lds + (bufoff) + ldsw + _i * 8192), 16, 0, 0); } while (0)
; #define PG8_LDA(dst, b, h) do { _Pragma("unroll") for (int m = 0; m < 4; ++m) _Pragma("unroll") for (int k = 0; k < 2; ++k) dst[m][k] = *(const PG8_LAS bf16x8*)(lds + PG8_SA(b, h) + aoff + m * 2048 + k * 1024); } while (0)
; #define PG8_MMA(ai, bj, At, Bt) do { __builtin_amdgcn_s_setprio(1); _Pragma("unroll") for (int m = 0; m < 4; ++m) _Pragma("unroll") for (int n = 0; n < 2; ++n) _Pragma("unroll") for (int k = 0; k < 2; ++k) \
;         acc[ai][bj][m][n] = __builtin_amdgcn_mfma_f32_16x16x32_bf16(Bt[n][k], At[m][k], acc[ai][bj][m][n], 0, 0, 0); __builtin_amdgcn_s_setprio(0); } while (0)
;     __device__ __forceinline__ void operator()(const f32x4 (&acc)[2][2][4][2], const Unit& u, int wr, int wc, int fr, int fq) const {
;         const int row0 = u.pm * BM + wr * 64 + fr, col0 = u.pn * BM + wc * 32 + 8 * fq;
; #pragma unroll
;         for (int ai = 0; ai < 2; ++ai)
; #pragma unroll
;             for (int m = 0; m < 4; ++m) { const size_t row = (size_t)(row0 + ai * HALF + m * 16);
;                 const f32x4* sp = (const f32x4*)(SS + row * 32) + 2 * fq; float s;
;                 { const f32x4 t0 = sp[0], t1 = sp[1]; s = ((t0[0] + t0[1]) + (t0[2] + t0[3])) + ((t1[0] + t1[1]) + (t1[2] + t1[3])); }
;                 s += __shfl_xor(s, 16); s += __shfl_xor(s, 32);
;                 const float rstd = 1.0f / sqrtf(s * (1.0f / DM) + NORM_EPS);
; template <class Epi, class Sched, bool ALIGN_EPI = false, bool SP2 = false>
; __device__ __forceinline__ void gemm_phase(PG8_LAS unsigned char* lds, const Gemm g, const Sched& S, const Epi& E) {
;     ...
;             PG8_WAIT_V(8); PG8_WAIT_L(0); PG8_BAR; PG8_MMA(0, 0, At, B0); PG8_MMA(0, 1, At, B1); PG8_BAR; PG8_SCHED;
;             PG8_LDA(At, 1, 1); PG8_STAGE(PG8_SB(1, 0), b3, voffB); PG8_STAGE(PG8_SB(1, 1), b3 + hstep, voffB); PG8_STAGE(PG8_SA(1, 0), a3, voffA);
;             PG8_WAIT_V(8); PG8_WAIT_L(0); PG8_BAR; PG8_MMA(1, 0, At, B0); PG8_MMA(1, 1, At, B1); PG8_BAR; PG8_SCHED;
;     ...
;         if constexpr (ALIGN_EPI) { if (wr == 0) PG8_BAR; }
;         if constexpr (!Epi::AFTER_DRAIN) { E(acc, cur, wr, wc, fr, fq); S.done(cur); }
	s_add_i32 s47, s47, s54
	v_lshl_add_u64 v[158:159], v[158:159], 0, s[68:69]
	s_mov_b32 m0, s47
	ds_read_b128 v[212:215], v161 offset:49152
	ds_read_b128 v[216:219], v161 offset:50176
	ds_read_b128 v[220:223], v161 offset:51200
	ds_read_b128 v[224:227], v161 offset:52224
	ds_read_b128 v[228:231], v161 offset:53248
	ds_read_b128 v[232:235], v161 offset:54272
	ds_read_b128 v[236:239], v161 offset:55296
	ds_read_b128 v[240:243], v161 offset:56320
	global_load_lds_dwordx4 v[158:159], off
	s_add_i32 m0, s47, 0x2000
	s_add_u32 s18, s18, 0x80080
	v_lshl_add_u64 v[158:159], v[186:187], 0, s[68:69]
	s_addc_u32 s19, s19, 0
	s_add_i32 s47, s76, s54
	global_load_lds_dwordx4 v[158:159], off
	v_lshl_add_u64 v[158:159], s[18:19], 0, v[148:149]
	s_mov_b32 m0, s47
	s_nop 0
	global_load_lds_dwordx4 v[158:159], off
	v_lshl_add_u64 v[158:159], s[18:19], 0, v[144:145]
	s_add_i32 m0, s47, 0x2000
	s_nop 0
	global_load_lds_dwordx4 v[158:159], off
	v_lshl_add_u64 v[158:159], v[244:245], 0, s[68:69]
	s_mov_b32 m0, s5
	s_nop 0
	global_load_lds_dwordx4 v[158:159], off
	v_lshl_add_u64 v[158:159], v[246:247], 0, s[68:69]
	s_mov_b32 m0, s57
	s_nop 0
	global_load_lds_dwordx4 v[158:159], off
	s_nop 0
	s_waitcnt vmcnt(8)
	s_waitcnt lgkmcnt(0)
	s_setprio 1
	s_barrier
	v_mfma_f32_16x16x32_bf16 v[62:65], v[162:165], v[212:215], v[62:65]
	v_mfma_f32_16x16x32_bf16 v[58:61], v[170:173], v[212:215], v[58:61]
	v_mfma_f32_16x16x32_bf16 v[46:49], v[162:165], v[220:223], v[46:49]
	v_mfma_f32_16x16x32_bf16 v[42:45], v[170:173], v[220:223], v[42:45]
	v_mfma_f32_16x16x32_bf16 v[30:33], v[162:165], v[228:231], v[30:33]
	v_mfma_f32_16x16x32_bf16 v[26:29], v[170:173], v[228:231], v[26:29]
	v_mfma_f32_16x16x32_bf16 v[14:17], v[162:165], v[236:239], v[14:17]
	v_mfma_f32_16x16x32_bf16 v[10:13], v[170:173], v[236:239], v[10:13]
	v_mfma_f32_16x16x32_bf16 v[62:65], v[166:169], v[216:219], v[62:65]
	v_mfma_f32_16x16x32_bf16 v[58:61], v[174:177], v[216:219], v[58:61]
	v_mfma_f32_16x16x32_bf16 v[46:49], v[166:169], v[224:227], v[46:49]
	v_mfma_f32_16x16x32_bf16 v[42:45], v[174:177], v[224:227], v[42:45]
	v_mfma_f32_16x16x32_bf16 v[30:33], v[166:169], v[232:235], v[30:33]
	v_mfma_f32_16x16x32_bf16 v[26:29], v[174:177], v[232:235], v[26:29]
	v_mfma_f32_16x16x32_bf16 v[14:17], v[166:169], v[240:243], v[14:17]
	v_mfma_f32_16x16x32_bf16 v[10:13], v[174:177], v[240:243], v[10:13]
	v_mfma_f32_16x16x32_bf16 v[54:57], v[178:181], v[212:215], v[54:57]
	v_mfma_f32_16x16x32_bf16 v[50:53], v[204:207], v[212:215], v[50:53]
	v_mfma_f32_16x16x32_bf16 v[38:41], v[178:181], v[220:223], v[38:41]
	v_mfma_f32_16x16x32_bf16 v[34:37], v[204:207], v[220:223], v[34:37]
	v_mfma_f32_16x16x32_bf16 v[22:25], v[178:181], v[228:231], v[22:25]
	v_mfma_f32_16x16x32_bf16 v[18:21], v[204:207], v[228:231], v[18:21]
	v_mfma_f32_16x16x32_bf16 v[6:9], v[178:181], v[236:239], v[6:9]
	v_mfma_f32_16x16x32_bf16 v[2:5], v[204:207], v[236:239], v[2:5]
	v_mfma_f32_16x16x32_bf16 v[54:57], v[182:185], v[216:219], v[54:57]
	v_mfma_f32_16x16x32_bf16 v[50:53], v[208:211], v[216:219], v[50:53]
	v_mfma_f32_16x16x32_bf16 v[38:41], v[182:185], v[224:227], v[38:41]
	v_mfma_f32_16x16x32_bf16 v[34:37], v[208:211], v[224:227], v[34:37]
	v_mfma_f32_16x16x32_bf16 v[22:25], v[182:185], v[232:235], v[22:25]
	v_mfma_f32_16x16x32_bf16 v[18:21], v[208:211], v[232:235], v[18:21]
	v_mfma_f32_16x16x32_bf16 v[6:9], v[182:185], v[240:243], v[6:9]
	v_mfma_f32_16x16x32_bf16 v[2:5], v[208:211], v[240:243], v[2:5]
	s_setprio 0
	s_barrier
	s_add_i32 s46, s46, 2
	s_add_u32 s0, s0, 0x100
	s_addc_u32 s1, s1, 0
	s_add_u32 s78, s78, 0x100
	s_addc_u32 s79, s79, 0
	s_cmp_gt_u32 s46, 29
	s_cbranch_scc0 .LBB0_76
	s_cmp_lg_u64 s[42:43], 0
	s_cselect_b32 s32, 3, 1
.LBB0_79:
	v_xor_b32_e32 v159, 16, v192
	v_add_u32_e32 v163, 64, v193
	v_cmp_lt_i32_e32 vcc, v159, v163
	v_lshl_add_u32 v158, s34, 8, v1
	v_lshl_or_b32 v172, s28, 8, v160
	v_cndmask_b32_e32 v159, v192, v159, vcc
	v_lshlrev_b32_e32 v162, 2, v159
	v_xor_b32_e32 v159, 32, v192
	v_cmp_lt_i32_e32 vcc, v159, v163
	v_ashrrev_i32_e32 v173, 31, v172
	s_nop 0
	v_cndmask_b32_e32 v159, v192, v159, vcc
	v_lshlrev_b32_e32 v163, 2, v159
	v_ashrrev_i32_e32 v159, 31, v158
	v_lshlrev_b64 v[164:165], 7, v[158:159]
	v_lshl_add_u64 v[168:169], v[152:153], 0, v[164:165]
	global_load_dwordx4 v[164:167], v[168:169], off
	s_nop 0
	global_load_dwordx4 v[168:171], v[168:169], off offset:16
	s_waitcnt vmcnt(0)
	v_mov_b32_e32 v174, v164
	v_mov_b32_e32 v175, v168
	v_mov_b32_e32 v168, v165
	v_pk_add_f32 v[164:165], v[174:175], v[168:169]
	v_mov_b32_e32 v168, v166
	v_mov_b32_e32 v169, v170
	v_mov_b32_e32 v170, v167
	v_pk_add_f32 v[166:167], v[168:169], v[170:171]
	s_nop 0
	v_pk_add_f32 v[164:165], v[164:165], v[166:167]
	s_nop 0
	v_add_f32_e32 v164, v164, v165
	ds_bpermute_b32 v165, v162, v164
	s_waitcnt lgkmcnt(0)
	v_add_f32_e32 v164, v164, v165
	ds_bpermute_b32 v165, v163, v164
	s_waitcnt lgkmcnt(0)
; __device__ __forceinline__ unsigned cvt_pk_bf16(float lo, float hi) { const f32x2c_t v = {lo, hi}; const bf16x2c_t b = __builtin_convertvector(v, bf16x2c_t); return __builtin_bit_cast(unsigned, b); }
;     __device__ __forceinline__ void operator()(const f32x4 (&acc)[2][2][4][2], const Unit& u, int wr, int wc, int fr, int fq) const {
;     ...
;             for (int m = 0; m < 4; ++m) { const size_t row = (size_t)(row0 + ai * HALF + m * 16);
;                 const f32x4* sp = (const f32x4*)(SS + row * 32) + 2 * fq; float s;
;                 { const f32x4 t0 = sp[0], t1 = sp[1]; s = ((t0[0] + t0[1]) + (t0[2] + t0[3])) + ((t1[0] + t1[1]) + (t1[2] + t1[3])); }
;                 s += __shfl_xor(s, 16); s += __shfl_xor(s, 32);
;                 const float rstd = 1.0f / sqrtf(s * (1.0f / DM) + NORM_EPS);
; #pragma unroll
;                 for (int bj = 0; bj < 2; ++bj) { f32x4 v0 = acc[ai][bj][m][0] * rstd, v1 = acc[ai][bj][m][1] * rstd;
; #pragma unroll
;                     for (int e = 0; e < 4; ++e) { const float a = fmaxf(v0[e], 0.f), b = fmaxf(v1[e], 0.f); v0[e] = a * a; v1[e] = b * b; }
;                     u32x4 w; w.x = cvt_pk_bf16(v0[0], v0[1]); w.y = cvt_pk_bf16(v0[2], v0[3]); w.z = cvt_pk_bf16(v1[0], v1[1]); w.w = cvt_pk_bf16(v1[2], v1[3]);
;                     *(u32x4*)(H + row * DFF + col0 + bj * HALF) = w; } }
	v_add_f32_e32 v164, v164, v165
	v_fmamk_f32 v164, v164, 0x3a000000, v190
	v_cmp_gt_f32_e32 vcc, s72, v164
	v_mul_f32_e32 v165, 0x4f800000, v164
	s_nop 0
	v_cndmask_b32_e32 v164, v164, v165, vcc
	v_sqrt_f32_e32 v165, v164
	s_nop 0
	v_add_u32_e32 v166, -1, v165
	v_fma_f32 v167, -v166, v165, v164
	v_cmp_ge_f32_e64 s[0:1], 0, v167
	v_add_u32_e32 v167, 1, v165
	s_nop 0
	v_cndmask_b32_e64 v166, v165, v166, s[0:1]
	v_fma_f32 v165, -v167, v165, v164
	v_cmp_lt_f32_e64 s[0:1], 0, v165
	s_nop 1
	v_cndmask_b32_e64 v165, v166, v167, s[0:1]
	v_mul_f32_e32 v166, 0x37800000, v165
	v_cndmask_b32_e32 v165, v165, v166, vcc
	v_cmp_class_f32_e32 vcc, v164, v191
	s_nop 1
	v_cndmask_b32_e32 v164, v165, v164, vcc
	v_div_scale_f32 v165, s[0:1], v164, v164, 1.0
	v_rcp_f32_e32 v166, v165
	s_nop 0
	v_fma_f32 v167, -v165, v166, 1.0
	v_fmac_f32_e32 v166, v167, v166
	v_div_scale_f32 v167, vcc, 1.0, v164, 1.0
	v_mul_f32_e32 v168, v167, v166
	v_fma_f32 v169, -v165, v168, v167
	v_fmac_f32_e32 v168, v169, v166
	v_fma_f32 v165, -v165, v168, v167
	v_div_fmas_f32 v165, v165, v166, v168
	v_div_fixup_f32 v164, v165, v164, 1.0
	v_pk_mul_f32 v[128:129], v[128:129], v[164:165] op_sel_hi:[1,0]
	v_pk_mul_f32 v[126:127], v[126:127], v[164:165] op_sel_hi:[1,0]
	v_pk_mul_f32 v[122:123], v[122:123], v[164:165] op_sel_hi:[1,0]
	v_pk_mul_f32 v[124:125], v[124:125], v[164:165] op_sel_hi:[1,0]
	v_max_f32_e32 v126, 0, v126
	v_max_f32_e32 v122, 0, v122
	v_max_f32_e32 v127, 0, v127
	v_max_f32_e32 v123, 0, v123
	v_max_f32_e32 v128, 0, v128
	v_max_f32_e32 v129, 0, v129
	v_lshlrev_b64 v[166:167], 14, v[158:159]
	v_pk_mul_f32 v[126:127], v[126:127], v[126:127]
	v_pk_mul_f32 v[122:123], v[122:123], v[122:123]
	v_max_f32_e32 v124, 0, v124
	v_max_f32_e32 v125, 0, v125
	v_pk_mul_f32 v[128:129], v[128:129], v[128:129]
	v_pk_mul_f32 v[168:169], v[124:125], v[124:125]
	v_cvt_pk_bf16_f32 v124, v126, v127
	v_cvt_pk_bf16_f32 v125, v128, v129
	v_cvt_pk_bf16_f32 v126, v122, v123
	v_lshl_add_u64 v[128:129], s[92:93], 0, v[166:167]
	v_lshlrev_b64 v[122:123], 1, v[172:173]
	v_pk_mul_f32 v[114:115], v[114:115], v[164:165] op_sel_hi:[1,0]
	v_cvt_pk_bf16_f32 v127, v168, v169
	v_lshl_add_u64 v[128:129], v[128:129], 0, v[122:123]
	v_pk_mul_f32 v[120:121], v[120:121], v[164:165] op_sel_hi:[1,0]
	v_pk_mul_f32 v[118:119], v[118:119], v[164:165] op_sel_hi:[1,0]
	v_pk_mul_f32 v[116:117], v[116:117], v[164:165] op_sel_hi:[1,0]
	v_max_f32_e32 v114, 0, v114
	v_max_f32_e32 v115, 0, v115
	global_store_dwordx4 v[128:129], v[124:127], off
	v_max_f32_e32 v118, 0, v118
	v_max_f32_e32 v119, 0, v119
	v_pk_mul_f32 v[124:125], v[114:115], v[114:115]
	v_max_f32_e32 v114, 0, v120
	v_max_f32_e32 v116, 0, v116
	v_max_f32_e32 v115, 0, v121
	v_max_f32_e32 v117, 0, v117
	v_pk_mul_f32 v[118:119], v[118:119], v[118:119]
	v_pk_mul_f32 v[120:121], v[114:115], v[114:115]
	v_pk_mul_f32 v[126:127], v[116:117], v[116:117]
	v_cvt_pk_bf16_f32 v114, v118, v119
	v_cvt_pk_bf16_f32 v115, v120, v121
	v_cvt_pk_bf16_f32 v116, v124, v125
	v_cvt_pk_bf16_f32 v117, v126, v127
	global_store_dwordx4 v[128:129], v[114:117], off offset:256
	s_bitcmp1_b32 s32, 1
	s_cbranch_scc0 .Lalign76
	s_barrier
.Lalign76:
	s_nop 1
	v_or_b32_e32 v114, 16, v158
	v_ashrrev_i32_e32 v115, 31, v114
	v_lshlrev_b64 v[116:117], 7, v[114:115]
	v_lshl_add_u64 v[120:121], v[152:153], 0, v[116:117]
	global_load_dwordx4 v[116:119], v[120:121], off
	global_load_dwordx4 v[124:127], v[120:121], off offset:16
	v_lshlrev_b64 v[114:115], 14, v[114:115]
	s_waitcnt vmcnt(1)
	v_mov_b32_e32 v120, v116
	s_waitcnt vmcnt(0)
	v_mov_b32_e32 v121, v124
	v_mov_b32_e32 v124, v117
	v_pk_add_f32 v[116:117], v[120:121], v[124:125]
	v_mov_b32_e32 v120, v118
	v_mov_b32_e32 v121, v126
	v_mov_b32_e32 v126, v119
	v_pk_add_f32 v[118:119], v[120:121], v[126:127]
	s_nop 0
	v_pk_add_f32 v[116:117], v[116:117], v[118:119]
	s_nop 0
	v_add_f32_e32 v116, v116, v117
	ds_bpermute_b32 v117, v162, v116
	s_waitcnt lgkmcnt(0)
	v_add_f32_e32 v116, v116, v117
	ds_bpermute_b32 v117, v163, v116
	s_waitcnt lgkmcnt(0)
	v_add_f32_e32 v116, v116, v117
	v_fmamk_f32 v116, v116, 0x3a000000, v190
	v_cmp_gt_f32_e32 vcc, s72, v116
	v_mul_f32_e32 v117, 0x4f800000, v116
	s_nop 0
	v_cndmask_b32_e32 v116, v116, v117, vcc
	v_sqrt_f32_e32 v117, v116
	s_nop 0
	v_add_u32_e32 v118, -1, v117
	v_fma_f32 v119, -v118, v117, v116
	v_cmp_ge_f32_e64 s[0:1], 0, v119
	v_add_u32_e32 v119, 1, v117
	s_nop 0
	v_cndmask_b32_e64 v118, v117, v118, s[0:1]
	v_fma_f32 v117, -v119, v117, v116
	v_cmp_lt_f32_e64 s[0:1], 0, v117
	s_nop 1
	v_cndmask_b32_e64 v117, v118, v119, s[0:1]
	v_mul_f32_e32 v118, 0x37800000, v117
	v_cndmask_b32_e32 v117, v117, v118, vcc
	v_cmp_class_f32_e32 vcc, v116, v191
	s_nop 1
	v_cndmask_b32_e32 v116, v117, v116, vcc
	v_div_scale_f32 v117, s[0:1], v116, v116, 1.0
	v_rcp_f32_e32 v118, v117
	s_nop 0
	v_fma_f32 v119, -v117, v118, 1.0
	v_fmac_f32_e32 v118, v119, v118
	v_div_scale_f32 v119, vcc, 1.0, v116, 1.0
	v_mul_f32_e32 v120, v119, v118
	v_fma_f32 v121, -v117, v120, v119
	v_fmac_f32_e32 v120, v121, v118
	v_fma_f32 v117, -v117, v120, v119
	v_div_fmas_f32 v117, v117, v118, v120
	v_div_fixup_f32 v116, v117, v116, 1.0
	v_pk_mul_f32 v[110:111], v[110:111], v[116:117] op_sel_hi:[1,0]
	v_pk_mul_f32 v[106:107], v[106:107], v[116:117] op_sel_hi:[1,0]
	v_pk_mul_f32 v[112:113], v[112:113], v[116:117] op_sel_hi:[1,0]
	v_pk_mul_f32 v[108:109], v[108:109], v[116:117] op_sel_hi:[1,0]
	v_max_f32_e32 v110, 0, v110
	v_max_f32_e32 v106, 0, v106
	v_max_f32_e32 v111, 0, v111
	v_max_f32_e32 v107, 0, v107
	v_pk_mul_f32 v[110:111], v[110:111], v[110:111]
	v_pk_mul_f32 v[118:119], v[106:107], v[106:107]
	v_max_f32_e32 v106, 0, v112
	v_max_f32_e32 v108, 0, v108
; __device__ __forceinline__ unsigned cvt_pk_bf16(float lo, float hi) { const f32x2c_t v = {lo, hi}; const bf16x2c_t b = __builtin_convertvector(v, bf16x2c_t); return __builtin_bit_cast(unsigned, b); }
;     __device__ __forceinline__ void operator()(const f32x4 (&acc)[2][2][4][2], const Unit& u, int wr, int wc, int fr, int fq) const {
;     ...
;         for (int ai = 0; ai < 2; ++ai)
; #pragma unroll
;             for (int m = 0; m < 4; ++m) { const size_t row = (size_t)(row0 + ai * HALF + m * 16);
;                 const f32x4* sp = (const f32x4*)(SS + row * 32) + 2 * fq; float s;
;                 { const f32x4 t0 = sp[0], t1 = sp[1]; s = ((t0[0] + t0[1]) + (t0[2] + t0[3])) + ((t1[0] + t1[1]) + (t1[2] + t1[3])); }
;                 s += __shfl_xor(s, 16); s += __shfl_xor(s, 32);
;                 const float rstd = 1.0f / sqrtf(s * (1.0f / DM) + NORM_EPS);
; #pragma unroll
;                 for (int bj = 0; bj < 2; ++bj) { f32x4 v0 = acc[ai][bj][m][0] * rstd, v1 = acc[ai][bj][m][1] * rstd;
; #pragma unroll
;                     for (int e = 0; e < 4; ++e) { const float a = fmaxf(v0[e], 0.f), b = fmaxf(v1[e], 0.f); v0[e] = a * a; v1[e] = b * b; }
;                     u32x4 w; w.x = cvt_pk_bf16(v0[0], v0[1]); w.y = cvt_pk_bf16(v0[2], v0[3]); w.z = cvt_pk_bf16(v1[0], v1[1]); w.w = cvt_pk_bf16(v1[2], v1[3]);
;                     *(u32x4*)(H + row * DFF + col0 + bj * HALF) = w; } }
	v_max_f32_e32 v107, 0, v113
	v_max_f32_e32 v109, 0, v109
	v_pk_mul_f32 v[112:113], v[106:107], v[106:107]
	v_pk_mul_f32 v[120:121], v[108:109], v[108:109]
	v_cvt_pk_bf16_f32 v106, v110, v111
	v_lshl_add_u64 v[110:111], s[92:93], 0, v[114:115]
	v_pk_mul_f32 v[98:99], v[98:99], v[116:117] op_sel_hi:[1,0]
	v_cvt_pk_bf16_f32 v107, v112, v113
	v_cvt_pk_bf16_f32 v108, v118, v119
	v_cvt_pk_bf16_f32 v109, v120, v121
	v_lshl_add_u64 v[110:111], v[110:111], 0, v[122:123]
	v_pk_mul_f32 v[104:105], v[104:105], v[116:117] op_sel_hi:[1,0]
	v_pk_mul_f32 v[102:103], v[102:103], v[116:117] op_sel_hi:[1,0]
	v_pk_mul_f32 v[100:101], v[100:101], v[116:117] op_sel_hi:[1,0]
	v_max_f32_e32 v98, 0, v98
	v_max_f32_e32 v99, 0, v99
	global_store_dwordx4 v[110:111], v[106:109], off
	v_max_f32_e32 v102, 0, v102
	v_max_f32_e32 v103, 0, v103
	v_pk_mul_f32 v[106:107], v[98:99], v[98:99]
	v_max_f32_e32 v98, 0, v104
	v_max_f32_e32 v100, 0, v100
	v_max_f32_e32 v99, 0, v105
	v_max_f32_e32 v101, 0, v101
	v_pk_mul_f32 v[102:103], v[102:103], v[102:103]
	v_pk_mul_f32 v[104:105], v[98:99], v[98:99]
	v_pk_mul_f32 v[108:109], v[100:101], v[100:101]
	v_cvt_pk_bf16_f32 v98, v102, v103
	v_cvt_pk_bf16_f32 v99, v104, v105
	v_cvt_pk_bf16_f32 v100, v106, v107
	v_cvt_pk_bf16_f32 v101, v108, v109
	global_store_dwordx4 v[110:111], v[98:101], off offset:256
	s_nop 1
	v_or_b32_e32 v98, 32, v158
	v_ashrrev_i32_e32 v99, 31, v98
	v_lshlrev_b64 v[100:101], 7, v[98:99]
	v_lshl_add_u64 v[100:101], v[152:153], 0, v[100:101]
	global_load_dwordx4 v[102:105], v[100:101], off
	global_load_dwordx4 v[106:109], v[100:101], off offset:16
	v_lshlrev_b64 v[98:99], 14, v[98:99]
	s_waitcnt vmcnt(1)
	v_mov_b32_e32 v100, v102
	s_waitcnt vmcnt(0)
	v_mov_b32_e32 v101, v106
	v_mov_b32_e32 v106, v103
	v_mov_b32_e32 v102, v104
	v_mov_b32_e32 v103, v108
	v_mov_b32_e32 v108, v105
	v_pk_add_f32 v[100:101], v[100:101], v[106:107]
	v_pk_add_f32 v[102:103], v[102:103], v[108:109]
	s_nop 0
	v_pk_add_f32 v[100:101], v[100:101], v[102:103]
	s_nop 0
	v_add_f32_e32 v100, v100, v101
	ds_bpermute_b32 v101, v162, v100
	s_waitcnt lgkmcnt(0)
	v_add_f32_e32 v100, v100, v101
	ds_bpermute_b32 v101, v163, v100
	s_waitcnt lgkmcnt(0)
	v_add_f32_e32 v100, v100, v101
	v_fmamk_f32 v100, v100, 0x3a000000, v190
	v_cmp_gt_f32_e32 vcc, s72, v100
	v_mul_f32_e32 v101, 0x4f800000, v100
	s_nop 0
	v_cndmask_b32_e32 v100, v100, v101, vcc
	v_sqrt_f32_e32 v101, v100
	s_nop 0
	v_add_u32_e32 v102, -1, v101
	v_fma_f32 v103, -v102, v101, v100
	v_cmp_ge_f32_e64 s[0:1], 0, v103
	v_add_u32_e32 v103, 1, v101
	s_nop 0
	v_cndmask_b32_e64 v102, v101, v102, s[0:1]
	v_fma_f32 v101, -v103, v101, v100
	v_cmp_lt_f32_e64 s[0:1], 0, v101
	s_nop 1
	v_cndmask_b32_e64 v101, v102, v103, s[0:1]
	v_mul_f32_e32 v102, 0x37800000, v101
	v_cndmask_b32_e32 v101, v101, v102, vcc
	v_cmp_class_f32_e32 vcc, v100, v191
	s_nop 1
	v_cndmask_b32_e32 v100, v101, v100, vcc
	v_div_scale_f32 v101, s[0:1], v100, v100, 1.0
	v_rcp_f32_e32 v102, v101
	s_nop 0
	v_fma_f32 v103, -v101, v102, 1.0
	v_fmac_f32_e32 v102, v103, v102
	v_div_scale_f32 v103, vcc, 1.0, v100, 1.0
	v_mul_f32_e32 v104, v103, v102
	v_fma_f32 v105, -v101, v104, v103
	v_fmac_f32_e32 v104, v105, v102
	v_fma_f32 v101, -v101, v104, v103
	v_div_fmas_f32 v101, v101, v102, v104
	v_div_fixup_f32 v100, v101, v100, 1.0
	v_pk_mul_f32 v[94:95], v[94:95], v[100:101] op_sel_hi:[1,0]
	v_pk_mul_f32 v[90:91], v[90:91], v[100:101] op_sel_hi:[1,0]
	v_pk_mul_f32 v[96:97], v[96:97], v[100:101] op_sel_hi:[1,0]
	v_pk_mul_f32 v[92:93], v[92:93], v[100:101] op_sel_hi:[1,0]
	v_max_f32_e32 v94, 0, v94
	v_max_f32_e32 v90, 0, v90
	v_max_f32_e32 v95, 0, v95
	v_max_f32_e32 v91, 0, v91
	v_pk_mul_f32 v[94:95], v[94:95], v[94:95]
	v_pk_mul_f32 v[102:103], v[90:91], v[90:91]
	v_max_f32_e32 v90, 0, v96
	v_max_f32_e32 v92, 0, v92
	v_max_f32_e32 v91, 0, v97
	v_max_f32_e32 v93, 0, v93
	v_pk_mul_f32 v[96:97], v[90:91], v[90:91]
	v_pk_mul_f32 v[104:105], v[92:93], v[92:93]
	v_cvt_pk_bf16_f32 v90, v94, v95
	v_lshl_add_u64 v[94:95], s[92:93], 0, v[98:99]
	v_pk_mul_f32 v[82:83], v[82:83], v[100:101] op_sel_hi:[1,0]
	v_cvt_pk_bf16_f32 v91, v96, v97
	v_cvt_pk_bf16_f32 v92, v102, v103
	v_cvt_pk_bf16_f32 v93, v104, v105
	v_lshl_add_u64 v[94:95], v[94:95], 0, v[122:123]
	v_pk_mul_f32 v[88:89], v[88:89], v[100:101] op_sel_hi:[1,0]
	v_pk_mul_f32 v[86:87], v[86:87], v[100:101] op_sel_hi:[1,0]
	v_pk_mul_f32 v[84:85], v[84:85], v[100:101] op_sel_hi:[1,0]
	v_max_f32_e32 v82, 0, v82
	v_max_f32_e32 v83, 0, v83
	global_store_dwordx4 v[94:95], v[90:93], off
	v_max_f32_e32 v86, 0, v86
	v_max_f32_e32 v87, 0, v87
	v_pk_mul_f32 v[90:91], v[82:83], v[82:83]
	v_max_f32_e32 v82, 0, v88
	v_max_f32_e32 v84, 0, v84
	v_max_f32_e32 v83, 0, v89
	v_max_f32_e32 v85, 0, v85
	v_pk_mul_f32 v[86:87], v[86:87], v[86:87]
	v_pk_mul_f32 v[88:89], v[82:83], v[82:83]
	v_pk_mul_f32 v[92:93], v[84:85], v[84:85]
	v_cvt_pk_bf16_f32 v82, v86, v87
	v_cvt_pk_bf16_f32 v83, v88, v89
	v_cvt_pk_bf16_f32 v84, v90, v91
	v_cvt_pk_bf16_f32 v85, v92, v93
	global_store_dwordx4 v[94:95], v[82:85], off offset:256
	s_nop 1
	v_or_b32_e32 v82, 48, v158
	v_ashrrev_i32_e32 v83, 31, v82
	v_lshlrev_b64 v[84:85], 7, v[82:83]
	v_lshl_add_u64 v[84:85], v[152:153], 0, v[84:85]
	global_load_dwordx4 v[86:89], v[84:85], off
	global_load_dwordx4 v[90:93], v[84:85], off offset:16
	v_lshlrev_b64 v[82:83], 14, v[82:83]
	s_waitcnt vmcnt(1)
	v_mov_b32_e32 v84, v86
	s_waitcnt vmcnt(0)
	v_mov_b32_e32 v85, v90
	v_mov_b32_e32 v90, v87
	v_mov_b32_e32 v86, v88
	v_mov_b32_e32 v87, v92
	v_mov_b32_e32 v92, v89
	v_pk_add_f32 v[84:85], v[84:85], v[90:91]
	v_pk_add_f32 v[86:87], v[86:87], v[92:93]
	s_nop 0
	v_pk_add_f32 v[84:85], v[84:85], v[86:87]
	s_nop 0
	v_add_f32_e32 v84, v84, v85
	ds_bpermute_b32 v85, v162, v84
	s_waitcnt lgkmcnt(0)
; __device__ __forceinline__ unsigned cvt_pk_bf16(float lo, float hi) { const f32x2c_t v = {lo, hi}; const bf16x2c_t b = __builtin_convertvector(v, bf16x2c_t); return __builtin_bit_cast(unsigned, b); }
;     __device__ __forceinline__ void operator()(const f32x4 (&acc)[2][2][4][2], const Unit& u, int wr, int wc, int fr, int fq) const {
;     ...
;         for (int ai = 0; ai < 2; ++ai)
; #pragma unroll
;             for (int m = 0; m < 4; ++m) { const size_t row = (size_t)(row0 + ai * HALF + m * 16);
;                 const f32x4* sp = (const f32x4*)(SS + row * 32) + 2 * fq; float s;
;                 { const f32x4 t0 = sp[0], t1 = sp[1]; s = ((t0[0] + t0[1]) + (t0[2] + t0[3])) + ((t1[0] + t1[1]) + (t1[2] + t1[3])); }
;                 s += __shfl_xor(s, 16); s += __shfl_xor(s, 32);
;                 const float rstd = 1.0f / sqrtf(s * (1.0f / DM) + NORM_EPS);
; #pragma unroll
;                 for (int bj = 0; bj < 2; ++bj) { f32x4 v0 = acc[ai][bj][m][0] * rstd, v1 = acc[ai][bj][m][1] * rstd;
; #pragma unroll
;                     for (int e = 0; e < 4; ++e) { const float a = fmaxf(v0[e], 0.f), b = fmaxf(v1[e], 0.f); v0[e] = a * a; v1[e] = b * b; }
;                     u32x4 w; w.x = cvt_pk_bf16(v0[0], v0[1]); w.y = cvt_pk_bf16(v0[2], v0[3]); w.z = cvt_pk_bf16(v1[0], v1[1]); w.w = cvt_pk_bf16(v1[2], v1[3]);
;                     *(u32x4*)(H + row * DFF + col0 + bj * HALF) = w; } }
	v_add_f32_e32 v84, v84, v85
	ds_bpermute_b32 v85, v163, v84
	s_waitcnt lgkmcnt(0)
	v_add_f32_e32 v84, v84, v85
	v_fmamk_f32 v84, v84, 0x3a000000, v190
	v_cmp_gt_f32_e32 vcc, s72, v84
	v_mul_f32_e32 v85, 0x4f800000, v84
	s_nop 0
	v_cndmask_b32_e32 v84, v84, v85, vcc
	v_sqrt_f32_e32 v85, v84
	s_nop 0
	v_add_u32_e32 v86, -1, v85
	v_fma_f32 v87, -v86, v85, v84
	v_cmp_ge_f32_e64 s[0:1], 0, v87
	v_add_u32_e32 v87, 1, v85
	s_nop 0
	v_cndmask_b32_e64 v86, v85, v86, s[0:1]
	v_fma_f32 v85, -v87, v85, v84
	v_cmp_lt_f32_e64 s[0:1], 0, v85
	s_nop 1
	v_cndmask_b32_e64 v85, v86, v87, s[0:1]
	v_mul_f32_e32 v86, 0x37800000, v85
	v_cndmask_b32_e32 v85, v85, v86, vcc
	v_cmp_class_f32_e32 vcc, v84, v191
	s_nop 1
	v_cndmask_b32_e32 v84, v85, v84, vcc
	v_div_scale_f32 v85, s[0:1], v84, v84, 1.0
	v_rcp_f32_e32 v86, v85
	s_nop 0
	v_fma_f32 v87, -v85, v86, 1.0
	v_fmac_f32_e32 v86, v87, v86
	v_div_scale_f32 v87, vcc, 1.0, v84, 1.0
	v_mul_f32_e32 v88, v87, v86
	v_fma_f32 v89, -v85, v88, v87
	v_fmac_f32_e32 v88, v89, v86
	v_fma_f32 v85, -v85, v88, v87
	v_div_fmas_f32 v85, v85, v86, v88
	v_div_fixup_f32 v84, v85, v84, 1.0
	v_pk_mul_f32 v[78:79], v[78:79], v[84:85] op_sel_hi:[1,0]
	v_pk_mul_f32 v[74:75], v[74:75], v[84:85] op_sel_hi:[1,0]
	v_pk_mul_f32 v[80:81], v[80:81], v[84:85] op_sel_hi:[1,0]
	v_pk_mul_f32 v[76:77], v[76:77], v[84:85] op_sel_hi:[1,0]
	v_max_f32_e32 v78, 0, v78
	v_max_f32_e32 v74, 0, v74
	v_max_f32_e32 v79, 0, v79
	v_max_f32_e32 v75, 0, v75
	v_pk_mul_f32 v[78:79], v[78:79], v[78:79]
	v_pk_mul_f32 v[86:87], v[74:75], v[74:75]
	v_max_f32_e32 v74, 0, v80
	v_max_f32_e32 v76, 0, v76
	v_max_f32_e32 v75, 0, v81
	v_max_f32_e32 v77, 0, v77
	v_pk_mul_f32 v[80:81], v[74:75], v[74:75]
	v_pk_mul_f32 v[88:89], v[76:77], v[76:77]
	v_cvt_pk_bf16_f32 v74, v78, v79
	v_lshl_add_u64 v[78:79], s[92:93], 0, v[82:83]
	v_pk_mul_f32 v[66:67], v[66:67], v[84:85] op_sel_hi:[1,0]
	v_cvt_pk_bf16_f32 v75, v80, v81
	v_cvt_pk_bf16_f32 v76, v86, v87
	v_cvt_pk_bf16_f32 v77, v88, v89
	v_lshl_add_u64 v[78:79], v[78:79], 0, v[122:123]
	v_pk_mul_f32 v[72:73], v[72:73], v[84:85] op_sel_hi:[1,0]
	v_pk_mul_f32 v[70:71], v[70:71], v[84:85] op_sel_hi:[1,0]
	v_pk_mul_f32 v[68:69], v[68:69], v[84:85] op_sel_hi:[1,0]
	v_max_f32_e32 v66, 0, v66
	v_max_f32_e32 v67, 0, v67
	global_store_dwordx4 v[78:79], v[74:77], off
	v_max_f32_e32 v70, 0, v70
	v_max_f32_e32 v71, 0, v71
	v_pk_mul_f32 v[74:75], v[66:67], v[66:67]
	v_max_f32_e32 v66, 0, v72
	v_max_f32_e32 v68, 0, v68
	v_max_f32_e32 v67, 0, v73
	v_max_f32_e32 v69, 0, v69
	v_pk_mul_f32 v[70:71], v[70:71], v[70:71]
	v_pk_mul_f32 v[72:73], v[66:67], v[66:67]
	v_pk_mul_f32 v[76:77], v[68:69], v[68:69]
	v_cvt_pk_bf16_f32 v66, v70, v71
	v_cvt_pk_bf16_f32 v67, v72, v73
	v_cvt_pk_bf16_f32 v68, v74, v75
	v_cvt_pk_bf16_f32 v69, v76, v77
	global_store_dwordx4 v[78:79], v[66:69], off offset:256
	s_nop 1
	v_add_u32_e32 v66, 0x80, v158
	v_ashrrev_i32_e32 v67, 31, v66
	v_lshlrev_b64 v[68:69], 7, v[66:67]
	v_lshl_add_u64 v[68:69], v[152:153], 0, v[68:69]
	global_load_dwordx4 v[70:73], v[68:69], off
	global_load_dwordx4 v[74:77], v[68:69], off offset:16
	v_lshlrev_b64 v[66:67], 14, v[66:67]
	s_waitcnt vmcnt(1)
	v_mov_b32_e32 v68, v70
	s_waitcnt vmcnt(0)
	v_mov_b32_e32 v69, v74
	v_mov_b32_e32 v74, v71
	v_mov_b32_e32 v70, v72
	v_mov_b32_e32 v71, v76
	v_mov_b32_e32 v76, v73
	v_pk_add_f32 v[68:69], v[68:69], v[74:75]
	v_pk_add_f32 v[70:71], v[70:71], v[76:77]
	s_nop 0
	v_pk_add_f32 v[68:69], v[68:69], v[70:71]
	s_nop 0
	v_add_f32_e32 v68, v68, v69
	ds_bpermute_b32 v69, v162, v68
	s_waitcnt lgkmcnt(0)
	v_add_f32_e32 v68, v68, v69
	ds_bpermute_b32 v69, v163, v68
	s_waitcnt lgkmcnt(0)
	v_add_f32_e32 v68, v68, v69
	v_fmamk_f32 v68, v68, 0x3a000000, v190
	v_cmp_gt_f32_e32 vcc, s72, v68
	v_mul_f32_e32 v69, 0x4f800000, v68
	s_nop 0
	v_cndmask_b32_e32 v68, v68, v69, vcc
	v_sqrt_f32_e32 v69, v68
	s_nop 0
	v_add_u32_e32 v70, -1, v69
	v_fma_f32 v71, -v70, v69, v68
	v_cmp_ge_f32_e64 s[0:1], 0, v71
	v_add_u32_e32 v71, 1, v69
	s_nop 0
	v_cndmask_b32_e64 v70, v69, v70, s[0:1]
	v_fma_f32 v69, -v71, v69, v68
	v_cmp_lt_f32_e64 s[0:1], 0, v69
	s_nop 1
	v_cndmask_b32_e64 v69, v70, v71, s[0:1]
	v_mul_f32_e32 v70, 0x37800000, v69
	v_cndmask_b32_e32 v69, v69, v70, vcc
	v_cmp_class_f32_e32 vcc, v68, v191
	s_nop 1
	v_cndmask_b32_e32 v68, v69, v68, vcc
	v_div_scale_f32 v69, s[0:1], v68, v68, 1.0
	v_rcp_f32_e32 v70, v69
	s_nop 0
	v_fma_f32 v71, -v69, v70, 1.0
	v_fmac_f32_e32 v70, v71, v70
	v_div_scale_f32 v71, vcc, 1.0, v68, 1.0
	v_mul_f32_e32 v72, v71, v70
	v_fma_f32 v73, -v69, v72, v71
	v_fmac_f32_e32 v72, v73, v70
	v_fma_f32 v69, -v69, v72, v71
	v_div_fmas_f32 v69, v69, v70, v72
	v_div_fixup_f32 v68, v69, v68, 1.0
	v_pk_mul_f32 v[62:63], v[62:63], v[68:69] op_sel_hi:[1,0]
	v_pk_mul_f32 v[58:59], v[58:59], v[68:69] op_sel_hi:[1,0]
	v_pk_mul_f32 v[64:65], v[64:65], v[68:69] op_sel_hi:[1,0]
	v_pk_mul_f32 v[60:61], v[60:61], v[68:69] op_sel_hi:[1,0]
	v_max_f32_e32 v62, 0, v62
	v_max_f32_e32 v58, 0, v58
	v_max_f32_e32 v63, 0, v63
	v_max_f32_e32 v59, 0, v59
	v_pk_mul_f32 v[62:63], v[62:63], v[62:63]
	v_pk_mul_f32 v[70:71], v[58:59], v[58:59]
	v_max_f32_e32 v58, 0, v64
	v_max_f32_e32 v60, 0, v60
	v_max_f32_e32 v59, 0, v65
	v_max_f32_e32 v61, 0, v61
	v_pk_mul_f32 v[64:65], v[58:59], v[58:59]
	v_pk_mul_f32 v[72:73], v[60:61], v[60:61]
	v_cvt_pk_bf16_f32 v58, v62, v63
	v_lshl_add_u64 v[62:63], s[92:93], 0, v[66:67]
	v_pk_mul_f32 v[50:51], v[50:51], v[68:69] op_sel_hi:[1,0]
	v_cvt_pk_bf16_f32 v59, v64, v65
	v_cvt_pk_bf16_f32 v60, v70, v71
	v_cvt_pk_bf16_f32 v61, v72, v73
	v_lshl_add_u64 v[62:63], v[62:63], 0, v[122:123]
	v_pk_mul_f32 v[56:57], v[56:57], v[68:69] op_sel_hi:[1,0]
	v_pk_mul_f32 v[54:55], v[54:55], v[68:69] op_sel_hi:[1,0]
	v_pk_mul_f32 v[52:53], v[52:53], v[68:69] op_sel_hi:[1,0]
	v_max_f32_e32 v50, 0, v50
	v_max_f32_e32 v51, 0, v51
	global_store_dwordx4 v[62:63], v[58:61], off
	v_max_f32_e32 v54, 0, v54
	v_max_f32_e32 v55, 0, v55
	v_pk_mul_f32 v[58:59], v[50:51], v[50:51]
	v_max_f32_e32 v50, 0, v56
	v_max_f32_e32 v52, 0, v52
	v_max_f32_e32 v51, 0, v57
	v_max_f32_e32 v53, 0, v53
	v_pk_mul_f32 v[54:55], v[54:55], v[54:55]
	v_pk_mul_f32 v[56:57], v[50:51], v[50:51]
	v_pk_mul_f32 v[60:61], v[52:53], v[52:53]
	v_cvt_pk_bf16_f32 v50, v54, v55
	v_cvt_pk_bf16_f32 v51, v56, v57
	v_cvt_pk_bf16_f32 v52, v58, v59
	v_cvt_pk_bf16_f32 v53, v60, v61
	global_store_dwordx4 v[62:63], v[50:53], off offset:256
	s_nop 1
	v_add_u32_e32 v50, 0x90, v158
	v_ashrrev_i32_e32 v51, 31, v50
	v_lshlrev_b64 v[52:53], 7, v[50:51]
	v_lshl_add_u64 v[52:53], v[152:153], 0, v[52:53]
	global_load_dwordx4 v[54:57], v[52:53], off
	global_load_dwordx4 v[58:61], v[52:53], off offset:16
	v_lshlrev_b64 v[50:51], 14, v[50:51]
	s_waitcnt vmcnt(1)
; __device__ __forceinline__ unsigned cvt_pk_bf16(float lo, float hi) { const f32x2c_t v = {lo, hi}; const bf16x2c_t b = __builtin_convertvector(v, bf16x2c_t); return __builtin_bit_cast(unsigned, b); }
;     __device__ __forceinline__ void operator()(const f32x4 (&acc)[2][2][4][2], const Unit& u, int wr, int wc, int fr, int fq) const {
;     ...
;         for (int ai = 0; ai < 2; ++ai)
; #pragma unroll
;             for (int m = 0; m < 4; ++m) { const size_t row = (size_t)(row0 + ai * HALF + m * 16);
;                 const f32x4* sp = (const f32x4*)(SS + row * 32) + 2 * fq; float s;
;                 { const f32x4 t0 = sp[0], t1 = sp[1]; s = ((t0[0] + t0[1]) + (t0[2] + t0[3])) + ((t1[0] + t1[1]) + (t1[2] + t1[3])); }
;                 s += __shfl_xor(s, 16); s += __shfl_xor(s, 32);
;                 const float rstd = 1.0f / sqrtf(s * (1.0f / DM) + NORM_EPS);
; #pragma unroll
;                 for (int bj = 0; bj < 2; ++bj) { f32x4 v0 = acc[ai][bj][m][0] * rstd, v1 = acc[ai][bj][m][1] * rstd;
; #pragma unroll
;                     for (int e = 0; e < 4; ++e) { const float a = fmaxf(v0[e], 0.f), b = fmaxf(v1[e], 0.f); v0[e] = a * a; v1[e] = b * b; }
;                     u32x4 w; w.x = cvt_pk_bf16(v0[0], v0[1]); w.y = cvt_pk_bf16(v0[2], v0[3]); w.z = cvt_pk_bf16(v1[0], v1[1]); w.w = cvt_pk_bf16(v1[2], v1[3]);
;                     *(u32x4*)(H + row * DFF + col0 + bj * HALF) = w; } }
	v_mov_b32_e32 v52, v54
	s_waitcnt vmcnt(0)
	v_mov_b32_e32 v53, v58
	v_mov_b32_e32 v58, v55
	v_mov_b32_e32 v54, v56
	v_mov_b32_e32 v55, v60
	v_mov_b32_e32 v60, v57
	v_pk_add_f32 v[52:53], v[52:53], v[58:59]
	v_pk_add_f32 v[54:55], v[54:55], v[60:61]
	s_nop 0
	v_pk_add_f32 v[52:53], v[52:53], v[54:55]
	s_nop 0
	v_add_f32_e32 v52, v52, v53
	ds_bpermute_b32 v53, v162, v52
	s_waitcnt lgkmcnt(0)
	v_add_f32_e32 v52, v52, v53
	ds_bpermute_b32 v53, v163, v52
	s_waitcnt lgkmcnt(0)
	v_add_f32_e32 v52, v52, v53
	v_fmamk_f32 v52, v52, 0x3a000000, v190
	v_cmp_gt_f32_e32 vcc, s72, v52
	v_mul_f32_e32 v53, 0x4f800000, v52
	s_nop 0
	v_cndmask_b32_e32 v52, v52, v53, vcc
	v_sqrt_f32_e32 v53, v52
	s_nop 0
	v_add_u32_e32 v54, -1, v53
	v_fma_f32 v55, -v54, v53, v52
	v_cmp_ge_f32_e64 s[0:1], 0, v55
	v_add_u32_e32 v55, 1, v53
	s_nop 0
	v_cndmask_b32_e64 v54, v53, v54, s[0:1]
	v_fma_f32 v53, -v55, v53, v52
	v_cmp_lt_f32_e64 s[0:1], 0, v53
	s_nop 1
	v_cndmask_b32_e64 v53, v54, v55, s[0:1]
	v_mul_f32_e32 v54, 0x37800000, v53
	v_cndmask_b32_e32 v53, v53, v54, vcc
	v_cmp_class_f32_e32 vcc, v52, v191
	s_nop 1
	v_cndmask_b32_e32 v52, v53, v52, vcc
	v_div_scale_f32 v53, s[0:1], v52, v52, 1.0
	v_rcp_f32_e32 v54, v53
	s_nop 0
	v_fma_f32 v55, -v53, v54, 1.0
	v_fmac_f32_e32 v54, v55, v54
	v_div_scale_f32 v55, vcc, 1.0, v52, 1.0
	v_mul_f32_e32 v56, v55, v54
	v_fma_f32 v57, -v53, v56, v55
	v_fmac_f32_e32 v56, v57, v54
	v_fma_f32 v53, -v53, v56, v55
	v_div_fmas_f32 v53, v53, v54, v56
	v_div_fixup_f32 v52, v53, v52, 1.0
	v_pk_mul_f32 v[46:47], v[46:47], v[52:53] op_sel_hi:[1,0]
	v_pk_mul_f32 v[42:43], v[42:43], v[52:53] op_sel_hi:[1,0]
	v_pk_mul_f32 v[48:49], v[48:49], v[52:53] op_sel_hi:[1,0]
	v_pk_mul_f32 v[44:45], v[44:45], v[52:53] op_sel_hi:[1,0]
	v_max_f32_e32 v46, 0, v46
	v_max_f32_e32 v42, 0, v42
	v_max_f32_e32 v47, 0, v47
	v_max_f32_e32 v43, 0, v43
	v_pk_mul_f32 v[46:47], v[46:47], v[46:47]
	v_pk_mul_f32 v[54:55], v[42:43], v[42:43]
	v_max_f32_e32 v42, 0, v48
	v_max_f32_e32 v44, 0, v44
	v_max_f32_e32 v43, 0, v49
	v_max_f32_e32 v45, 0, v45
	v_pk_mul_f32 v[48:49], v[42:43], v[42:43]
	v_pk_mul_f32 v[56:57], v[44:45], v[44:45]
	v_cvt_pk_bf16_f32 v42, v46, v47
	v_lshl_add_u64 v[46:47], s[92:93], 0, v[50:51]
	v_pk_mul_f32 v[34:35], v[34:35], v[52:53] op_sel_hi:[1,0]
	v_cvt_pk_bf16_f32 v43, v48, v49
	v_cvt_pk_bf16_f32 v44, v54, v55
	v_cvt_pk_bf16_f32 v45, v56, v57
	v_lshl_add_u64 v[46:47], v[46:47], 0, v[122:123]
	v_pk_mul_f32 v[40:41], v[40:41], v[52:53] op_sel_hi:[1,0]
	v_pk_mul_f32 v[38:39], v[38:39], v[52:53] op_sel_hi:[1,0]
	v_pk_mul_f32 v[36:37], v[36:37], v[52:53] op_sel_hi:[1,0]
	v_max_f32_e32 v34, 0, v34
	v_max_f32_e32 v35, 0, v35
	global_store_dwordx4 v[46:47], v[42:45], off
	v_max_f32_e32 v38, 0, v38
	v_max_f32_e32 v39, 0, v39
	v_pk_mul_f32 v[42:43], v[34:35], v[34:35]
	v_max_f32_e32 v34, 0, v40
	v_max_f32_e32 v36, 0, v36
	v_max_f32_e32 v35, 0, v41
	v_max_f32_e32 v37, 0, v37
	v_pk_mul_f32 v[38:39], v[38:39], v[38:39]
	v_pk_mul_f32 v[40:41], v[34:35], v[34:35]
	v_pk_mul_f32 v[44:45], v[36:37], v[36:37]
	v_cvt_pk_bf16_f32 v34, v38, v39
	v_cvt_pk_bf16_f32 v35, v40, v41
	v_cvt_pk_bf16_f32 v36, v42, v43
	v_cvt_pk_bf16_f32 v37, v44, v45
	global_store_dwordx4 v[46:47], v[34:37], off offset:256
	s_nop 1
	v_add_u32_e32 v34, 0xa0, v158
	v_ashrrev_i32_e32 v35, 31, v34
	v_lshlrev_b64 v[36:37], 7, v[34:35]
	v_lshl_add_u64 v[36:37], v[152:153], 0, v[36:37]
	global_load_dwordx4 v[38:41], v[36:37], off
	global_load_dwordx4 v[42:45], v[36:37], off offset:16
	v_lshlrev_b64 v[34:35], 14, v[34:35]
	s_waitcnt vmcnt(1)
	v_mov_b32_e32 v36, v38
	s_waitcnt vmcnt(0)
	v_mov_b32_e32 v37, v42
	v_mov_b32_e32 v42, v39
	v_mov_b32_e32 v38, v40
	v_mov_b32_e32 v39, v44
	v_mov_b32_e32 v44, v41
	v_pk_add_f32 v[36:37], v[36:37], v[42:43]
	v_pk_add_f32 v[38:39], v[38:39], v[44:45]
	s_nop 0
	v_pk_add_f32 v[36:37], v[36:37], v[38:39]
	s_nop 0
	v_add_f32_e32 v36, v36, v37
	ds_bpermute_b32 v37, v162, v36
	s_waitcnt lgkmcnt(0)
	v_add_f32_e32 v36, v36, v37
	ds_bpermute_b32 v37, v163, v36
	s_waitcnt lgkmcnt(0)
; __device__ __forceinline__ unsigned cvt_pk_bf16(float lo, float hi) { const f32x2c_t v = {lo, hi}; const bf16x2c_t b = __builtin_convertvector(v, bf16x2c_t); return __builtin_bit_cast(unsigned, b); }
; #define PG8_BAR __builtin_amdgcn_s_barrier()
;     __device__ __forceinline__ void operator()(const f32x4 (&acc)[2][2][4][2], const Unit& u, int wr, int wc, int fr, int fq) const {
;     ...
;         for (int ai = 0; ai < 2; ++ai)
; #pragma unroll
;             for (int m = 0; m < 4; ++m) { const size_t row = (size_t)(row0 + ai * HALF + m * 16);
;                 const f32x4* sp = (const f32x4*)(SS + row * 32) + 2 * fq; float s;
;                 { const f32x4 t0 = sp[0], t1 = sp[1]; s = ((t0[0] + t0[1]) + (t0[2] + t0[3])) + ((t1[0] + t1[1]) + (t1[2] + t1[3])); }
;                 s += __shfl_xor(s, 16); s += __shfl_xor(s, 32);
;                 const float rstd = 1.0f / sqrtf(s * (1.0f / DM) + NORM_EPS);
; #pragma unroll
;                 for (int bj = 0; bj < 2; ++bj) { f32x4 v0 = acc[ai][bj][m][0] * rstd, v1 = acc[ai][bj][m][1] * rstd;
; #pragma unroll
;                     for (int e = 0; e < 4; ++e) { const float a = fmaxf(v0[e], 0.f), b = fmaxf(v1[e], 0.f); v0[e] = a * a; v1[e] = b * b; }
;                     u32x4 w; w.x = cvt_pk_bf16(v0[0], v0[1]); w.y = cvt_pk_bf16(v0[2], v0[3]); w.z = cvt_pk_bf16(v1[0], v1[1]); w.w = cvt_pk_bf16(v1[2], v1[3]);
;                     *(u32x4*)(H + row * DFF + col0 + bj * HALF) = w; } }
; template <class Epi, class Sched, bool ALIGN_EPI = false, bool SP2 = false>
; __device__ __forceinline__ void gemm_phase(PG8_LAS unsigned char* lds, const Gemm g, const Sched& S, const Epi& E) {
;     ...
;         if (!has_next) break;
; #pragma unroll
;         for (int a = 0; a < 2; ++a)
; #pragma unroll
;             for (int b = 0; b < 2; ++b)
; #pragma unroll
;                 for (int m = 0; m < 4; ++m)
; #pragma unroll
;                     for (int n = 0; n < 2; ++n) acc[a][b][m][n] = (f32x4){0.f, 0.f, 0.f, 0.f};
;         cur = nxt; cA = nA; cB = nB; ++ui;
;         if constexpr (ALIGN_EPI) { if (wr == 1) PG8_BAR; }
	v_add_f32_e32 v36, v36, v37
	v_fmamk_f32 v36, v36, 0x3a000000, v190
	v_cmp_gt_f32_e32 vcc, s72, v36
	v_mul_f32_e32 v37, 0x4f800000, v36
	s_nop 0
	v_cndmask_b32_e32 v36, v36, v37, vcc
	v_sqrt_f32_e32 v37, v36
	s_nop 0
	v_add_u32_e32 v38, -1, v37
	v_fma_f32 v39, -v38, v37, v36
	v_cmp_ge_f32_e64 s[0:1], 0, v39
	v_add_u32_e32 v39, 1, v37
	s_nop 0
	v_cndmask_b32_e64 v38, v37, v38, s[0:1]
	v_fma_f32 v37, -v39, v37, v36
	v_cmp_lt_f32_e64 s[0:1], 0, v37
	s_nop 1
	v_cndmask_b32_e64 v37, v38, v39, s[0:1]
	v_mul_f32_e32 v38, 0x37800000, v37
	v_cndmask_b32_e32 v37, v37, v38, vcc
	v_cmp_class_f32_e32 vcc, v36, v191
	s_nop 1
	v_cndmask_b32_e32 v36, v37, v36, vcc
	v_div_scale_f32 v37, s[0:1], v36, v36, 1.0
	v_rcp_f32_e32 v38, v37
	s_nop 0
	v_fma_f32 v39, -v37, v38, 1.0
	v_fmac_f32_e32 v38, v39, v38
	v_div_scale_f32 v39, vcc, 1.0, v36, 1.0
	v_mul_f32_e32 v40, v39, v38
	v_fma_f32 v41, -v37, v40, v39
	v_fmac_f32_e32 v40, v41, v38
	v_fma_f32 v37, -v37, v40, v39
	v_div_fmas_f32 v37, v37, v38, v40
	v_div_fixup_f32 v36, v37, v36, 1.0
	v_pk_mul_f32 v[30:31], v[30:31], v[36:37] op_sel_hi:[1,0]
	v_pk_mul_f32 v[26:27], v[26:27], v[36:37] op_sel_hi:[1,0]
	v_pk_mul_f32 v[32:33], v[32:33], v[36:37] op_sel_hi:[1,0]
	v_pk_mul_f32 v[28:29], v[28:29], v[36:37] op_sel_hi:[1,0]
	v_max_f32_e32 v30, 0, v30
	v_max_f32_e32 v26, 0, v26
	v_max_f32_e32 v31, 0, v31
	v_max_f32_e32 v27, 0, v27
	v_pk_mul_f32 v[30:31], v[30:31], v[30:31]
	v_pk_mul_f32 v[38:39], v[26:27], v[26:27]
	v_max_f32_e32 v26, 0, v32
	v_max_f32_e32 v28, 0, v28
	v_max_f32_e32 v27, 0, v33
	v_max_f32_e32 v29, 0, v29
	v_pk_mul_f32 v[32:33], v[26:27], v[26:27]
	v_pk_mul_f32 v[40:41], v[28:29], v[28:29]
	v_cvt_pk_bf16_f32 v26, v30, v31
	v_lshl_add_u64 v[30:31], s[92:93], 0, v[34:35]
	v_pk_mul_f32 v[18:19], v[18:19], v[36:37] op_sel_hi:[1,0]
	v_cvt_pk_bf16_f32 v27, v32, v33
	v_cvt_pk_bf16_f32 v28, v38, v39
	v_cvt_pk_bf16_f32 v29, v40, v41
	v_lshl_add_u64 v[30:31], v[30:31], 0, v[122:123]
	v_pk_mul_f32 v[24:25], v[24:25], v[36:37] op_sel_hi:[1,0]
	v_pk_mul_f32 v[22:23], v[22:23], v[36:37] op_sel_hi:[1,0]
	v_pk_mul_f32 v[20:21], v[20:21], v[36:37] op_sel_hi:[1,0]
	v_max_f32_e32 v18, 0, v18
	v_max_f32_e32 v19, 0, v19
	global_store_dwordx4 v[30:31], v[26:29], off
	v_max_f32_e32 v22, 0, v22
	v_max_f32_e32 v23, 0, v23
	v_pk_mul_f32 v[26:27], v[18:19], v[18:19]
	v_max_f32_e32 v18, 0, v24
	v_max_f32_e32 v20, 0, v20
	v_max_f32_e32 v19, 0, v25
	v_max_f32_e32 v21, 0, v21
	v_pk_mul_f32 v[22:23], v[22:23], v[22:23]
	v_pk_mul_f32 v[24:25], v[18:19], v[18:19]
	v_pk_mul_f32 v[28:29], v[20:21], v[20:21]
	v_cvt_pk_bf16_f32 v18, v22, v23
	v_cvt_pk_bf16_f32 v19, v24, v25
	v_cvt_pk_bf16_f32 v20, v26, v27
	v_cvt_pk_bf16_f32 v21, v28, v29
	global_store_dwordx4 v[30:31], v[18:21], off offset:256
	s_nop 1
	v_add_u32_e32 v18, 0xb0, v158
	v_ashrrev_i32_e32 v19, 31, v18
	v_lshlrev_b64 v[20:21], 7, v[18:19]
	v_lshl_add_u64 v[20:21], v[152:153], 0, v[20:21]
	global_load_dwordx4 v[22:25], v[20:21], off
	global_load_dwordx4 v[26:29], v[20:21], off offset:16
	v_lshlrev_b64 v[18:19], 14, v[18:19]
	s_waitcnt vmcnt(1)
	v_mov_b32_e32 v20, v22
	s_waitcnt vmcnt(0)
	v_mov_b32_e32 v21, v26
	v_mov_b32_e32 v26, v23
	v_mov_b32_e32 v22, v24
	v_mov_b32_e32 v23, v28
	v_mov_b32_e32 v28, v25
	v_pk_add_f32 v[20:21], v[20:21], v[26:27]
	v_pk_add_f32 v[22:23], v[22:23], v[28:29]
	s_nop 0
	v_pk_add_f32 v[20:21], v[20:21], v[22:23]
	s_nop 0
	v_add_f32_e32 v20, v20, v21
	ds_bpermute_b32 v21, v162, v20
	s_waitcnt lgkmcnt(0)
	v_add_f32_e32 v20, v20, v21
	ds_bpermute_b32 v21, v163, v20
	s_waitcnt lgkmcnt(0)
	v_add_f32_e32 v20, v20, v21
	v_fmamk_f32 v20, v20, 0x3a000000, v190
	v_cmp_gt_f32_e32 vcc, s72, v20
	v_mul_f32_e32 v21, 0x4f800000, v20
	s_nop 0
	v_cndmask_b32_e32 v20, v20, v21, vcc
	v_sqrt_f32_e32 v21, v20
	s_nop 0
	v_add_u32_e32 v22, -1, v21
	v_fma_f32 v23, -v22, v21, v20
	v_cmp_ge_f32_e64 s[0:1], 0, v23
	v_add_u32_e32 v23, 1, v21
	s_nop 0
	v_cndmask_b32_e64 v22, v21, v22, s[0:1]
	v_fma_f32 v21, -v23, v21, v20
	v_cmp_lt_f32_e64 s[0:1], 0, v21
	s_nop 1
	v_cndmask_b32_e64 v21, v22, v23, s[0:1]
	v_mul_f32_e32 v22, 0x37800000, v21
	v_cndmask_b32_e32 v21, v21, v22, vcc
	v_cmp_class_f32_e32 vcc, v20, v191
	s_nop 1
	v_cndmask_b32_e32 v20, v21, v20, vcc
	v_div_scale_f32 v21, s[0:1], v20, v20, 1.0
	v_rcp_f32_e32 v22, v21
	s_mov_b64 s[0:1], -1
	v_fma_f32 v23, -v21, v22, 1.0
	v_fmac_f32_e32 v22, v23, v22
	v_div_scale_f32 v23, vcc, 1.0, v20, 1.0
	v_mul_f32_e32 v24, v23, v22
	v_fma_f32 v25, -v21, v24, v23
	v_fmac_f32_e32 v24, v25, v22
	v_fma_f32 v21, -v21, v24, v23
	v_div_fmas_f32 v21, v21, v22, v24
	v_div_fixup_f32 v20, v21, v20, 1.0
	v_pk_mul_f32 v[14:15], v[14:15], v[20:21] op_sel_hi:[1,0]
	v_pk_mul_f32 v[10:11], v[10:11], v[20:21] op_sel_hi:[1,0]
	v_pk_mul_f32 v[16:17], v[16:17], v[20:21] op_sel_hi:[1,0]
	v_pk_mul_f32 v[12:13], v[12:13], v[20:21] op_sel_hi:[1,0]
	v_max_f32_e32 v14, 0, v14
	v_max_f32_e32 v10, 0, v10
	v_max_f32_e32 v15, 0, v15
	v_max_f32_e32 v11, 0, v11
	v_pk_mul_f32 v[14:15], v[14:15], v[14:15]
	v_pk_mul_f32 v[22:23], v[10:11], v[10:11]
	v_max_f32_e32 v10, 0, v16
	v_max_f32_e32 v12, 0, v12
	v_max_f32_e32 v11, 0, v17
	v_max_f32_e32 v13, 0, v13
	v_pk_mul_f32 v[16:17], v[10:11], v[10:11]
	v_pk_mul_f32 v[24:25], v[12:13], v[12:13]
	v_cvt_pk_bf16_f32 v10, v14, v15
	v_lshl_add_u64 v[14:15], s[92:93], 0, v[18:19]
	v_pk_mul_f32 v[2:3], v[2:3], v[20:21] op_sel_hi:[1,0]
	v_cvt_pk_bf16_f32 v11, v16, v17
	v_cvt_pk_bf16_f32 v12, v22, v23
	v_cvt_pk_bf16_f32 v13, v24, v25
	v_lshl_add_u64 v[14:15], v[14:15], 0, v[122:123]
	v_pk_mul_f32 v[8:9], v[8:9], v[20:21] op_sel_hi:[1,0]
	v_pk_mul_f32 v[6:7], v[6:7], v[20:21] op_sel_hi:[1,0]
	v_pk_mul_f32 v[4:5], v[4:5], v[20:21] op_sel_hi:[1,0]
	v_max_f32_e32 v2, 0, v2
	v_max_f32_e32 v3, 0, v3
	global_store_dwordx4 v[14:15], v[10:13], off
	v_max_f32_e32 v6, 0, v6
	v_max_f32_e32 v7, 0, v7
	v_pk_mul_f32 v[10:11], v[2:3], v[2:3]
	v_max_f32_e32 v2, 0, v8
	v_max_f32_e32 v4, 0, v4
	v_max_f32_e32 v3, 0, v9
	v_max_f32_e32 v5, 0, v5
	v_pk_mul_f32 v[6:7], v[6:7], v[6:7]
	v_pk_mul_f32 v[8:9], v[2:3], v[2:3]
	v_pk_mul_f32 v[12:13], v[4:5], v[4:5]
	v_cvt_pk_bf16_f32 v2, v6, v7
	v_cvt_pk_bf16_f32 v3, v8, v9
	v_cvt_pk_bf16_f32 v4, v10, v11
	v_cvt_pk_bf16_f32 v5, v12, v13
	s_andn2_b64 vcc, exec, s[40:41]
	global_store_dwordx4 v[14:15], v[2:5], off offset:256
	s_cbranch_vccnz .LBB0_68
	s_andn2_b64 vcc, exec, s[12:13]
	s_cbranch_vccnz .LBB0_67
	s_barrier
	s_branch .LBB0_67

; #define PG8_STAGE(bufoff, gbase, voff) do { _Pragma("unroll") for (int _i = 0; _i < 2; ++_i) \
;         __builtin_amdgcn_global_load_lds((const unsigned*)((const char*)(gbase) + (voff)[_i]), (PG8_LAS unsigned*)(lds + (bufoff) + ldsw + _i * 8192), 16, 0, 0); } while (0)
; #define PG8_LDA(dst, b, h) do { _Pragma("unroll") for (int m = 0; m < 4; ++m) _Pragma("unroll") for (int k = 0; k < 2; ++k) dst[m][k] = *(const PG8_LAS bf16x8*)(lds + PG8_SA(b, h) + aoff + m * 2048 + k * 1024); } while (0)
; #define PG8_LDB(dst, b, h) do { _Pragma("unroll") for (int n = 0; n < 2; ++n) _Pragma("unroll") for (int k = 0; k < 2; ++k) dst[n][k] = *(const PG8_LAS bf16x8*)(lds + PG8_SB(b, h) + boff + n * 2048 + k * 1024); } while (0)
; #define PG8_MMA(ai, bj, At, Bt) do { __builtin_amdgcn_s_setprio(1); _Pragma("unroll") for (int m = 0; m < 4; ++m) _Pragma("unroll") for (int n = 0; n < 2; ++n) _Pragma("unroll") for (int k = 0; k < 2; ++k) \
;         acc[ai][bj][m][n] = __builtin_amdgcn_mfma_f32_16x16x32_bf16(Bt[n][k], At[m][k], acc[ai][bj][m][n], 0, 0, 0); __builtin_amdgcn_s_setprio(0); } while (0)
; #define PG8_WAIT_V(n) asm volatile("s_waitcnt vmcnt(" #n ")" ::: "memory")
; #define PG8_WAIT_L(n) asm volatile("s_waitcnt lgkmcnt(" #n ")" ::: "memory")
; #define PG8_BAR __builtin_amdgcn_s_barrier()
; #define PG8_SCHED __builtin_amdgcn_sched_barrier(0)
; template <class Epi, class Sched, bool ALIGN_EPI = false, bool SP2 = false>
; __device__ __forceinline__ void gemm_phase(PG8_LAS unsigned char* lds, const Gemm g, const Sched& S, const Epi& E) {
;     ...
;             PG8_LDB(B0, 0, 0); PG8_LDB(B1, 0, 1); PG8_SCHED; PG8_LDA(At, 0, 0); PG8_STAGE(PG8_SA(1, 1), a1 + hstep, voffA);
;             PG8_WAIT_V(8); PG8_WAIT_L(0); PG8_BAR; PG8_MMA(0, 0, At, B0); PG8_MMA(0, 1, At, B1); PG8_BAR; PG8_SCHED;
;             PG8_LDA(At, 0, 1); PG8_STAGE(PG8_SB(0, 0), b2, voffB); PG8_STAGE(PG8_SB(0, 1), b2 + hstep, voffB); PG8_STAGE(PG8_SA(0, 0), a2, voffA);
;             PG8_WAIT_V(8); PG8_WAIT_L(0); PG8_BAR; PG8_MMA(1, 0, At, B0); PG8_MMA(1, 1, At, B1); PG8_BAR; PG8_SCHED;
.Lpw5_j:
	s_nop 0
	s_nop 0
	s_waitcnt lgkmcnt(0)
	s_setprio 1
	s_barrier
	v_mfma_f32_16x16x32_bf16 v[126:129], v[156:159], v[208:211], 0
	v_mfma_f32_16x16x32_bf16 v[122:125], v[166:169], v[208:211], 0
	v_mfma_f32_16x16x32_bf16 v[110:113], v[156:159], v[216:219], 0
	v_mfma_f32_16x16x32_bf16 v[106:109], v[166:169], v[216:219], 0
	v_mfma_f32_16x16x32_bf16 v[94:97], v[156:159], v[224:227], 0
	v_mfma_f32_16x16x32_bf16 v[90:93], v[166:169], v[224:227], 0
	v_mfma_f32_16x16x32_bf16 v[78:81], v[156:159], v[232:235], 0
	v_mfma_f32_16x16x32_bf16 v[74:77], v[166:169], v[232:235], 0
	s_setprio 0
	s_setprio 1
	v_mfma_f32_16x16x32_bf16 v[126:129], v[162:165], v[212:215], v[126:129]
	v_mfma_f32_16x16x32_bf16 v[122:125], v[170:173], v[212:215], v[122:125]
	v_mfma_f32_16x16x32_bf16 v[110:113], v[162:165], v[220:223], v[110:113]
	v_mfma_f32_16x16x32_bf16 v[106:109], v[170:173], v[220:223], v[106:109]
	v_mfma_f32_16x16x32_bf16 v[94:97], v[162:165], v[228:231], v[94:97]
	v_mfma_f32_16x16x32_bf16 v[90:93], v[170:173], v[228:231], v[90:93]
	v_mfma_f32_16x16x32_bf16 v[78:81], v[162:165], v[236:239], v[78:81]
	v_mfma_f32_16x16x32_bf16 v[74:77], v[170:173], v[236:239], v[74:77]
	s_setprio 0
	s_setprio 1
	v_mfma_f32_16x16x32_bf16 v[118:121], v[174:177], v[208:211], 0
	v_mfma_f32_16x16x32_bf16 v[114:117], v[182:185], v[208:211], 0
	v_mfma_f32_16x16x32_bf16 v[102:105], v[174:177], v[216:219], 0
	v_mfma_f32_16x16x32_bf16 v[98:101], v[182:185], v[216:219], 0
	v_mfma_f32_16x16x32_bf16 v[86:89], v[174:177], v[224:227], 0
	v_mfma_f32_16x16x32_bf16 v[82:85], v[182:185], v[224:227], 0
	v_mfma_f32_16x16x32_bf16 v[70:73], v[174:177], v[232:235], 0
	v_mfma_f32_16x16x32_bf16 v[66:69], v[182:185], v[232:235], 0
	s_setprio 0
	s_setprio 1
	v_mfma_f32_16x16x32_bf16 v[118:121], v[178:181], v[212:215], v[118:121]
	v_mfma_f32_16x16x32_bf16 v[114:117], v[204:207], v[212:215], v[114:117]
	v_mfma_f32_16x16x32_bf16 v[102:105], v[178:181], v[220:223], v[102:105]
	v_mfma_f32_16x16x32_bf16 v[98:101], v[204:207], v[220:223], v[98:101]
	v_mfma_f32_16x16x32_bf16 v[86:89], v[178:181], v[228:231], v[86:89]
	v_mfma_f32_16x16x32_bf16 v[82:85], v[204:207], v[228:231], v[82:85]
	v_mfma_f32_16x16x32_bf16 v[70:73], v[178:181], v[236:239], v[70:73]
	v_mfma_f32_16x16x32_bf16 v[66:69], v[204:207], v[236:239], v[66:69]
	s_setprio 0
	s_barrier
	s_add_i32 s47, s47, s4
	v_lshl_add_u64 v[186:187], s[40:41], 0, v[148:149]
	s_mov_b32 m0, s47
	ds_read_b128 v[208:211], v161 offset:16384
	ds_read_b128 v[212:215], v161 offset:17408
	ds_read_b128 v[216:219], v161 offset:18432
	ds_read_b128 v[220:223], v161 offset:19456
	ds_read_b128 v[224:227], v161 offset:20480
	ds_read_b128 v[228:231], v161 offset:21504
	ds_read_b128 v[232:235], v161 offset:22528
	ds_read_b128 v[236:239], v161 offset:23552
	global_load_lds_dwordx4 v[186:187], off
	s_add_i32 m0, s47, 0x2000
	s_add_u32 s76, s40, 0x80000
	v_lshl_add_u64 v[240:241], s[40:41], 0, v[144:145]
	s_addc_u32 s77, s41, 0
	s_add_i32 s47, s80, s4
	global_load_lds_dwordx4 v[240:241], off
	v_lshl_add_u64 v[242:243], s[76:77], 0, v[148:149]
	s_mov_b32 m0, s47
	v_lshl_add_u64 v[244:245], s[58:59], 0, v[146:147]
	global_load_lds_dwordx4 v[242:243], off
	v_lshl_add_u64 v[242:243], s[76:77], 0, v[144:145]
	s_add_i32 m0, s47, 0x2000
	s_nop 0
	global_load_lds_dwordx4 v[242:243], off
	v_lshl_add_u64 v[242:243], s[58:59], 0, v[150:151]
	s_mov_b32 m0, s5
	s_nop 0
	global_load_lds_dwordx4 v[242:243], off
	s_mov_b32 m0, s30
	s_nop 0
	global_load_lds_dwordx4 v[244:245], off
	s_cmp_eq_u32 s32, 0
	s_cbranch_scc1 .Lpw6_f
	s_waitcnt vmcnt(24)
	s_branch .Lpw6_j

; #define PG8_STAGE(bufoff, gbase, voff) do { _Pragma("unroll") for (int _i = 0; _i < 2; ++_i) \
;         __builtin_amdgcn_global_load_lds((const unsigned*)((const char*)(gbase) + (voff)[_i]), (PG8_LAS unsigned*)(lds + (bufoff) + ldsw + _i * 8192), 16, 0, 0); } while (0)
; #define PG8_LDA(dst, b, h) do { _Pragma("unroll") for (int m = 0; m < 4; ++m) _Pragma("unroll") for (int k = 0; k < 2; ++k) dst[m][k] = *(const PG8_LAS bf16x8*)(lds + PG8_SA(b, h) + aoff + m * 2048 + k * 1024); } while (0)
; #define PG8_LDB(dst, b, h) do { _Pragma("unroll") for (int n = 0; n < 2; ++n) _Pragma("unroll") for (int k = 0; k < 2; ++k) dst[n][k] = *(const PG8_LAS bf16x8*)(lds + PG8_SB(b, h) + boff + n * 2048 + k * 1024); } while (0)
; #define PG8_MMA(ai, bj, At, Bt) do { __builtin_amdgcn_s_setprio(1); _Pragma("unroll") for (int m = 0; m < 4; ++m) _Pragma("unroll") for (int n = 0; n < 2; ++n) _Pragma("unroll") for (int k = 0; k < 2; ++k) \
;         acc[ai][bj][m][n] = __builtin_amdgcn_mfma_f32_16x16x32_bf16(Bt[n][k], At[m][k], acc[ai][bj][m][n], 0, 0, 0); __builtin_amdgcn_s_setprio(0); } while (0)
; #define PG8_WAIT_V(n) asm volatile("s_waitcnt vmcnt(" #n ")" ::: "memory")
; template <class Epi, class Sched, bool ALIGN_EPI = false, bool SP2 = false>
; __device__ __forceinline__ void gemm_phase(PG8_LAS unsigned char* lds, const Gemm g, const Sched& S, const Epi& E) {
;     ...
;             PG8_LDB(B0, 0, 0); PG8_LDB(B1, 0, 1); PG8_SCHED; PG8_LDA(At, 0, 0); PG8_STAGE(PG8_SA(1, 1), a1 + hstep, voffA);
;             PG8_WAIT_V(8); PG8_WAIT_L(0); PG8_BAR; PG8_MMA(0, 0, At, B0); PG8_MMA(0, 1, At, B1); PG8_BAR; PG8_SCHED;
;             PG8_LDA(At, 0, 1); PG8_STAGE(PG8_SB(0, 0), b2, voffB); PG8_STAGE(PG8_SB(0, 1), b2 + hstep, voffB); PG8_STAGE(PG8_SA(0, 0), a2, voffA);
;             PG8_WAIT_V(8); PG8_WAIT_L(0); PG8_BAR; PG8_MMA(1, 0, At, B0); PG8_MMA(1, 1, At, B1); PG8_BAR; PG8_SCHED;
;             PG8_LDB(B0, 1, 0); PG8_LDB(B1, 1, 1); PG8_SCHED; PG8_LDA(At, 1, 0); PG8_STAGE(PG8_SA(0, 1), a2 + hstep, voffA);
;             PG8_WAIT_V(8); PG8_WAIT_L(0); PG8_BAR; PG8_MMA(0, 0, At, B0); PG8_MMA(0, 1, At, B1); PG8_BAR; PG8_SCHED;
;             PG8_LDA(At, 1, 1); PG8_STAGE(PG8_SB(1, 0), b3, voffB); PG8_STAGE(PG8_SB(1, 1), b3 + hstep, voffB); PG8_STAGE(PG8_SA(1, 0), a3, voffA);
;             PG8_WAIT_V(8); PG8_WAIT_L(0); PG8_BAR; PG8_MMA(1, 0, At, B0); PG8_MMA(1, 1, At, B1); PG8_BAR; PG8_SCHED;
.LBB0_160:
	s_add_u32 s42, s36, 0x100
	s_addc_u32 s43, s37, 0
	s_add_i32 s47, 0, 0x10000
	s_cmp_eq_u32 s46, 20
	s_cselect_b32 s45, s1, s43
	s_cselect_b32 s44, s0, s42
	s_cselect_b32 s19, s7, s73
	s_cselect_b32 s18, s6, s60
	s_add_i32 s76, 0, 0x14000
	v_add_u32_e32 v174, s47, v143
	v_add_u32_e32 v186, s76, v143
	ds_read_b128 v[160:163], v174
	ds_read_b128 v[164:167], v174 offset:1024
	ds_read_b128 v[170:173], v174 offset:2048
	ds_read_b128 v[174:177], v174 offset:3072
	ds_read_b128 v[178:181], v186
	ds_read_b128 v[182:185], v186 offset:1024
	ds_read_b128 v[204:207], v186 offset:2048
	ds_read_b128 v[208:211], v186 offset:3072
	v_lshl_add_u64 v[186:187], s[36:37], 0, v[156:157]
	s_add_i32 m0, s54, 0xc000
	ds_read_b128 v[212:215], v169
	ds_read_b128 v[216:219], v169 offset:1024
	ds_read_b128 v[220:223], v169 offset:2048
	ds_read_b128 v[224:227], v169 offset:3072
	ds_read_b128 v[228:231], v169 offset:4096
	ds_read_b128 v[232:235], v169 offset:5120
	ds_read_b128 v[236:239], v169 offset:6144
	ds_read_b128 v[240:243], v169 offset:7168
	global_load_lds_dwordx4 v[186:187], off
	v_lshl_add_u64 v[186:187], s[36:37], 0, v[158:159]
	s_add_i32 m0, s54, 0xe000
	s_nop 0
	global_load_lds_dwordx4 v[186:187], off
	s_nop 0
	s_waitcnt vmcnt(8)
	s_waitcnt lgkmcnt(0)
	s_setprio 1
	s_barrier
	v_mfma_f32_16x16x32_bf16 v[126:129], v[160:163], v[212:215], v[126:129]
	v_mfma_f32_16x16x32_bf16 v[122:125], v[170:173], v[212:215], v[122:125]
	v_mfma_f32_16x16x32_bf16 v[110:113], v[160:163], v[220:223], v[110:113]
	v_mfma_f32_16x16x32_bf16 v[106:109], v[170:173], v[220:223], v[106:109]
	v_mfma_f32_16x16x32_bf16 v[94:97], v[160:163], v[228:231], v[94:97]
	v_mfma_f32_16x16x32_bf16 v[90:93], v[170:173], v[228:231], v[90:93]
	v_mfma_f32_16x16x32_bf16 v[78:81], v[160:163], v[236:239], v[78:81]
	v_mfma_f32_16x16x32_bf16 v[74:77], v[170:173], v[236:239], v[74:77]
	s_setprio 0
	s_setprio 1
	v_mfma_f32_16x16x32_bf16 v[126:129], v[164:167], v[216:219], v[126:129]
	v_mfma_f32_16x16x32_bf16 v[122:125], v[174:177], v[216:219], v[122:125]
	v_mfma_f32_16x16x32_bf16 v[110:113], v[164:167], v[224:227], v[110:113]
	v_mfma_f32_16x16x32_bf16 v[106:109], v[174:177], v[224:227], v[106:109]
	v_mfma_f32_16x16x32_bf16 v[94:97], v[164:167], v[232:235], v[94:97]
	v_mfma_f32_16x16x32_bf16 v[90:93], v[174:177], v[232:235], v[90:93]
	v_mfma_f32_16x16x32_bf16 v[78:81], v[164:167], v[240:243], v[78:81]
	v_mfma_f32_16x16x32_bf16 v[74:77], v[174:177], v[240:243], v[74:77]
	s_setprio 0
	s_setprio 1
	v_mfma_f32_16x16x32_bf16 v[118:121], v[178:181], v[212:215], v[118:121]
	v_mfma_f32_16x16x32_bf16 v[114:117], v[204:207], v[212:215], v[114:117]
	v_mfma_f32_16x16x32_bf16 v[102:105], v[178:181], v[220:223], v[102:105]
	v_mfma_f32_16x16x32_bf16 v[98:101], v[204:207], v[220:223], v[98:101]
	v_mfma_f32_16x16x32_bf16 v[86:89], v[178:181], v[228:231], v[86:89]
	v_mfma_f32_16x16x32_bf16 v[82:85], v[204:207], v[228:231], v[82:85]
	v_mfma_f32_16x16x32_bf16 v[70:73], v[178:181], v[236:239], v[70:73]
	v_mfma_f32_16x16x32_bf16 v[66:69], v[204:207], v[236:239], v[66:69]
	s_setprio 0
	s_setprio 1
	v_mfma_f32_16x16x32_bf16 v[118:121], v[182:185], v[216:219], v[118:121]
	v_mfma_f32_16x16x32_bf16 v[114:117], v[208:211], v[216:219], v[114:117]
	v_mfma_f32_16x16x32_bf16 v[102:105], v[182:185], v[224:227], v[102:105]
	v_mfma_f32_16x16x32_bf16 v[98:101], v[208:211], v[224:227], v[98:101]
	v_mfma_f32_16x16x32_bf16 v[86:89], v[182:185], v[232:235], v[86:89]
	v_mfma_f32_16x16x32_bf16 v[82:85], v[208:211], v[232:235], v[82:85]
	v_mfma_f32_16x16x32_bf16 v[70:73], v[182:185], v[240:243], v[70:73]
	v_mfma_f32_16x16x32_bf16 v[66:69], v[208:211], v[240:243], v[66:69]
	s_setprio 0
	s_barrier
	s_add_i32 s36, s47, s4
	v_lshl_add_u64 v[186:187], s[18:19], 0, v[148:149]
	s_mov_b32 m0, s36
	ds_read_b128 v[212:215], v169 offset:16384
	ds_read_b128 v[216:219], v169 offset:17408
	ds_read_b128 v[220:223], v169 offset:18432
	ds_read_b128 v[224:227], v169 offset:19456
	ds_read_b128 v[228:231], v169 offset:20480
	ds_read_b128 v[232:235], v169 offset:21504
	ds_read_b128 v[236:239], v169 offset:22528
	ds_read_b128 v[240:243], v169 offset:23552
	global_load_lds_dwordx4 v[186:187], off
	s_add_i32 m0, s36, 0x2000
	s_add_u32 s36, s18, 0x60000
	v_lshl_add_u64 v[244:245], s[18:19], 0, v[144:145]
	s_addc_u32 s37, s19, 0
	s_add_i32 s47, s76, s4
	global_load_lds_dwordx4 v[244:245], off
	v_lshl_add_u64 v[246:247], s[36:37], 0, v[148:149]
	s_mov_b32 m0, s47
	v_lshl_add_u64 v[248:249], s[44:45], 0, v[146:147]
	global_load_lds_dwordx4 v[246:247], off
	v_lshl_add_u64 v[246:247], s[36:37], 0, v[144:145]
	s_add_i32 m0, s47, 0x2000
	s_nop 0
	global_load_lds_dwordx4 v[246:247], off
	v_lshl_add_u64 v[246:247], s[44:45], 0, v[150:151]
	s_mov_b32 m0, s54
	s_nop 0
	global_load_lds_dwordx4 v[246:247], off
	s_mov_b32 m0, s57
	s_nop 0
	global_load_lds_dwordx4 v[248:249], off
	s_waitcnt vmcnt(8)
	s_waitcnt lgkmcnt(0)
	s_setprio 1
	s_barrier
; #define PG8_STAGE(bufoff, gbase, voff) do { _Pragma("unroll") for (int _i = 0; _i < 2; ++_i) \
;         __builtin_amdgcn_global_load_lds((const unsigned*)((const char*)(gbase) + (voff)[_i]), (PG8_LAS unsigned*)(lds + (bufoff) + ldsw + _i * 8192), 16, 0, 0); } while (0)
; #define PG8_LDA(dst, b, h) do { _Pragma("unroll") for (int m = 0; m < 4; ++m) _Pragma("unroll") for (int k = 0; k < 2; ++k) dst[m][k] = *(const PG8_LAS bf16x8*)(lds + PG8_SA(b, h) + aoff + m * 2048 + k * 1024); } while (0)
; #define PG8_LDB(dst, b, h) do { _Pragma("unroll") for (int n = 0; n < 2; ++n) _Pragma("unroll") for (int k = 0; k < 2; ++k) dst[n][k] = *(const PG8_LAS bf16x8*)(lds + PG8_SB(b, h) + boff + n * 2048 + k * 1024); } while (0)
; #define PG8_MMA(ai, bj, At, Bt) do { __builtin_amdgcn_s_setprio(1); _Pragma("unroll") for (int m = 0; m < 4; ++m) _Pragma("unroll") for (int n = 0; n < 2; ++n) _Pragma("unroll") for (int k = 0; k < 2; ++k) \
;         acc[ai][bj][m][n] = __builtin_amdgcn_mfma_f32_16x16x32_bf16(Bt[n][k], At[m][k], acc[ai][bj][m][n], 0, 0, 0); __builtin_amdgcn_s_setprio(0); } while (0)
; #define PG8_WAIT_V(n) asm volatile("s_waitcnt vmcnt(" #n ")" ::: "memory")
; template <class Epi, class Sched, bool ALIGN_EPI = false, bool SP2 = false>
; __device__ __forceinline__ void gemm_phase(PG8_LAS unsigned char* lds, const Gemm g, const Sched& S, const Epi& E) {
;     ...
;             PG8_LDB(B0, 0, 0); PG8_LDB(B1, 0, 1); PG8_SCHED; PG8_LDA(At, 0, 0); PG8_STAGE(PG8_SA(1, 1), a1 + hstep, voffA);
;             PG8_WAIT_V(8); PG8_WAIT_L(0); PG8_BAR; PG8_MMA(0, 0, At, B0); PG8_MMA(0, 1, At, B1); PG8_BAR; PG8_SCHED;
;             PG8_LDA(At, 0, 1); PG8_STAGE(PG8_SB(0, 0), b2, voffB); PG8_STAGE(PG8_SB(0, 1), b2 + hstep, voffB); PG8_STAGE(PG8_SA(0, 0), a2, voffA);
;             PG8_WAIT_V(8); PG8_WAIT_L(0); PG8_BAR; PG8_MMA(1, 0, At, B0); PG8_MMA(1, 1, At, B1); PG8_BAR; PG8_SCHED;
;             PG8_LDB(B0, 1, 0); PG8_LDB(B1, 1, 1); PG8_SCHED; PG8_LDA(At, 1, 0); PG8_STAGE(PG8_SA(0, 1), a2 + hstep, voffA);
;             PG8_WAIT_V(8); PG8_WAIT_L(0); PG8_BAR; PG8_MMA(0, 0, At, B0); PG8_MMA(0, 1, At, B1); PG8_BAR; PG8_SCHED;
;             PG8_LDA(At, 1, 1); PG8_STAGE(PG8_SB(1, 0), b3, voffB); PG8_STAGE(PG8_SB(1, 1), b3 + hstep, voffB); PG8_STAGE(PG8_SA(1, 0), a3, voffA);
;             PG8_WAIT_V(8); PG8_WAIT_L(0); PG8_BAR; PG8_MMA(1, 0, At, B0); PG8_MMA(1, 1, At, B1); PG8_BAR; PG8_SCHED;
	v_mfma_f32_16x16x32_bf16 v[62:65], v[160:163], v[212:215], v[62:65]
	v_mfma_f32_16x16x32_bf16 v[58:61], v[170:173], v[212:215], v[58:61]
	v_mfma_f32_16x16x32_bf16 v[46:49], v[160:163], v[220:223], v[46:49]
	v_mfma_f32_16x16x32_bf16 v[42:45], v[170:173], v[220:223], v[42:45]
	v_mfma_f32_16x16x32_bf16 v[30:33], v[160:163], v[228:231], v[30:33]
	v_mfma_f32_16x16x32_bf16 v[26:29], v[170:173], v[228:231], v[26:29]
	v_mfma_f32_16x16x32_bf16 v[14:17], v[160:163], v[236:239], v[14:17]
	v_mfma_f32_16x16x32_bf16 v[10:13], v[170:173], v[236:239], v[10:13]
	v_mfma_f32_16x16x32_bf16 v[62:65], v[164:167], v[216:219], v[62:65]
	v_mfma_f32_16x16x32_bf16 v[58:61], v[174:177], v[216:219], v[58:61]
	v_mfma_f32_16x16x32_bf16 v[46:49], v[164:167], v[224:227], v[46:49]
	v_mfma_f32_16x16x32_bf16 v[42:45], v[174:177], v[224:227], v[42:45]
	v_mfma_f32_16x16x32_bf16 v[30:33], v[164:167], v[232:235], v[30:33]
	v_mfma_f32_16x16x32_bf16 v[26:29], v[174:177], v[232:235], v[26:29]
	v_mfma_f32_16x16x32_bf16 v[14:17], v[164:167], v[240:243], v[14:17]
	v_mfma_f32_16x16x32_bf16 v[10:13], v[174:177], v[240:243], v[10:13]
	v_mfma_f32_16x16x32_bf16 v[54:57], v[178:181], v[212:215], v[54:57]
	v_mfma_f32_16x16x32_bf16 v[50:53], v[204:207], v[212:215], v[50:53]
	v_mfma_f32_16x16x32_bf16 v[38:41], v[178:181], v[220:223], v[38:41]
	v_mfma_f32_16x16x32_bf16 v[34:37], v[204:207], v[220:223], v[34:37]
	v_mfma_f32_16x16x32_bf16 v[22:25], v[178:181], v[228:231], v[22:25]
	v_mfma_f32_16x16x32_bf16 v[18:21], v[204:207], v[228:231], v[18:21]
	v_mfma_f32_16x16x32_bf16 v[6:9], v[178:181], v[236:239], v[6:9]
	v_mfma_f32_16x16x32_bf16 v[2:5], v[204:207], v[236:239], v[2:5]
	v_mfma_f32_16x16x32_bf16 v[54:57], v[182:185], v[216:219], v[54:57]
	v_mfma_f32_16x16x32_bf16 v[50:53], v[208:211], v[216:219], v[50:53]
	v_mfma_f32_16x16x32_bf16 v[38:41], v[182:185], v[224:227], v[38:41]
	v_mfma_f32_16x16x32_bf16 v[34:37], v[208:211], v[224:227], v[34:37]
	v_mfma_f32_16x16x32_bf16 v[22:25], v[182:185], v[232:235], v[22:25]
	v_mfma_f32_16x16x32_bf16 v[18:21], v[208:211], v[232:235], v[18:21]
	v_mfma_f32_16x16x32_bf16 v[6:9], v[182:185], v[240:243], v[6:9]
	v_mfma_f32_16x16x32_bf16 v[2:5], v[208:211], v[240:243], v[2:5]
	s_setprio 0
	s_barrier
	s_add_i32 s47, 0, 0x18000
	s_add_i32 s76, 0, 0x1c000
	v_add_u32_e32 v174, s47, v143
	v_add_u32_e32 v203, s76, v143
	ds_read_b128 v[160:163], v174
	ds_read_b128 v[164:167], v174 offset:1024
	ds_read_b128 v[170:173], v174 offset:2048
	ds_read_b128 v[174:177], v174 offset:3072
	ds_read_b128 v[178:181], v203
	ds_read_b128 v[182:185], v203 offset:1024
	ds_read_b128 v[204:207], v203 offset:2048
	ds_read_b128 v[208:211], v203 offset:3072
	s_add_u32 s36, s44, 0x60000
	s_addc_u32 s37, s45, 0
	s_mov_b32 m0, s58
	v_lshl_add_u64 v[250:251], s[36:37], 0, v[150:151]
	ds_read_b128 v[212:215], v169 offset:32768
	ds_read_b128 v[216:219], v169 offset:33792
	ds_read_b128 v[220:223], v169 offset:34816
	ds_read_b128 v[224:227], v169 offset:35840
	ds_read_b128 v[228:231], v169 offset:36864
	ds_read_b128 v[232:235], v169 offset:37888
	ds_read_b128 v[236:239], v169 offset:38912
	ds_read_b128 v[240:243], v169 offset:39936
	global_load_lds_dwordx4 v[250:251], off
	v_lshl_add_u64 v[250:251], s[36:37], 0, v[146:147]
	s_mov_b32 m0, s59
	s_nop 0
	global_load_lds_dwordx4 v[250:251], off
	s_waitcnt vmcnt(8)
	s_waitcnt lgkmcnt(0)
	s_setprio 1
	s_barrier
	v_mfma_f32_16x16x32_bf16 v[126:129], v[160:163], v[212:215], v[126:129]
	v_mfma_f32_16x16x32_bf16 v[122:125], v[170:173], v[212:215], v[122:125]
	v_mfma_f32_16x16x32_bf16 v[110:113], v[160:163], v[220:223], v[110:113]
	v_mfma_f32_16x16x32_bf16 v[106:109], v[170:173], v[220:223], v[106:109]
	v_mfma_f32_16x16x32_bf16 v[94:97], v[160:163], v[228:231], v[94:97]
	v_mfma_f32_16x16x32_bf16 v[90:93], v[170:173], v[228:231], v[90:93]
	v_mfma_f32_16x16x32_bf16 v[78:81], v[160:163], v[236:239], v[78:81]
	v_mfma_f32_16x16x32_bf16 v[74:77], v[170:173], v[236:239], v[74:77]
	s_setprio 0
	s_setprio 1
	v_mfma_f32_16x16x32_bf16 v[126:129], v[164:167], v[216:219], v[126:129]
	v_mfma_f32_16x16x32_bf16 v[122:125], v[174:177], v[216:219], v[122:125]
	v_mfma_f32_16x16x32_bf16 v[110:113], v[164:167], v[224:227], v[110:113]
	v_mfma_f32_16x16x32_bf16 v[106:109], v[174:177], v[224:227], v[106:109]
	v_mfma_f32_16x16x32_bf16 v[94:97], v[164:167], v[232:235], v[94:97]
	v_mfma_f32_16x16x32_bf16 v[90:93], v[174:177], v[232:235], v[90:93]
	v_mfma_f32_16x16x32_bf16 v[78:81], v[164:167], v[240:243], v[78:81]
	v_mfma_f32_16x16x32_bf16 v[74:77], v[174:177], v[240:243], v[74:77]
	s_setprio 0
	s_setprio 1
	v_mfma_f32_16x16x32_bf16 v[118:121], v[178:181], v[212:215], v[118:121]
	v_mfma_f32_16x16x32_bf16 v[114:117], v[204:207], v[212:215], v[114:117]
	v_mfma_f32_16x16x32_bf16 v[102:105], v[178:181], v[220:223], v[102:105]
	v_mfma_f32_16x16x32_bf16 v[98:101], v[204:207], v[220:223], v[98:101]
	v_mfma_f32_16x16x32_bf16 v[86:89], v[178:181], v[228:231], v[86:89]
	v_mfma_f32_16x16x32_bf16 v[82:85], v[204:207], v[228:231], v[82:85]
	v_mfma_f32_16x16x32_bf16 v[70:73], v[178:181], v[236:239], v[70:73]
	v_mfma_f32_16x16x32_bf16 v[66:69], v[204:207], v[236:239], v[66:69]
	s_setprio 0
	s_setprio 1
	v_mfma_f32_16x16x32_bf16 v[118:121], v[182:185], v[216:219], v[118:121]
	v_mfma_f32_16x16x32_bf16 v[114:117], v[208:211], v[216:219], v[114:117]
	v_mfma_f32_16x16x32_bf16 v[102:105], v[182:185], v[224:227], v[102:105]
	v_mfma_f32_16x16x32_bf16 v[98:101], v[208:211], v[224:227], v[98:101]
	v_mfma_f32_16x16x32_bf16 v[86:89], v[182:185], v[232:235], v[86:89]
	v_mfma_f32_16x16x32_bf16 v[82:85], v[208:211], v[232:235], v[82:85]
	v_mfma_f32_16x16x32_bf16 v[70:73], v[182:185], v[240:243], v[70:73]
	v_mfma_f32_16x16x32_bf16 v[66:69], v[208:211], v[240:243], v[66:69]
	s_setprio 0
	s_barrier
; #define PG8_STAGE(bufoff, gbase, voff) do { _Pragma("unroll") for (int _i = 0; _i < 2; ++_i) \
;         __builtin_amdgcn_global_load_lds((const unsigned*)((const char*)(gbase) + (voff)[_i]), (PG8_LAS unsigned*)(lds + (bufoff) + ldsw + _i * 8192), 16, 0, 0); } while (0)
; #define PG8_LDA(dst, b, h) do { _Pragma("unroll") for (int m = 0; m < 4; ++m) _Pragma("unroll") for (int k = 0; k < 2; ++k) dst[m][k] = *(const PG8_LAS bf16x8*)(lds + PG8_SA(b, h) + aoff + m * 2048 + k * 1024); } while (0)
; #define PG8_MMA(ai, bj, At, Bt) do { __builtin_amdgcn_s_setprio(1); _Pragma("unroll") for (int m = 0; m < 4; ++m) _Pragma("unroll") for (int n = 0; n < 2; ++n) _Pragma("unroll") for (int k = 0; k < 2; ++k) \
;         acc[ai][bj][m][n] = __builtin_amdgcn_mfma_f32_16x16x32_bf16(Bt[n][k], At[m][k], acc[ai][bj][m][n], 0, 0, 0); __builtin_amdgcn_s_setprio(0); } while (0)
; #define PG8_BAR __builtin_amdgcn_s_barrier()
;     __device__ __forceinline__ void operator()(const f32x4 (&acc)[2][2][4][2], const Unit& u, int wr, int wc, int fr, int fq) const {
;         const int row0 = u.pm * BM + wr * 64 + fr, col0 = u.pn * BM + wc * 32 + 8 * fq;
;         const int tidn = (wr * 4 + wc) * 64 + fq * 16 + fr;
;         const u32x4* gp = (const u32x4*)G8 + (size_t)(u.pm * 16 + gsel + u.pn) * 8 * 512 + tidn;
;         u32x4* mp = M1 + (size_t)(u.pm * 8 + u.pn) * 16 * 512 + tidn;
;         constexpr float K255 = 1.0f / 255.0f;
; #pragma unroll
;         for (int ai = 0; ai < 2; ++ai)
; #pragma unroll
;             for (int m = 0; m < 4; ++m) { const size_t row = (size_t)(row0 + ai * HALF + m * 16);
;                 const u32x4 gw = gp[(ai * 4 + m) * 512];
;                 u32x4 pw[2];
;                 if (SECOND) { pw[0] = mp[((ai * 4 + m) * 2 + 0) * 512]; pw[1] = mp[((ai * 4 + m) * 2 + 1) * 512]; }
; template <class Epi, class Sched, bool ALIGN_EPI = false, bool SP2 = false>
; __device__ __forceinline__ void gemm_phase(PG8_LAS unsigned char* lds, const Gemm g, const Sched& S, const Epi& E) {
;     ...
;             PG8_WAIT_V(8); PG8_WAIT_L(0); PG8_BAR; PG8_MMA(0, 0, At, B0); PG8_MMA(0, 1, At, B1); PG8_BAR; PG8_SCHED;
;             PG8_LDA(At, 1, 1); PG8_STAGE(PG8_SB(1, 0), b3, voffB); PG8_STAGE(PG8_SB(1, 1), b3 + hstep, voffB); PG8_STAGE(PG8_SA(1, 0), a3, voffA);
;             PG8_WAIT_V(8); PG8_WAIT_L(0); PG8_BAR; PG8_MMA(1, 0, At, B0); PG8_MMA(1, 1, At, B1); PG8_BAR; PG8_SCHED;
	s_add_i32 s36, s47, s4
	v_lshl_add_u64 v[186:187], v[186:187], 0, s[68:69]
	s_mov_b32 m0, s36
	ds_read_b128 v[212:215], v169 offset:49152
	ds_read_b128 v[216:219], v169 offset:50176
	ds_read_b128 v[220:223], v169 offset:51200
	ds_read_b128 v[224:227], v169 offset:52224
	ds_read_b128 v[228:231], v169 offset:53248
	ds_read_b128 v[232:235], v169 offset:54272
	ds_read_b128 v[236:239], v169 offset:55296
	ds_read_b128 v[240:243], v169 offset:56320
	global_load_lds_dwordx4 v[186:187], off
	s_add_i32 m0, s36, 0x2000
	s_add_u32 s18, s18, 0x60080
	v_lshl_add_u64 v[186:187], v[244:245], 0, s[68:69]
	s_addc_u32 s19, s19, 0
	s_add_i32 s36, s76, s4
	global_load_lds_dwordx4 v[186:187], off
	v_lshl_add_u64 v[186:187], s[18:19], 0, v[148:149]
	s_mov_b32 m0, s36
	s_nop 0
	global_load_lds_dwordx4 v[186:187], off
	v_lshl_add_u64 v[186:187], s[18:19], 0, v[144:145]
	s_add_i32 m0, s36, 0x2000
	s_nop 0
	global_load_lds_dwordx4 v[186:187], off
	v_lshl_add_u64 v[186:187], v[246:247], 0, s[68:69]
	s_mov_b32 m0, s62
	s_nop 0
	global_load_lds_dwordx4 v[186:187], off
	v_lshl_add_u64 v[186:187], v[248:249], 0, s[68:69]
	s_mov_b32 m0, s63
	s_nop 0
	global_load_lds_dwordx4 v[186:187], off
	s_nop 0
	s_waitcnt vmcnt(8)
	s_waitcnt lgkmcnt(0)
	s_setprio 1
	s_barrier
	v_mfma_f32_16x16x32_bf16 v[62:65], v[160:163], v[212:215], v[62:65]
	v_mfma_f32_16x16x32_bf16 v[58:61], v[170:173], v[212:215], v[58:61]
	v_mfma_f32_16x16x32_bf16 v[46:49], v[160:163], v[220:223], v[46:49]
	v_mfma_f32_16x16x32_bf16 v[42:45], v[170:173], v[220:223], v[42:45]
	v_mfma_f32_16x16x32_bf16 v[30:33], v[160:163], v[228:231], v[30:33]
	v_mfma_f32_16x16x32_bf16 v[26:29], v[170:173], v[228:231], v[26:29]
	v_mfma_f32_16x16x32_bf16 v[14:17], v[160:163], v[236:239], v[14:17]
	v_mfma_f32_16x16x32_bf16 v[10:13], v[170:173], v[236:239], v[10:13]
	v_mfma_f32_16x16x32_bf16 v[62:65], v[164:167], v[216:219], v[62:65]
	v_mfma_f32_16x16x32_bf16 v[58:61], v[174:177], v[216:219], v[58:61]
	v_mfma_f32_16x16x32_bf16 v[46:49], v[164:167], v[224:227], v[46:49]
	v_mfma_f32_16x16x32_bf16 v[42:45], v[174:177], v[224:227], v[42:45]
	v_mfma_f32_16x16x32_bf16 v[30:33], v[164:167], v[232:235], v[30:33]
	v_mfma_f32_16x16x32_bf16 v[26:29], v[174:177], v[232:235], v[26:29]
	v_mfma_f32_16x16x32_bf16 v[14:17], v[164:167], v[240:243], v[14:17]
	v_mfma_f32_16x16x32_bf16 v[10:13], v[174:177], v[240:243], v[10:13]
	v_mfma_f32_16x16x32_bf16 v[54:57], v[178:181], v[212:215], v[54:57]
	v_mfma_f32_16x16x32_bf16 v[50:53], v[204:207], v[212:215], v[50:53]
	v_mfma_f32_16x16x32_bf16 v[38:41], v[178:181], v[220:223], v[38:41]
	v_mfma_f32_16x16x32_bf16 v[34:37], v[204:207], v[220:223], v[34:37]
	v_mfma_f32_16x16x32_bf16 v[22:25], v[178:181], v[228:231], v[22:25]
	v_mfma_f32_16x16x32_bf16 v[18:21], v[204:207], v[228:231], v[18:21]
	v_mfma_f32_16x16x32_bf16 v[6:9], v[178:181], v[236:239], v[6:9]
	v_mfma_f32_16x16x32_bf16 v[2:5], v[204:207], v[236:239], v[2:5]
	v_mfma_f32_16x16x32_bf16 v[54:57], v[182:185], v[216:219], v[54:57]
	v_mfma_f32_16x16x32_bf16 v[50:53], v[208:211], v[216:219], v[50:53]
	v_mfma_f32_16x16x32_bf16 v[38:41], v[182:185], v[224:227], v[38:41]
	v_mfma_f32_16x16x32_bf16 v[34:37], v[208:211], v[224:227], v[34:37]
	v_mfma_f32_16x16x32_bf16 v[22:25], v[182:185], v[232:235], v[22:25]
	v_mfma_f32_16x16x32_bf16 v[18:21], v[208:211], v[232:235], v[18:21]
	v_mfma_f32_16x16x32_bf16 v[6:9], v[182:185], v[240:243], v[6:9]
	v_mfma_f32_16x16x32_bf16 v[2:5], v[208:211], v[240:243], v[2:5]
	s_setprio 0
	s_barrier
	s_add_i32 s46, s46, 2
	s_add_u32 s60, s60, 0x100
	s_addc_u32 s73, s73, 0
	s_cmp_gt_u32 s46, 21
	s_mov_b64 s[36:37], s[42:43]
	s_cbranch_scc0 .LBB0_160
	s_cmp_lg_u64 s[10:11], 0
	s_cselect_b32 s32, 3, 1
.LBB0_163:
	s_lshl_b32 s18, s34, 4
	s_add_i32 s18, s28, s18
	s_add_i32 s18, s18, 8
	s_ashr_i32 s19, s18, 31
	s_lshl_b64 s[18:19], s[18:19], 16
	v_lshl_add_u64 v[160:161], v[152:153], 0, s[18:19]
	s_lshl_b32 s18, s34, 3
	s_add_i32 s18, s18, s28
	s_ashr_i32 s19, s18, 31
	s_lshl_b64 s[18:19], s[18:19], 17
	v_lshl_add_u64 v[162:163], v[154:155], 0, s[18:19]
	global_load_dwordx4 v[170:173], v[160:161], off
	global_load_dwordx4 v[174:177], v[162:163], off
	s_movk_i32 s18, 0x2000
	v_add_co_u32_e32 v178, vcc, s18, v162
	v_lshl_add_u32 v164, s34, 8, v1
	s_nop 0
	v_addc_co_u32_e32 v179, vcc, 0, v163, vcc
	global_load_dwordx4 v[178:181], v[178:179], off
	v_lshl_or_b32 v166, s28, 8, v168
	v_ashrrev_i32_e32 v165, 31, v164
	v_ashrrev_i32_e32 v167, 31, v166
	v_lshlrev_b64 v[182:183], 12, v[164:165]
	s_movk_i32 s28, 0x6000
	s_movk_i32 s19, 0x4000
	s_mov_b32 s34, 0xa000
	s_mov_b32 s37, 0xe000
	s_mov_b32 s36, 0xc000
	s_movk_i32 s81, 0x4000
	s_waitcnt vmcnt(0)
; __device__ __forceinline__ unsigned cvt_pk_bf16(float lo, float hi) { const f32x2c_t v = {lo, hi}; const bf16x2c_t b = __builtin_convertvector(v, bf16x2c_t); return __builtin_bit_cast(unsigned, b); }
; __device__ __forceinline__ float bf_lo(unsigned w) { return __uint_as_float(w << 16); }
; __device__ __forceinline__ float bf_hi(unsigned w) { return __uint_as_float(w & 0xffff0000u); }
;     __device__ __forceinline__ void operator()(const f32x4 (&acc)[2][2][4][2], const Unit& u, int wr, int wc, int fr, int fq) const {
;     ...
; #pragma unroll
;         for (int ai = 0; ai < 2; ++ai)
; #pragma unroll
;             for (int m = 0; m < 4; ++m) { const size_t row = (size_t)(row0 + ai * HALF + m * 16);
;                 const u32x4 gw = gp[(ai * 4 + m) * 512];
;                 u32x4 pw[2];
;                 if (SECOND) { pw[0] = mp[((ai * 4 + m) * 2 + 0) * 512]; pw[1] = mp[((ai * 4 + m) * 2 + 1) * 512]; }
; #pragma unroll
;                 for (int bj = 0; bj < 2; ++bj) { const unsigned gx = bj ? gw.z : gw.x, gy = bj ? gw.w : gw.y;
;                     const f32x4 g0 = (f32x4){(float)(gx & 255u), (float)((gx >> 8) & 255u), (float)((gx >> 16) & 255u), (float)(gx >> 24)} * K255,
;                                 g1 = (f32x4){(float)(gy & 255u), (float)((gy >> 8) & 255u), (float)((gy >> 16) & 255u), (float)(gy >> 24)} * K255;
;                     f32x4 v0 = acc[ai][bj][m][0] * g0, v1 = acc[ai][bj][m][1] * g1;
;                     if (SECOND) { const u32x4 p = pw[bj];
;                         v0 = v0 + (f32x4){bf_lo(p.x), bf_hi(p.x), bf_lo(p.y), bf_hi(p.y)}; v1 = v1 + (f32x4){bf_lo(p.z), bf_hi(p.z), bf_lo(p.w), bf_hi(p.w)}; }
;                     u32x4 w; w.x = cvt_pk_bf16(v0[0], v0[1]); w.y = cvt_pk_bf16(v0[2], v0[3]); w.z = cvt_pk_bf16(v1[0], v1[1]); w.w = cvt_pk_bf16(v1[2], v1[3]);
;                     if (SECOND) *(u32x4*)(MG + row * DM + col0 + bj * HALF) = w; else mp[((ai * 4 + m) * 2 + bj) * 512] = w; }
	v_cvt_f32_ubyte3_e32 v185, v170
	v_cvt_f32_ubyte2_e32 v184, v170
	v_cvt_f32_ubyte1_e32 v207, v171
	v_cvt_f32_ubyte0_e32 v206, v171
	v_cvt_f32_ubyte1_e32 v187, v170
	v_cvt_f32_ubyte0_e32 v186, v170
	v_pk_mul_f32 v[184:185], v[184:185], s[26:27] op_sel_hi:[1,0]
	v_cvt_f32_ubyte3_e32 v205, v171
	v_cvt_f32_ubyte2_e32 v204, v171
	v_pk_mul_f32 v[170:171], v[206:207], s[26:27] op_sel_hi:[1,0]
	v_lshlrev_b32_e32 v206, 16, v174
	v_and_b32_e32 v207, 0xffff0000, v174
	v_lshlrev_b32_e32 v174, 16, v175
	v_and_b32_e32 v175, 0xffff0000, v175
	v_pk_mul_f32 v[186:187], v[186:187], s[26:27] op_sel_hi:[1,0]
	v_pk_mul_f32 v[204:205], v[204:205], s[26:27] op_sel_hi:[1,0]
	v_pk_fma_f32 v[128:129], v[128:129], v[184:185], v[174:175]
	v_lshlrev_b32_e32 v174, 16, v176
	v_and_b32_e32 v175, 0xffff0000, v176
	v_lshlrev_b32_e32 v176, 16, v177
	v_and_b32_e32 v177, 0xffff0000, v177
	v_pk_fma_f32 v[126:127], v[126:127], v[186:187], v[206:207]
	v_pk_fma_f32 v[124:125], v[124:125], v[204:205], v[176:177]
	v_pk_fma_f32 v[122:123], v[122:123], v[170:171], v[174:175]
	v_cvt_pk_bf16_f32 v126, v126, v127
	v_cvt_pk_bf16_f32 v127, v128, v129
	v_cvt_pk_bf16_f32 v128, v122, v123
	v_cvt_pk_bf16_f32 v129, v124, v125
	v_lshl_add_u64 v[122:123], s[12:13], 0, v[182:183]
	v_lshlrev_b64 v[124:125], 1, v[166:167]
	v_lshl_add_u64 v[122:123], v[122:123], 0, v[124:125]
	global_store_dwordx4 v[122:123], v[126:129], off
	v_cvt_f32_ubyte3_e32 v167, v173
	v_cvt_f32_ubyte2_e32 v166, v173
	v_cvt_f32_ubyte3_e32 v127, v172
	v_cvt_f32_ubyte2_e32 v126, v172
	v_cvt_f32_ubyte1_e32 v129, v172
	v_cvt_f32_ubyte0_e32 v128, v172
	v_pk_mul_f32 v[128:129], v[128:129], s[26:27] op_sel_hi:[1,0]
	v_pk_mul_f32 v[126:127], v[126:127], s[26:27] op_sel_hi:[1,0]
	v_cvt_f32_ubyte1_e32 v171, v173
	v_cvt_f32_ubyte0_e32 v170, v173
	v_lshlrev_b32_e32 v172, 16, v178
	v_and_b32_e32 v173, 0xffff0000, v178
	v_lshlrev_b32_e32 v174, 16, v179
	v_and_b32_e32 v175, 0xffff0000, v179
	v_pk_mul_f32 v[170:171], v[170:171], s[26:27] op_sel_hi:[1,0]
	v_pk_mul_f32 v[166:167], v[166:167], s[26:27] op_sel_hi:[1,0]
	v_pk_fma_f32 v[120:121], v[120:121], v[126:127], v[174:175]
	v_pk_fma_f32 v[118:119], v[118:119], v[128:129], v[172:173]
	v_lshlrev_b32_e32 v126, 16, v180
	v_and_b32_e32 v127, 0xffff0000, v180
	v_lshlrev_b32_e32 v128, 16, v181
	v_and_b32_e32 v129, 0xffff0000, v181
	v_pk_fma_f32 v[128:129], v[116:117], v[166:167], v[128:129]
	v_pk_fma_f32 v[116:117], v[114:115], v[170:171], v[126:127]
	v_cvt_pk_bf16_f32 v114, v118, v119
	v_cvt_pk_bf16_f32 v115, v120, v121
	v_cvt_pk_bf16_f32 v116, v116, v117
	v_cvt_pk_bf16_f32 v117, v128, v129
	global_store_dwordx4 v[122:123], v[114:117], off offset:256
	s_bitcmp1_b32 s32, 1
	s_cbranch_scc0 .Lalign160
	s_barrier
.Lalign160:
	v_or_b32_e32 v166, 16, v164
	v_ashrrev_i32_e32 v167, 31, v166
	v_add_co_u32_e32 v114, vcc, s28, v162
	v_lshlrev_b64 v[166:167], 12, v[166:167]
	s_nop 0
	v_addc_co_u32_e32 v115, vcc, 0, v163, vcc
	v_add_co_u32_e32 v118, vcc, s19, v162
	global_load_dwordx4 v[114:117], v[114:115], off
	s_nop 0
	v_addc_co_u32_e32 v119, vcc, 0, v163, vcc
	v_add_co_u32_e32 v126, vcc, s18, v160
	global_load_dwordx4 v[118:121], v[118:119], off
	s_nop 0
	v_addc_co_u32_e32 v127, vcc, 0, v161, vcc
	global_load_dwordx4 v[126:129], v[126:127], off
	s_mov_b32 s18, 0x8000
	s_waitcnt vmcnt(0)
	v_cvt_f32_ubyte3_e32 v171, v126
	v_cvt_f32_ubyte2_e32 v170, v126
	v_cvt_f32_ubyte1_e32 v173, v126
	v_cvt_f32_ubyte0_e32 v172, v126
	v_cvt_f32_ubyte1_e32 v177, v127
	v_cvt_f32_ubyte0_e32 v176, v127
	v_pk_mul_f32 v[172:173], v[172:173], s[26:27] op_sel_hi:[1,0]
	v_pk_mul_f32 v[170:171], v[170:171], s[26:27] op_sel_hi:[1,0]
	v_cvt_f32_ubyte3_e32 v175, v127
	v_cvt_f32_ubyte2_e32 v174, v127
	v_pk_mul_f32 v[126:127], v[176:177], s[26:27] op_sel_hi:[1,0]
	v_lshlrev_b32_e32 v176, 16, v118
	v_and_b32_e32 v177, 0xffff0000, v118
	v_lshlrev_b32_e32 v118, 16, v119
	v_and_b32_e32 v119, 0xffff0000, v119
	v_pk_mul_f32 v[174:175], v[174:175], s[26:27] op_sel_hi:[1,0]
	v_pk_fma_f32 v[112:113], v[112:113], v[170:171], v[118:119]
	v_pk_fma_f32 v[110:111], v[110:111], v[172:173], v[176:177]
	v_lshlrev_b32_e32 v118, 16, v120
	v_and_b32_e32 v119, 0xffff0000, v120
	v_lshlrev_b32_e32 v120, 16, v121
	v_and_b32_e32 v121, 0xffff0000, v121
	v_pk_fma_f32 v[120:121], v[108:109], v[174:175], v[120:121]
	v_pk_fma_f32 v[108:109], v[106:107], v[126:127], v[118:119]
	v_cvt_pk_bf16_f32 v106, v110, v111
	v_lshl_add_u64 v[110:111], s[12:13], 0, v[166:167]
	v_cvt_pk_bf16_f32 v107, v112, v113
	v_cvt_pk_bf16_f32 v108, v108, v109
	v_cvt_pk_bf16_f32 v109, v120, v121
	v_lshl_add_u64 v[110:111], v[110:111], 0, v[124:125]
	global_store_dwordx4 v[110:111], v[106:109], off
	v_cvt_f32_ubyte3_e32 v113, v129
	v_cvt_f32_ubyte2_e32 v112, v129
	v_cvt_f32_ubyte3_e32 v107, v128
	v_cvt_f32_ubyte2_e32 v106, v128
	v_cvt_f32_ubyte1_e32 v109, v128
	v_cvt_f32_ubyte0_e32 v108, v128
	v_pk_mul_f32 v[108:109], v[108:109], s[26:27] op_sel_hi:[1,0]
	v_pk_mul_f32 v[106:107], v[106:107], s[26:27] op_sel_hi:[1,0]
	v_cvt_f32_ubyte1_e32 v119, v129
	v_cvt_f32_ubyte0_e32 v118, v129
	v_lshlrev_b32_e32 v120, 16, v114
	v_and_b32_e32 v121, 0xffff0000, v114
	v_lshlrev_b32_e32 v114, 16, v115
	v_and_b32_e32 v115, 0xffff0000, v115
	v_pk_mul_f32 v[118:119], v[118:119], s[26:27] op_sel_hi:[1,0]
	v_pk_mul_f32 v[112:113], v[112:113], s[26:27] op_sel_hi:[1,0]
	v_pk_fma_f32 v[104:105], v[104:105], v[106:107], v[114:115]
	v_pk_fma_f32 v[102:103], v[102:103], v[108:109], v[120:121]
	v_lshlrev_b32_e32 v106, 16, v116
	v_and_b32_e32 v107, 0xffff0000, v116
	v_lshlrev_b32_e32 v108, 16, v117
	v_and_b32_e32 v109, 0xffff0000, v117
	v_pk_fma_f32 v[108:109], v[100:101], v[112:113], v[108:109]
	v_pk_fma_f32 v[100:101], v[98:99], v[118:119], v[106:107]
	v_cvt_pk_bf16_f32 v98, v102, v103
	v_cvt_pk_bf16_f32 v99, v104, v105
	v_cvt_pk_bf16_f32 v100, v100, v101
	v_cvt_pk_bf16_f32 v101, v108, v109
	global_store_dwordx4 v[110:111], v[98:101], off offset:256
	v_or_b32_e32 v110, 32, v164
	v_ashrrev_i32_e32 v111, 31, v110
	v_add_co_u32_e32 v98, vcc, s34, v162
	v_lshlrev_b64 v[110:111], 12, v[110:111]
	s_nop 0
	v_addc_co_u32_e32 v99, vcc, 0, v163, vcc
	v_add_co_u32_e32 v102, vcc, s18, v162
	global_load_dwordx4 v[98:101], v[98:99], off
	s_nop 0
	v_addc_co_u32_e32 v103, vcc, 0, v163, vcc
	v_add_co_u32_e32 v106, vcc, s19, v160
	global_load_dwordx4 v[102:105], v[102:103], off
	s_nop 0
	v_addc_co_u32_e32 v107, vcc, 0, v161, vcc
	global_load_dwordx4 v[106:109], v[106:107], off
	s_waitcnt vmcnt(0)
; __device__ __forceinline__ unsigned cvt_pk_bf16(float lo, float hi) { const f32x2c_t v = {lo, hi}; const bf16x2c_t b = __builtin_convertvector(v, bf16x2c_t); return __builtin_bit_cast(unsigned, b); }
; __device__ __forceinline__ float bf_lo(unsigned w) { return __uint_as_float(w << 16); }
; __device__ __forceinline__ float bf_hi(unsigned w) { return __uint_as_float(w & 0xffff0000u); }
;     __device__ __forceinline__ void operator()(const f32x4 (&acc)[2][2][4][2], const Unit& u, int wr, int wc, int fr, int fq) const {
;     ...
; #pragma unroll
;         for (int ai = 0; ai < 2; ++ai)
; #pragma unroll
;             for (int m = 0; m < 4; ++m) { const size_t row = (size_t)(row0 + ai * HALF + m * 16);
;                 const u32x4 gw = gp[(ai * 4 + m) * 512];
;                 u32x4 pw[2];
;                 if (SECOND) { pw[0] = mp[((ai * 4 + m) * 2 + 0) * 512]; pw[1] = mp[((ai * 4 + m) * 2 + 1) * 512]; }
; #pragma unroll
;                 for (int bj = 0; bj < 2; ++bj) { const unsigned gx = bj ? gw.z : gw.x, gy = bj ? gw.w : gw.y;
;                     const f32x4 g0 = (f32x4){(float)(gx & 255u), (float)((gx >> 8) & 255u), (float)((gx >> 16) & 255u), (float)(gx >> 24)} * K255,
;                                 g1 = (f32x4){(float)(gy & 255u), (float)((gy >> 8) & 255u), (float)((gy >> 16) & 255u), (float)(gy >> 24)} * K255;
;                     f32x4 v0 = acc[ai][bj][m][0] * g0, v1 = acc[ai][bj][m][1] * g1;
;                     if (SECOND) { const u32x4 p = pw[bj];
;                         v0 = v0 + (f32x4){bf_lo(p.x), bf_hi(p.x), bf_lo(p.y), bf_hi(p.y)}; v1 = v1 + (f32x4){bf_lo(p.z), bf_hi(p.z), bf_lo(p.w), bf_hi(p.w)}; }
;                     u32x4 w; w.x = cvt_pk_bf16(v0[0], v0[1]); w.y = cvt_pk_bf16(v0[2], v0[3]); w.z = cvt_pk_bf16(v1[0], v1[1]); w.w = cvt_pk_bf16(v1[2], v1[3]);
;                     if (SECOND) *(u32x4*)(MG + row * DM + col0 + bj * HALF) = w; else mp[((ai * 4 + m) * 2 + bj) * 512] = w; }
	v_cvt_f32_ubyte3_e32 v113, v106
	v_cvt_f32_ubyte2_e32 v112, v106
	v_cvt_f32_ubyte1_e32 v115, v106
	v_cvt_f32_ubyte0_e32 v114, v106
	v_cvt_f32_ubyte1_e32 v119, v107
	v_cvt_f32_ubyte0_e32 v118, v107
	v_pk_mul_f32 v[114:115], v[114:115], s[26:27] op_sel_hi:[1,0]
	v_pk_mul_f32 v[112:113], v[112:113], s[26:27] op_sel_hi:[1,0]
	v_cvt_f32_ubyte3_e32 v117, v107
	v_cvt_f32_ubyte2_e32 v116, v107
	v_pk_mul_f32 v[106:107], v[118:119], s[26:27] op_sel_hi:[1,0]
	v_lshlrev_b32_e32 v118, 16, v102
	v_and_b32_e32 v119, 0xffff0000, v102
	v_lshlrev_b32_e32 v102, 16, v103
	v_and_b32_e32 v103, 0xffff0000, v103
	v_pk_mul_f32 v[116:117], v[116:117], s[26:27] op_sel_hi:[1,0]
	v_pk_fma_f32 v[96:97], v[96:97], v[112:113], v[102:103]
	v_pk_fma_f32 v[94:95], v[94:95], v[114:115], v[118:119]
	v_lshlrev_b32_e32 v102, 16, v104
	v_and_b32_e32 v103, 0xffff0000, v104
	v_lshlrev_b32_e32 v104, 16, v105
	v_and_b32_e32 v105, 0xffff0000, v105
	v_pk_fma_f32 v[104:105], v[92:93], v[116:117], v[104:105]
	v_pk_fma_f32 v[92:93], v[90:91], v[106:107], v[102:103]
	v_cvt_pk_bf16_f32 v90, v94, v95
	v_lshl_add_u64 v[94:95], s[12:13], 0, v[110:111]
	v_cvt_pk_bf16_f32 v91, v96, v97
	v_cvt_pk_bf16_f32 v92, v92, v93
	v_cvt_pk_bf16_f32 v93, v104, v105
	v_lshl_add_u64 v[94:95], v[94:95], 0, v[124:125]
	global_store_dwordx4 v[94:95], v[90:93], off
	v_cvt_f32_ubyte3_e32 v97, v109
	v_cvt_f32_ubyte2_e32 v96, v109
	v_cvt_f32_ubyte3_e32 v91, v108
	v_cvt_f32_ubyte2_e32 v90, v108
	v_cvt_f32_ubyte1_e32 v93, v108
	v_cvt_f32_ubyte0_e32 v92, v108
	v_pk_mul_f32 v[92:93], v[92:93], s[26:27] op_sel_hi:[1,0]
	v_pk_mul_f32 v[90:91], v[90:91], s[26:27] op_sel_hi:[1,0]
	v_cvt_f32_ubyte1_e32 v103, v109
	v_cvt_f32_ubyte0_e32 v102, v109
	v_lshlrev_b32_e32 v104, 16, v98
	v_and_b32_e32 v105, 0xffff0000, v98
	v_lshlrev_b32_e32 v98, 16, v99
	v_and_b32_e32 v99, 0xffff0000, v99
	v_pk_mul_f32 v[102:103], v[102:103], s[26:27] op_sel_hi:[1,0]
	v_pk_mul_f32 v[96:97], v[96:97], s[26:27] op_sel_hi:[1,0]
	v_pk_fma_f32 v[88:89], v[88:89], v[90:91], v[98:99]
	v_pk_fma_f32 v[86:87], v[86:87], v[92:93], v[104:105]
	v_lshlrev_b32_e32 v90, 16, v100
	v_and_b32_e32 v91, 0xffff0000, v100
	v_lshlrev_b32_e32 v92, 16, v101
	v_and_b32_e32 v93, 0xffff0000, v101
	v_pk_fma_f32 v[92:93], v[84:85], v[96:97], v[92:93]
	v_pk_fma_f32 v[84:85], v[82:83], v[102:103], v[90:91]
	v_cvt_pk_bf16_f32 v82, v86, v87
	v_cvt_pk_bf16_f32 v83, v88, v89
	v_cvt_pk_bf16_f32 v84, v84, v85
	v_cvt_pk_bf16_f32 v85, v92, v93
	global_store_dwordx4 v[94:95], v[82:85], off offset:256
	v_or_b32_e32 v94, 48, v164
	v_ashrrev_i32_e32 v95, 31, v94
	v_add_co_u32_e32 v82, vcc, s37, v162
	v_lshlrev_b64 v[94:95], 12, v[94:95]
	s_nop 0
	v_addc_co_u32_e32 v83, vcc, 0, v163, vcc
	v_add_co_u32_e32 v86, vcc, s36, v162
	global_load_dwordx4 v[82:85], v[82:83], off
	s_nop 0
	v_addc_co_u32_e32 v87, vcc, 0, v163, vcc
	v_add_co_u32_e32 v90, vcc, s28, v160
	global_load_dwordx4 v[86:89], v[86:87], off
	s_nop 0
	v_addc_co_u32_e32 v91, vcc, 0, v161, vcc
	global_load_dwordx4 v[90:93], v[90:91], off
	s_waitcnt vmcnt(0)
	v_cvt_f32_ubyte3_e32 v97, v90
	v_cvt_f32_ubyte2_e32 v96, v90
	v_cvt_f32_ubyte1_e32 v99, v90
	v_cvt_f32_ubyte0_e32 v98, v90
	v_cvt_f32_ubyte1_e32 v103, v91
	v_cvt_f32_ubyte0_e32 v102, v91
	v_pk_mul_f32 v[98:99], v[98:99], s[26:27] op_sel_hi:[1,0]
	v_pk_mul_f32 v[96:97], v[96:97], s[26:27] op_sel_hi:[1,0]
	v_cvt_f32_ubyte3_e32 v101, v91
	v_cvt_f32_ubyte2_e32 v100, v91
	v_pk_mul_f32 v[90:91], v[102:103], s[26:27] op_sel_hi:[1,0]
	v_lshlrev_b32_e32 v102, 16, v86
	v_and_b32_e32 v103, 0xffff0000, v86
	v_lshlrev_b32_e32 v86, 16, v87
	v_and_b32_e32 v87, 0xffff0000, v87
	v_pk_mul_f32 v[100:101], v[100:101], s[26:27] op_sel_hi:[1,0]
	v_pk_fma_f32 v[80:81], v[80:81], v[96:97], v[86:87]
	v_pk_fma_f32 v[78:79], v[78:79], v[98:99], v[102:103]
	v_lshlrev_b32_e32 v86, 16, v88
	v_and_b32_e32 v87, 0xffff0000, v88
	v_lshlrev_b32_e32 v88, 16, v89
	v_and_b32_e32 v89, 0xffff0000, v89
	v_pk_fma_f32 v[88:89], v[76:77], v[100:101], v[88:89]
	v_pk_fma_f32 v[76:77], v[74:75], v[90:91], v[86:87]
	v_cvt_pk_bf16_f32 v74, v78, v79
	v_lshl_add_u64 v[78:79], s[12:13], 0, v[94:95]
	v_cvt_pk_bf16_f32 v75, v80, v81
	v_cvt_pk_bf16_f32 v76, v76, v77
	v_cvt_pk_bf16_f32 v77, v88, v89
	v_lshl_add_u64 v[78:79], v[78:79], 0, v[124:125]
	global_store_dwordx4 v[78:79], v[74:77], off
	v_cvt_f32_ubyte3_e32 v81, v93
	v_cvt_f32_ubyte2_e32 v80, v93
	v_cvt_f32_ubyte3_e32 v75, v92
	v_cvt_f32_ubyte2_e32 v74, v92
	v_cvt_f32_ubyte1_e32 v77, v92
	v_cvt_f32_ubyte0_e32 v76, v92
	v_pk_mul_f32 v[76:77], v[76:77], s[26:27] op_sel_hi:[1,0]
	v_pk_mul_f32 v[74:75], v[74:75], s[26:27] op_sel_hi:[1,0]
	v_cvt_f32_ubyte1_e32 v87, v93
	v_cvt_f32_ubyte0_e32 v86, v93
	v_lshlrev_b32_e32 v88, 16, v82
	v_and_b32_e32 v89, 0xffff0000, v82
	v_lshlrev_b32_e32 v82, 16, v83
	v_and_b32_e32 v83, 0xffff0000, v83
	v_pk_mul_f32 v[86:87], v[86:87], s[26:27] op_sel_hi:[1,0]
	v_pk_mul_f32 v[80:81], v[80:81], s[26:27] op_sel_hi:[1,0]
	v_pk_fma_f32 v[72:73], v[72:73], v[74:75], v[82:83]
	v_pk_fma_f32 v[70:71], v[70:71], v[76:77], v[88:89]
	v_lshlrev_b32_e32 v74, 16, v84
	v_and_b32_e32 v75, 0xffff0000, v84
	v_lshlrev_b32_e32 v76, 16, v85
	v_and_b32_e32 v77, 0xffff0000, v85
	v_pk_fma_f32 v[76:77], v[68:69], v[80:81], v[76:77]
	v_pk_fma_f32 v[68:69], v[66:67], v[86:87], v[74:75]
	v_cvt_pk_bf16_f32 v66, v70, v71
	v_cvt_pk_bf16_f32 v67, v72, v73
	v_cvt_pk_bf16_f32 v68, v68, v69
	v_cvt_pk_bf16_f32 v69, v76, v77
	global_store_dwordx4 v[78:79], v[66:69], off offset:256
	s_nop 1
	v_add_co_u32_e32 v66, vcc, s18, v160
	s_mov_b32 s18, 0x10000
	s_nop 0
	v_addc_co_u32_e32 v67, vcc, 0, v161, vcc
	v_add_co_u32_e32 v70, vcc, s18, v162
	global_load_dwordx4 v[66:69], v[66:67], off
	s_nop 0
	v_addc_co_u32_e32 v71, vcc, 0, v163, vcc
	global_load_dwordx4 v[70:73], v[70:71], off
	s_mov_b32 s18, 0x12000
	v_add_co_u32_e32 v74, vcc, s18, v162
	s_mov_b64 s[18:19], 0x80000
	s_nop 0
	v_addc_co_u32_e32 v75, vcc, 0, v163, vcc
	global_load_dwordx4 v[74:77], v[74:75], off
	s_waitcnt vmcnt(2)
; __device__ __forceinline__ unsigned cvt_pk_bf16(float lo, float hi) { const f32x2c_t v = {lo, hi}; const bf16x2c_t b = __builtin_convertvector(v, bf16x2c_t); return __builtin_bit_cast(unsigned, b); }
; __device__ __forceinline__ float bf_lo(unsigned w) { return __uint_as_float(w << 16); }
; __device__ __forceinline__ float bf_hi(unsigned w) { return __uint_as_float(w & 0xffff0000u); }
;     __device__ __forceinline__ void operator()(const f32x4 (&acc)[2][2][4][2], const Unit& u, int wr, int wc, int fr, int fq) const {
;     ...
; #pragma unroll
;         for (int ai = 0; ai < 2; ++ai)
; #pragma unroll
;             for (int m = 0; m < 4; ++m) { const size_t row = (size_t)(row0 + ai * HALF + m * 16);
;                 const u32x4 gw = gp[(ai * 4 + m) * 512];
;                 u32x4 pw[2];
;                 if (SECOND) { pw[0] = mp[((ai * 4 + m) * 2 + 0) * 512]; pw[1] = mp[((ai * 4 + m) * 2 + 1) * 512]; }
; #pragma unroll
;                 for (int bj = 0; bj < 2; ++bj) { const unsigned gx = bj ? gw.z : gw.x, gy = bj ? gw.w : gw.y;
;                     const f32x4 g0 = (f32x4){(float)(gx & 255u), (float)((gx >> 8) & 255u), (float)((gx >> 16) & 255u), (float)(gx >> 24)} * K255,
;                                 g1 = (f32x4){(float)(gy & 255u), (float)((gy >> 8) & 255u), (float)((gy >> 16) & 255u), (float)(gy >> 24)} * K255;
;                     f32x4 v0 = acc[ai][bj][m][0] * g0, v1 = acc[ai][bj][m][1] * g1;
;                     if (SECOND) { const u32x4 p = pw[bj];
;                         v0 = v0 + (f32x4){bf_lo(p.x), bf_hi(p.x), bf_lo(p.y), bf_hi(p.y)}; v1 = v1 + (f32x4){bf_lo(p.z), bf_hi(p.z), bf_lo(p.w), bf_hi(p.w)}; }
;                     u32x4 w; w.x = cvt_pk_bf16(v0[0], v0[1]); w.y = cvt_pk_bf16(v0[2], v0[3]); w.z = cvt_pk_bf16(v1[0], v1[1]); w.w = cvt_pk_bf16(v1[2], v1[3]);
;                     if (SECOND) *(u32x4*)(MG + row * DM + col0 + bj * HALF) = w; else mp[((ai * 4 + m) * 2 + bj) * 512] = w; }
	v_cvt_f32_ubyte3_e32 v79, v66
	v_cvt_f32_ubyte2_e32 v78, v66
	v_cvt_f32_ubyte1_e32 v81, v66
	v_cvt_f32_ubyte0_e32 v80, v66
	v_cvt_f32_ubyte1_e32 v85, v67
	v_cvt_f32_ubyte0_e32 v84, v67
	v_pk_mul_f32 v[80:81], v[80:81], s[26:27] op_sel_hi:[1,0]
	v_pk_mul_f32 v[78:79], v[78:79], s[26:27] op_sel_hi:[1,0]
	v_cvt_f32_ubyte3_e32 v83, v67
	v_cvt_f32_ubyte2_e32 v82, v67
	v_pk_mul_f32 v[66:67], v[84:85], s[26:27] op_sel_hi:[1,0]
	s_waitcnt vmcnt(1)
	v_lshlrev_b32_e32 v84, 16, v70
	v_and_b32_e32 v85, 0xffff0000, v70
	v_lshlrev_b32_e32 v70, 16, v71
	v_and_b32_e32 v71, 0xffff0000, v71
	v_pk_mul_f32 v[82:83], v[82:83], s[26:27] op_sel_hi:[1,0]
	v_pk_fma_f32 v[64:65], v[64:65], v[78:79], v[70:71]
	v_pk_fma_f32 v[62:63], v[62:63], v[80:81], v[84:85]
	v_lshlrev_b32_e32 v70, 16, v72
	v_and_b32_e32 v71, 0xffff0000, v72
	v_lshlrev_b32_e32 v72, 16, v73
	v_and_b32_e32 v73, 0xffff0000, v73
	v_pk_fma_f32 v[72:73], v[60:61], v[82:83], v[72:73]
	v_pk_fma_f32 v[60:61], v[58:59], v[66:67], v[70:71]
	v_cvt_pk_bf16_f32 v58, v62, v63
	v_lshl_add_u64 v[62:63], v[122:123], 0, s[18:19]
	s_mov_b32 s18, 0x80000
	v_cvt_pk_bf16_f32 v59, v64, v65
	v_add_co_u32_e32 v64, vcc, s18, v122
	v_cvt_pk_bf16_f32 v60, v60, v61
	v_cvt_pk_bf16_f32 v61, v72, v73
	v_addc_co_u32_e32 v65, vcc, 0, v123, vcc
	global_store_dwordx4 v[64:65], v[58:61], off
	v_cvt_f32_ubyte3_e32 v65, v69
	v_cvt_f32_ubyte2_e32 v64, v69
	v_cvt_f32_ubyte3_e32 v59, v68
	v_cvt_f32_ubyte2_e32 v58, v68
	v_cvt_f32_ubyte1_e32 v61, v68
	v_cvt_f32_ubyte0_e32 v60, v68
	v_pk_mul_f32 v[60:61], v[60:61], s[26:27] op_sel_hi:[1,0]
	v_pk_mul_f32 v[58:59], v[58:59], s[26:27] op_sel_hi:[1,0]
	v_cvt_f32_ubyte1_e32 v67, v69
	v_cvt_f32_ubyte0_e32 v66, v69
	s_waitcnt vmcnt(1)
	v_lshlrev_b32_e32 v68, 16, v74
	v_and_b32_e32 v69, 0xffff0000, v74
	v_lshlrev_b32_e32 v70, 16, v75
	v_and_b32_e32 v71, 0xffff0000, v75
	v_pk_mul_f32 v[66:67], v[66:67], s[26:27] op_sel_hi:[1,0]
	v_pk_mul_f32 v[64:65], v[64:65], s[26:27] op_sel_hi:[1,0]
	v_pk_fma_f32 v[56:57], v[56:57], v[58:59], v[70:71]
	v_pk_fma_f32 v[54:55], v[54:55], v[60:61], v[68:69]
	v_lshlrev_b32_e32 v58, 16, v76
	v_and_b32_e32 v59, 0xffff0000, v76
	v_lshlrev_b32_e32 v60, 16, v77
	v_and_b32_e32 v61, 0xffff0000, v77
	v_pk_fma_f32 v[60:61], v[52:53], v[64:65], v[60:61]
	v_pk_fma_f32 v[52:53], v[50:51], v[66:67], v[58:59]
	v_cvt_pk_bf16_f32 v50, v54, v55
	v_cvt_pk_bf16_f32 v51, v56, v57
	v_cvt_pk_bf16_f32 v52, v52, v53
	v_cvt_pk_bf16_f32 v53, v60, v61
	s_mov_b32 s18, 0x16000
	global_store_dwordx4 v[62:63], v[50:53], off offset:256
	s_nop 1
	v_add_co_u32_e32 v50, vcc, s18, v162
	s_mov_b32 s18, 0x14000
	s_nop 0
	v_addc_co_u32_e32 v51, vcc, 0, v163, vcc
	v_add_co_u32_e32 v54, vcc, s18, v162
	global_load_dwordx4 v[50:53], v[50:51], off
	s_nop 0
	v_addc_co_u32_e32 v55, vcc, 0, v163, vcc
	v_add_co_u32_e32 v58, vcc, s34, v160
	global_load_dwordx4 v[54:57], v[54:55], off
	s_nop 0
	v_addc_co_u32_e32 v59, vcc, 0, v161, vcc
	global_load_dwordx4 v[58:61], v[58:59], off
	s_mov_b64 s[18:19], 0x90000
	s_waitcnt vmcnt(0)
	v_cvt_f32_ubyte3_e32 v63, v58
	v_cvt_f32_ubyte2_e32 v62, v58
	v_cvt_f32_ubyte1_e32 v65, v58
	v_cvt_f32_ubyte0_e32 v64, v58
	v_cvt_f32_ubyte1_e32 v69, v59
	v_cvt_f32_ubyte0_e32 v68, v59
	v_pk_mul_f32 v[64:65], v[64:65], s[26:27] op_sel_hi:[1,0]
	v_pk_mul_f32 v[62:63], v[62:63], s[26:27] op_sel_hi:[1,0]
	v_cvt_f32_ubyte3_e32 v67, v59
	v_cvt_f32_ubyte2_e32 v66, v59
	v_pk_mul_f32 v[58:59], v[68:69], s[26:27] op_sel_hi:[1,0]
	v_lshlrev_b32_e32 v68, 16, v54
	v_and_b32_e32 v69, 0xffff0000, v54
	v_lshlrev_b32_e32 v54, 16, v55
	v_and_b32_e32 v55, 0xffff0000, v55
	v_pk_mul_f32 v[66:67], v[66:67], s[26:27] op_sel_hi:[1,0]
	v_pk_fma_f32 v[48:49], v[48:49], v[62:63], v[54:55]
	v_pk_fma_f32 v[46:47], v[46:47], v[64:65], v[68:69]
	v_lshlrev_b32_e32 v54, 16, v56
	v_and_b32_e32 v55, 0xffff0000, v56
	v_lshlrev_b32_e32 v56, 16, v57
	v_and_b32_e32 v57, 0xffff0000, v57
	v_pk_fma_f32 v[56:57], v[44:45], v[66:67], v[56:57]
	v_pk_fma_f32 v[44:45], v[42:43], v[58:59], v[54:55]
	v_cvt_pk_bf16_f32 v42, v46, v47
	v_lshl_add_u64 v[46:47], v[122:123], 0, s[18:19]
	s_mov_b32 s18, 0x90000
	v_cvt_pk_bf16_f32 v43, v48, v49
	v_add_co_u32_e32 v48, vcc, s18, v122
	v_cvt_pk_bf16_f32 v44, v44, v45
	v_cvt_pk_bf16_f32 v45, v56, v57
	v_addc_co_u32_e32 v49, vcc, 0, v123, vcc
	global_store_dwordx4 v[48:49], v[42:45], off
	v_cvt_f32_ubyte3_e32 v49, v61
	v_cvt_f32_ubyte2_e32 v48, v61
	v_cvt_f32_ubyte3_e32 v43, v60
	v_cvt_f32_ubyte2_e32 v42, v60
	v_cvt_f32_ubyte1_e32 v45, v60
	v_cvt_f32_ubyte0_e32 v44, v60
	v_pk_mul_f32 v[44:45], v[44:45], s[26:27] op_sel_hi:[1,0]
	v_pk_mul_f32 v[42:43], v[42:43], s[26:27] op_sel_hi:[1,0]
	v_cvt_f32_ubyte1_e32 v55, v61
	v_cvt_f32_ubyte0_e32 v54, v61
	v_lshlrev_b32_e32 v56, 16, v50
	v_and_b32_e32 v57, 0xffff0000, v50
	v_lshlrev_b32_e32 v50, 16, v51
	v_and_b32_e32 v51, 0xffff0000, v51
	v_pk_mul_f32 v[54:55], v[54:55], s[26:27] op_sel_hi:[1,0]
	v_pk_mul_f32 v[48:49], v[48:49], s[26:27] op_sel_hi:[1,0]
	v_pk_fma_f32 v[40:41], v[40:41], v[42:43], v[50:51]
	v_pk_fma_f32 v[38:39], v[38:39], v[44:45], v[56:57]
	v_lshlrev_b32_e32 v42, 16, v52
	v_and_b32_e32 v43, 0xffff0000, v52
	v_lshlrev_b32_e32 v44, 16, v53
	v_and_b32_e32 v45, 0xffff0000, v53
	v_pk_fma_f32 v[44:45], v[36:37], v[48:49], v[44:45]
	v_pk_fma_f32 v[36:37], v[34:35], v[54:55], v[42:43]
	v_cvt_pk_bf16_f32 v34, v38, v39
	v_cvt_pk_bf16_f32 v35, v40, v41
	v_cvt_pk_bf16_f32 v36, v36, v37
	v_cvt_pk_bf16_f32 v37, v44, v45
	s_mov_b32 s18, 0x1a000
	global_store_dwordx4 v[46:47], v[34:37], off offset:256
	s_nop 1
	v_add_co_u32_e32 v34, vcc, s18, v162
	s_mov_b32 s18, 0x18000
	s_nop 0
	v_addc_co_u32_e32 v35, vcc, 0, v163, vcc
	v_add_co_u32_e32 v38, vcc, s18, v162
	global_load_dwordx4 v[34:37], v[34:35], off
	s_nop 0
	v_addc_co_u32_e32 v39, vcc, 0, v163, vcc
	v_add_co_u32_e32 v42, vcc, s36, v160
	global_load_dwordx4 v[38:41], v[38:39], off
	s_nop 0
	v_addc_co_u32_e32 v43, vcc, 0, v161, vcc
	global_load_dwordx4 v[42:45], v[42:43], off
	s_mov_b64 s[18:19], 0xa0000
	s_waitcnt vmcnt(0)
; __device__ __forceinline__ unsigned cvt_pk_bf16(float lo, float hi) { const f32x2c_t v = {lo, hi}; const bf16x2c_t b = __builtin_convertvector(v, bf16x2c_t); return __builtin_bit_cast(unsigned, b); }
;     __device__ __forceinline__ void operator()(const f32x4 (&acc)[2][2][4][2], const Unit& u, int wr, int wc, int fr, int fq) const {
;     ...
; #pragma unroll
;         for (int ai = 0; ai < 2; ++ai)
; #pragma unroll
;             for (int m = 0; m < 4; ++m) { const size_t row = (size_t)(row0 + ai * HALF + m * 16);
;                 const u32x4 gw = gp[(ai * 4 + m) * 512];
;                 u32x4 pw[2];
;                 if (SECOND) { pw[0] = mp[((ai * 4 + m) * 2 + 0) * 512]; pw[1] = mp[((ai * 4 + m) * 2 + 1) * 512]; }
; #pragma unroll
;                 for (int bj = 0; bj < 2; ++bj) { const unsigned gx = bj ? gw.z : gw.x, gy = bj ? gw.w : gw.y;
;                     const f32x4 g0 = (f32x4){(float)(gx & 255u), (float)((gx >> 8) & 255u), (float)((gx >> 16) & 255u), (float)(gx >> 24)} * K255,
;                                 g1 = (f32x4){(float)(gy & 255u), (float)((gy >> 8) & 255u), (float)((gy >> 16) & 255u), (float)(gy >> 24)} * K255;
;                     f32x4 v0 = acc[ai][bj][m][0] * g0, v1 = acc[ai][bj][m][1] * g1;
;                     if (SECOND) { const u32x4 p = pw[bj];
;                         v0 = v0 + (f32x4){bf_lo(p.x), bf_hi(p.x), bf_lo(p.y), bf_hi(p.y)}; v1 = v1 + (f32x4){bf_lo(p.z), bf_hi(p.z), bf_lo(p.w), bf_hi(p.w)}; }
;                     u32x4 w; w.x = cvt_pk_bf16(v0[0], v0[1]); w.y = cvt_pk_bf16(v0[2], v0[3]); w.z = cvt_pk_bf16(v1[0], v1[1]); w.w = cvt_pk_bf16(v1[2], v1[3]);
;                     if (SECOND) *(u32x4*)(MG + row * DM + col0 + bj * HALF) = w; else mp[((ai * 4 + m) * 2 + bj) * 512] = w; }
; template <class Epi, class Sched, bool ALIGN_EPI = false, bool SP2 = false>
; __device__ __forceinline__ void gemm_phase(PG8_LAS unsigned char* lds, const Gemm g, const Sched& S, const Epi& E) {
;     ...
;         if (!has_next) break;
; #pragma unroll
;         for (int a = 0; a < 2; ++a)
; #pragma unroll
;             for (int b = 0; b < 2; ++b)
; #pragma unroll
;                 for (int m = 0; m < 4; ++m)
; #pragma unroll
;                     for (int n = 0; n < 2; ++n) acc[a][b][m][n] = (f32x4){0.f, 0.f, 0.f, 0.f};
;         cur = nxt; cA = nA; cB = nB; ++ui;
;         if constexpr (ALIGN_EPI) { if (wr == 1) PG8_BAR; }
	v_cvt_f32_ubyte3_e32 v47, v42
	v_cvt_f32_ubyte2_e32 v46, v42
	v_cvt_f32_ubyte1_e32 v49, v42
	v_cvt_f32_ubyte0_e32 v48, v42
	v_cvt_f32_ubyte1_e32 v53, v43
	v_cvt_f32_ubyte0_e32 v52, v43
	v_pk_mul_f32 v[48:49], v[48:49], s[26:27] op_sel_hi:[1,0]
	v_pk_mul_f32 v[46:47], v[46:47], s[26:27] op_sel_hi:[1,0]
	v_cvt_f32_ubyte3_e32 v51, v43
	v_cvt_f32_ubyte2_e32 v50, v43
	v_pk_mul_f32 v[42:43], v[52:53], s[26:27] op_sel_hi:[1,0]
	v_lshlrev_b32_e32 v52, 16, v38
	v_and_b32_e32 v53, 0xffff0000, v38
	v_lshlrev_b32_e32 v38, 16, v39
	v_and_b32_e32 v39, 0xffff0000, v39
	v_pk_mul_f32 v[50:51], v[50:51], s[26:27] op_sel_hi:[1,0]
	v_pk_fma_f32 v[32:33], v[32:33], v[46:47], v[38:39]
	v_pk_fma_f32 v[30:31], v[30:31], v[48:49], v[52:53]
	v_lshlrev_b32_e32 v38, 16, v40
	v_and_b32_e32 v39, 0xffff0000, v40
	v_lshlrev_b32_e32 v40, 16, v41
	v_and_b32_e32 v41, 0xffff0000, v41
	v_pk_fma_f32 v[40:41], v[28:29], v[50:51], v[40:41]
	v_pk_fma_f32 v[28:29], v[26:27], v[42:43], v[38:39]
	v_cvt_pk_bf16_f32 v26, v30, v31
	v_lshl_add_u64 v[30:31], v[122:123], 0, s[18:19]
	s_mov_b32 s18, 0xa0000
	v_cvt_pk_bf16_f32 v27, v32, v33
	v_add_co_u32_e32 v32, vcc, s18, v122
	v_cvt_pk_bf16_f32 v28, v28, v29
	v_cvt_pk_bf16_f32 v29, v40, v41
	v_addc_co_u32_e32 v33, vcc, 0, v123, vcc
	global_store_dwordx4 v[32:33], v[26:29], off
	v_cvt_f32_ubyte3_e32 v33, v45
	v_cvt_f32_ubyte2_e32 v32, v45
	v_cvt_f32_ubyte3_e32 v27, v44
	v_cvt_f32_ubyte2_e32 v26, v44
	v_cvt_f32_ubyte1_e32 v29, v44
	v_cvt_f32_ubyte0_e32 v28, v44
	v_pk_mul_f32 v[28:29], v[28:29], s[26:27] op_sel_hi:[1,0]
	v_pk_mul_f32 v[26:27], v[26:27], s[26:27] op_sel_hi:[1,0]
	v_cvt_f32_ubyte1_e32 v39, v45
	v_cvt_f32_ubyte0_e32 v38, v45
	v_lshlrev_b32_e32 v40, 16, v34
	v_and_b32_e32 v41, 0xffff0000, v34
	v_lshlrev_b32_e32 v34, 16, v35
	v_and_b32_e32 v35, 0xffff0000, v35
	v_pk_mul_f32 v[38:39], v[38:39], s[26:27] op_sel_hi:[1,0]
	v_pk_mul_f32 v[32:33], v[32:33], s[26:27] op_sel_hi:[1,0]
	v_pk_fma_f32 v[24:25], v[24:25], v[26:27], v[34:35]
	v_pk_fma_f32 v[22:23], v[22:23], v[28:29], v[40:41]
	v_lshlrev_b32_e32 v26, 16, v36
	v_and_b32_e32 v27, 0xffff0000, v36
	v_lshlrev_b32_e32 v28, 16, v37
	v_and_b32_e32 v29, 0xffff0000, v37
	v_pk_fma_f32 v[28:29], v[20:21], v[32:33], v[28:29]
	v_pk_fma_f32 v[20:21], v[18:19], v[38:39], v[26:27]
	v_cvt_pk_bf16_f32 v18, v22, v23
	v_cvt_pk_bf16_f32 v19, v24, v25
	v_cvt_pk_bf16_f32 v20, v20, v21
	v_cvt_pk_bf16_f32 v21, v28, v29
	s_mov_b32 s18, 0x1e000
	global_store_dwordx4 v[30:31], v[18:21], off offset:256
	s_nop 1
	v_add_co_u32_e32 v18, vcc, s18, v162
	s_mov_b32 s18, 0x1c000
	s_nop 0
	v_addc_co_u32_e32 v19, vcc, 0, v163, vcc
	v_add_co_u32_e32 v22, vcc, s18, v162
	global_load_dwordx4 v[18:21], v[18:19], off
	s_nop 0
	v_addc_co_u32_e32 v23, vcc, 0, v163, vcc
	v_add_co_u32_e32 v26, vcc, s37, v160
	global_load_dwordx4 v[22:25], v[22:23], off
	s_nop 0
	v_addc_co_u32_e32 v27, vcc, 0, v161, vcc
	global_load_dwordx4 v[26:29], v[26:27], off
	s_mov_b64 s[18:19], 0xb0000
	s_waitcnt vmcnt(0)
	v_cvt_f32_ubyte3_e32 v31, v26
	v_cvt_f32_ubyte2_e32 v30, v26
	v_cvt_f32_ubyte1_e32 v37, v27
	v_cvt_f32_ubyte0_e32 v36, v27
	v_cvt_f32_ubyte1_e32 v33, v26
	v_cvt_f32_ubyte0_e32 v32, v26
	v_pk_mul_f32 v[30:31], v[30:31], s[26:27] op_sel_hi:[1,0]
	v_cvt_f32_ubyte3_e32 v35, v27
	v_cvt_f32_ubyte2_e32 v34, v27
	v_pk_mul_f32 v[26:27], v[36:37], s[26:27] op_sel_hi:[1,0]
	v_lshlrev_b32_e32 v36, 16, v22
	v_and_b32_e32 v37, 0xffff0000, v22
	v_lshlrev_b32_e32 v22, 16, v23
	v_and_b32_e32 v23, 0xffff0000, v23
	v_pk_mul_f32 v[32:33], v[32:33], s[26:27] op_sel_hi:[1,0]
	v_pk_fma_f32 v[16:17], v[16:17], v[30:31], v[22:23]
	v_lshlrev_b32_e32 v22, 16, v24
	v_and_b32_e32 v23, 0xffff0000, v24
	v_pk_mul_f32 v[34:35], v[34:35], s[26:27] op_sel_hi:[1,0]
	v_pk_fma_f32 v[14:15], v[14:15], v[32:33], v[36:37]
	v_lshlrev_b32_e32 v24, 16, v25
	v_and_b32_e32 v25, 0xffff0000, v25
	v_pk_fma_f32 v[10:11], v[10:11], v[26:27], v[22:23]
	v_pk_fma_f32 v[24:25], v[12:13], v[34:35], v[24:25]
	v_cvt_pk_bf16_f32 v12, v14, v15
	v_cvt_pk_bf16_f32 v14, v10, v11
	v_lshl_add_u64 v[10:11], v[122:123], 0, s[18:19]
	s_mov_b32 s18, 0xb0000
	v_cvt_pk_bf16_f32 v13, v16, v17
	v_add_co_u32_e32 v16, vcc, s18, v122
	v_cvt_pk_bf16_f32 v15, v24, v25
	s_nop 0
	v_addc_co_u32_e32 v17, vcc, 0, v123, vcc
	global_store_dwordx4 v[16:17], v[12:15], off
	v_cvt_f32_ubyte3_e32 v17, v29
	v_cvt_f32_ubyte2_e32 v16, v29
	v_cvt_f32_ubyte3_e32 v13, v28
	v_cvt_f32_ubyte2_e32 v12, v28
	v_cvt_f32_ubyte1_e32 v15, v28
	v_cvt_f32_ubyte0_e32 v14, v28
	v_pk_mul_f32 v[14:15], v[14:15], s[26:27] op_sel_hi:[1,0]
	v_pk_mul_f32 v[12:13], v[12:13], s[26:27] op_sel_hi:[1,0]
	v_cvt_f32_ubyte1_e32 v23, v29
	v_cvt_f32_ubyte0_e32 v22, v29
	v_lshlrev_b32_e32 v24, 16, v18
	v_and_b32_e32 v25, 0xffff0000, v18
	v_lshlrev_b32_e32 v18, 16, v19
	v_and_b32_e32 v19, 0xffff0000, v19
	v_pk_mul_f32 v[22:23], v[22:23], s[26:27] op_sel_hi:[1,0]
	v_pk_mul_f32 v[16:17], v[16:17], s[26:27] op_sel_hi:[1,0]
	v_pk_fma_f32 v[8:9], v[8:9], v[12:13], v[18:19]
	v_pk_fma_f32 v[6:7], v[6:7], v[14:15], v[24:25]
	v_lshlrev_b32_e32 v12, 16, v20
	v_and_b32_e32 v13, 0xffff0000, v20
	v_lshlrev_b32_e32 v14, 16, v21
	v_and_b32_e32 v15, 0xffff0000, v21
	v_pk_fma_f32 v[14:15], v[4:5], v[16:17], v[14:15]
	v_pk_fma_f32 v[4:5], v[2:3], v[22:23], v[12:13]
	v_cvt_pk_bf16_f32 v2, v6, v7
	v_cvt_pk_bf16_f32 v3, v8, v9
	v_cvt_pk_bf16_f32 v4, v4, v5
	v_cvt_pk_bf16_f32 v5, v14, v15
	global_store_dwordx4 v[10:11], v[2:5], off offset:256
	s_mov_b64 s[18:19], -1
	s_and_b64 vcc, exec, s[40:41]
	s_cbranch_vccnz .LBB0_148
	s_andn2_b64 vcc, exec, s[8:9]
	s_cbranch_vccnz .LBB0_147
	s_barrier
	s_branch .LBB0_147

; #define PG8_STAGE(bufoff, gbase, voff) do { _Pragma("unroll") for (int _i = 0; _i < 2; ++_i) \
;         __builtin_amdgcn_global_load_lds((const unsigned*)((const char*)(gbase) + (voff)[_i]), (PG8_LAS unsigned*)(lds + (bufoff) + ldsw + _i * 8192), 16, 0, 0); } while (0)
; #define PG8_LDA(dst, b, h) do { _Pragma("unroll") for (int m = 0; m < 4; ++m) _Pragma("unroll") for (int k = 0; k < 2; ++k) dst[m][k] = *(const PG8_LAS bf16x8*)(lds + PG8_SA(b, h) + aoff + m * 2048 + k * 1024); } while (0)
; #define PG8_LDB(dst, b, h) do { _Pragma("unroll") for (int n = 0; n < 2; ++n) _Pragma("unroll") for (int k = 0; k < 2; ++k) dst[n][k] = *(const PG8_LAS bf16x8*)(lds + PG8_SB(b, h) + boff + n * 2048 + k * 1024); } while (0)
; #define PG8_MMA(ai, bj, At, Bt) do { __builtin_amdgcn_s_setprio(1); _Pragma("unroll") for (int m = 0; m < 4; ++m) _Pragma("unroll") for (int n = 0; n < 2; ++n) _Pragma("unroll") for (int k = 0; k < 2; ++k) \
;         acc[ai][bj][m][n] = __builtin_amdgcn_mfma_f32_16x16x32_bf16(Bt[n][k], At[m][k], acc[ai][bj][m][n], 0, 0, 0); __builtin_amdgcn_s_setprio(0); } while (0)
; #define PG8_WAIT_V(n) asm volatile("s_waitcnt vmcnt(" #n ")" ::: "memory")
; #define PG8_WAIT_L(n) asm volatile("s_waitcnt lgkmcnt(" #n ")" ::: "memory")
; #define PG8_BAR __builtin_amdgcn_s_barrier()
; #define PG8_SCHED __builtin_amdgcn_sched_barrier(0)
; template <class Epi, class Sched, bool ALIGN_EPI = false, bool SP2 = false>
; __device__ __forceinline__ void gemm_phase(PG8_LAS unsigned char* lds, const Gemm g, const Sched& S, const Epi& E) {
;     ...
;             PG8_LDB(B0, 0, 0); PG8_LDB(B1, 0, 1); PG8_SCHED; PG8_LDA(At, 0, 0); PG8_STAGE(PG8_SA(1, 1), a1 + hstep, voffA);
;             PG8_WAIT_V(8); PG8_WAIT_L(0); PG8_BAR; PG8_MMA(0, 0, At, B0); PG8_MMA(0, 1, At, B1); PG8_BAR; PG8_SCHED;
;             PG8_LDA(At, 0, 1); PG8_STAGE(PG8_SB(0, 0), b2, voffB); PG8_STAGE(PG8_SB(0, 1), b2 + hstep, voffB); PG8_STAGE(PG8_SA(0, 0), a2, voffA);
;             PG8_WAIT_V(8); PG8_WAIT_L(0); PG8_BAR; PG8_MMA(1, 0, At, B0); PG8_MMA(1, 1, At, B1); PG8_BAR; PG8_SCHED;
.Lpw11_j:
	s_nop 0
	s_nop 0
	s_waitcnt lgkmcnt(0)
	s_setprio 1
	s_barrier
	v_mfma_f32_16x16x32_bf16 v[126:129], v[156:159], v[208:211], 0
	v_mfma_f32_16x16x32_bf16 v[122:125], v[168:171], v[208:211], 0
	v_mfma_f32_16x16x32_bf16 v[110:113], v[156:159], v[216:219], 0
	v_mfma_f32_16x16x32_bf16 v[106:109], v[168:171], v[216:219], 0
	v_mfma_f32_16x16x32_bf16 v[94:97], v[156:159], v[224:227], 0
	v_mfma_f32_16x16x32_bf16 v[90:93], v[168:171], v[224:227], 0
	v_mfma_f32_16x16x32_bf16 v[78:81], v[156:159], v[232:235], 0
	v_mfma_f32_16x16x32_bf16 v[74:77], v[168:171], v[232:235], 0
	s_setprio 0
	s_setprio 1
	v_mfma_f32_16x16x32_bf16 v[126:129], v[164:167], v[212:215], v[126:129]
	v_mfma_f32_16x16x32_bf16 v[122:125], v[172:175], v[212:215], v[122:125]
	v_mfma_f32_16x16x32_bf16 v[110:113], v[164:167], v[220:223], v[110:113]
	v_mfma_f32_16x16x32_bf16 v[106:109], v[172:175], v[220:223], v[106:109]
	v_mfma_f32_16x16x32_bf16 v[94:97], v[164:167], v[228:231], v[94:97]
	v_mfma_f32_16x16x32_bf16 v[90:93], v[172:175], v[228:231], v[90:93]
	v_mfma_f32_16x16x32_bf16 v[78:81], v[164:167], v[236:239], v[78:81]
	v_mfma_f32_16x16x32_bf16 v[74:77], v[172:175], v[236:239], v[74:77]
	s_setprio 0
	s_setprio 1
	v_mfma_f32_16x16x32_bf16 v[118:121], v[176:179], v[208:211], 0
	v_mfma_f32_16x16x32_bf16 v[114:117], v[184:187], v[208:211], 0
	v_mfma_f32_16x16x32_bf16 v[102:105], v[176:179], v[216:219], 0
	v_mfma_f32_16x16x32_bf16 v[98:101], v[184:187], v[216:219], 0
	v_mfma_f32_16x16x32_bf16 v[86:89], v[176:179], v[224:227], 0
	v_mfma_f32_16x16x32_bf16 v[82:85], v[184:187], v[224:227], 0
	v_mfma_f32_16x16x32_bf16 v[70:73], v[176:179], v[232:235], 0
	v_mfma_f32_16x16x32_bf16 v[66:69], v[184:187], v[232:235], 0
	s_setprio 0
	s_setprio 1
	v_mfma_f32_16x16x32_bf16 v[118:121], v[180:183], v[212:215], v[118:121]
	v_mfma_f32_16x16x32_bf16 v[114:117], v[204:207], v[212:215], v[114:117]
	v_mfma_f32_16x16x32_bf16 v[102:105], v[180:183], v[220:223], v[102:105]
	v_mfma_f32_16x16x32_bf16 v[98:101], v[204:207], v[220:223], v[98:101]
	v_mfma_f32_16x16x32_bf16 v[86:89], v[180:183], v[228:231], v[86:89]
	v_mfma_f32_16x16x32_bf16 v[82:85], v[204:207], v[228:231], v[82:85]
	v_mfma_f32_16x16x32_bf16 v[70:73], v[180:183], v[236:239], v[70:73]
	v_mfma_f32_16x16x32_bf16 v[66:69], v[204:207], v[236:239], v[66:69]
	s_setprio 0
	s_barrier
	s_add_i32 s73, s73, s28
	v_lshl_add_u64 v[240:241], s[18:19], 0, v[146:147]
	s_mov_b32 m0, s73
	ds_read_b128 v[208:211], v162 offset:16384
	ds_read_b128 v[212:215], v162 offset:17408
	ds_read_b128 v[216:219], v162 offset:18432
	ds_read_b128 v[220:223], v162 offset:19456
	ds_read_b128 v[224:227], v162 offset:20480
	ds_read_b128 v[228:231], v162 offset:21504
	ds_read_b128 v[232:235], v162 offset:22528
	ds_read_b128 v[236:239], v162 offset:23552
	global_load_lds_dwordx4 v[240:241], off
	s_add_i32 m0, s73, 0x2000
	s_add_u32 s78, s18, 0x80000
	v_lshl_add_u64 v[242:243], s[18:19], 0, v[142:143]
	s_addc_u32 s79, s19, 0
	s_add_i32 s73, s76, s28
	global_load_lds_dwordx4 v[242:243], off
	v_lshl_add_u64 v[244:245], s[78:79], 0, v[146:147]
	s_mov_b32 m0, s73
	v_lshl_add_u64 v[246:247], s[42:43], 0, v[144:145]
	global_load_lds_dwordx4 v[244:245], off
	v_lshl_add_u64 v[244:245], s[78:79], 0, v[142:143]
	s_add_i32 m0, s73, 0x2000
	s_nop 0
	global_load_lds_dwordx4 v[244:245], off
	v_lshl_add_u64 v[244:245], s[42:43], 0, v[148:149]
	s_mov_b32 m0, s30
	s_nop 0
	global_load_lds_dwordx4 v[244:245], off
	s_mov_b32 m0, s34
	s_nop 0
	global_load_lds_dwordx4 v[246:247], off
	s_cmp_eq_u32 s32, 0
	s_cbranch_scc1 .Lpw12_f
	s_waitcnt vmcnt(16)
	s_branch .Lpw12_j

; #define PG8_STAGE(bufoff, gbase, voff) do { _Pragma("unroll") for (int _i = 0; _i < 2; ++_i) \
;         __builtin_amdgcn_global_load_lds((const unsigned*)((const char*)(gbase) + (voff)[_i]), (PG8_LAS unsigned*)(lds + (bufoff) + ldsw + _i * 8192), 16, 0, 0); } while (0)
; #define PG8_LDA(dst, b, h) do { _Pragma("unroll") for (int m = 0; m < 4; ++m) _Pragma("unroll") for (int k = 0; k < 2; ++k) dst[m][k] = *(const PG8_LAS bf16x8*)(lds + PG8_SA(b, h) + aoff + m * 2048 + k * 1024); } while (0)
; #define PG8_LDB(dst, b, h) do { _Pragma("unroll") for (int n = 0; n < 2; ++n) _Pragma("unroll") for (int k = 0; k < 2; ++k) dst[n][k] = *(const PG8_LAS bf16x8*)(lds + PG8_SB(b, h) + boff + n * 2048 + k * 1024); } while (0)
; #define PG8_MMA(ai, bj, At, Bt) do { __builtin_amdgcn_s_setprio(1); _Pragma("unroll") for (int m = 0; m < 4; ++m) _Pragma("unroll") for (int n = 0; n < 2; ++n) _Pragma("unroll") for (int k = 0; k < 2; ++k) \
;         acc[ai][bj][m][n] = __builtin_amdgcn_mfma_f32_16x16x32_bf16(Bt[n][k], At[m][k], acc[ai][bj][m][n], 0, 0, 0); __builtin_amdgcn_s_setprio(0); } while (0)
; #define PG8_WAIT_V(n) asm volatile("s_waitcnt vmcnt(" #n ")" ::: "memory")
; template <class Epi, class Sched, bool ALIGN_EPI = false, bool SP2 = false>
; __device__ __forceinline__ void gemm_phase(PG8_LAS unsigned char* lds, const Gemm g, const Sched& S, const Epi& E) {
;     ...
;             PG8_LDB(B0, 0, 0); PG8_LDB(B1, 0, 1); PG8_SCHED; PG8_LDA(At, 0, 0); PG8_STAGE(PG8_SA(1, 1), a1 + hstep, voffA);
;             PG8_WAIT_V(8); PG8_WAIT_L(0); PG8_BAR; PG8_MMA(0, 0, At, B0); PG8_MMA(0, 1, At, B1); PG8_BAR; PG8_SCHED;
;             PG8_LDA(At, 0, 1); PG8_STAGE(PG8_SB(0, 0), b2, voffB); PG8_STAGE(PG8_SB(0, 1), b2 + hstep, voffB); PG8_STAGE(PG8_SA(0, 0), a2, voffA);
;             PG8_WAIT_V(8); PG8_WAIT_L(0); PG8_BAR; PG8_MMA(1, 0, At, B0); PG8_MMA(1, 1, At, B1); PG8_BAR; PG8_SCHED;
;             PG8_LDB(B0, 1, 0); PG8_LDB(B1, 1, 1); PG8_SCHED; PG8_LDA(At, 1, 0); PG8_STAGE(PG8_SA(0, 1), a2 + hstep, voffA);
;             PG8_WAIT_V(8); PG8_WAIT_L(0); PG8_BAR; PG8_MMA(0, 0, At, B0); PG8_MMA(0, 1, At, B1); PG8_BAR; PG8_SCHED;
;             PG8_LDA(At, 1, 1); PG8_STAGE(PG8_SB(1, 0), b3, voffB); PG8_STAGE(PG8_SB(1, 1), b3 + hstep, voffB); PG8_STAGE(PG8_SA(1, 0), a3, voffA);
;             PG8_WAIT_V(8); PG8_WAIT_L(0); PG8_BAR; PG8_MMA(1, 0, At, B0); PG8_MMA(1, 1, At, B1); PG8_BAR; PG8_SCHED;
.LBB0_281:
	s_add_u32 s18, s36, 0xfff80080
	s_addc_u32 s19, s37, -1
	s_add_i32 s73, 0, 0x10000
	s_cmp_eq_u32 s67, 28
	s_cselect_b32 s43, s9, s19
	s_cselect_b32 s42, s59, s18
	v_add_u32_e32 v163, s73, v160
	s_cselect_b32 s19, s7, s63
	s_cselect_b32 s18, s60, s62
	s_add_i32 s76, 0, 0x14000
	ds_read_b128 v[156:159], v163
	ds_read_b128 v[164:167], v163 offset:1024
	ds_read_b128 v[168:171], v163 offset:2048
	ds_read_b128 v[172:175], v163 offset:3072
	v_add_u32_e32 v163, s76, v160
	ds_read_b128 v[176:179], v163
	ds_read_b128 v[180:183], v163 offset:1024
	ds_read_b128 v[184:187], v163 offset:2048
	ds_read_b128 v[204:207], v163 offset:3072
	v_lshl_add_u64 v[240:241], s[36:37], 0, v[152:153]
	s_add_i32 m0, s30, 0xc000
	ds_read_b128 v[208:211], v162
	ds_read_b128 v[212:215], v162 offset:1024
	ds_read_b128 v[216:219], v162 offset:2048
	ds_read_b128 v[220:223], v162 offset:3072
	ds_read_b128 v[224:227], v162 offset:4096
	ds_read_b128 v[228:231], v162 offset:5120
	ds_read_b128 v[232:235], v162 offset:6144
	ds_read_b128 v[236:239], v162 offset:7168
	global_load_lds_dwordx4 v[240:241], off
	v_lshl_add_u64 v[240:241], s[36:37], 0, v[154:155]
	s_add_i32 m0, s30, 0xe000
	s_nop 0
	global_load_lds_dwordx4 v[240:241], off
	s_nop 0
	s_nop 0
	s_nop 0
	s_waitcnt vmcnt(8)
	s_waitcnt lgkmcnt(0)
	s_setprio 1
	s_barrier
	v_mfma_f32_16x16x32_bf16 v[126:129], v[156:159], v[208:211], v[126:129]
	v_mfma_f32_16x16x32_bf16 v[122:125], v[168:171], v[208:211], v[122:125]
	v_mfma_f32_16x16x32_bf16 v[110:113], v[156:159], v[216:219], v[110:113]
	v_mfma_f32_16x16x32_bf16 v[106:109], v[168:171], v[216:219], v[106:109]
	v_mfma_f32_16x16x32_bf16 v[94:97], v[156:159], v[224:227], v[94:97]
	v_mfma_f32_16x16x32_bf16 v[90:93], v[168:171], v[224:227], v[90:93]
	v_mfma_f32_16x16x32_bf16 v[78:81], v[156:159], v[232:235], v[78:81]
	v_mfma_f32_16x16x32_bf16 v[74:77], v[168:171], v[232:235], v[74:77]
	s_setprio 0
	s_setprio 1
	v_mfma_f32_16x16x32_bf16 v[126:129], v[164:167], v[212:215], v[126:129]
	v_mfma_f32_16x16x32_bf16 v[122:125], v[172:175], v[212:215], v[122:125]
	v_mfma_f32_16x16x32_bf16 v[110:113], v[164:167], v[220:223], v[110:113]
	v_mfma_f32_16x16x32_bf16 v[106:109], v[172:175], v[220:223], v[106:109]
	v_mfma_f32_16x16x32_bf16 v[94:97], v[164:167], v[228:231], v[94:97]
	v_mfma_f32_16x16x32_bf16 v[90:93], v[172:175], v[228:231], v[90:93]
	v_mfma_f32_16x16x32_bf16 v[78:81], v[164:167], v[236:239], v[78:81]
	v_mfma_f32_16x16x32_bf16 v[74:77], v[172:175], v[236:239], v[74:77]
	s_setprio 0
	s_setprio 1
	v_mfma_f32_16x16x32_bf16 v[118:121], v[176:179], v[208:211], v[118:121]
	v_mfma_f32_16x16x32_bf16 v[114:117], v[184:187], v[208:211], v[114:117]
	v_mfma_f32_16x16x32_bf16 v[102:105], v[176:179], v[216:219], v[102:105]
	v_mfma_f32_16x16x32_bf16 v[98:101], v[184:187], v[216:219], v[98:101]
	v_mfma_f32_16x16x32_bf16 v[86:89], v[176:179], v[224:227], v[86:89]
	v_mfma_f32_16x16x32_bf16 v[82:85], v[184:187], v[224:227], v[82:85]
	v_mfma_f32_16x16x32_bf16 v[70:73], v[176:179], v[232:235], v[70:73]
	v_mfma_f32_16x16x32_bf16 v[66:69], v[184:187], v[232:235], v[66:69]
	s_setprio 0
	s_setprio 1
	v_mfma_f32_16x16x32_bf16 v[118:121], v[180:183], v[212:215], v[118:121]
	v_mfma_f32_16x16x32_bf16 v[114:117], v[204:207], v[212:215], v[114:117]
	v_mfma_f32_16x16x32_bf16 v[102:105], v[180:183], v[220:223], v[102:105]
	v_mfma_f32_16x16x32_bf16 v[98:101], v[204:207], v[220:223], v[98:101]
	v_mfma_f32_16x16x32_bf16 v[86:89], v[180:183], v[228:231], v[86:89]
	v_mfma_f32_16x16x32_bf16 v[82:85], v[204:207], v[228:231], v[82:85]
	v_mfma_f32_16x16x32_bf16 v[70:73], v[180:183], v[236:239], v[70:73]
	v_mfma_f32_16x16x32_bf16 v[66:69], v[204:207], v[236:239], v[66:69]
	s_setprio 0
	s_barrier
	s_add_i32 s73, s73, s28
	v_lshl_add_u64 v[240:241], s[18:19], 0, v[146:147]
	s_mov_b32 m0, s73
	ds_read_b128 v[208:211], v162 offset:16384
	ds_read_b128 v[212:215], v162 offset:17408
	ds_read_b128 v[216:219], v162 offset:18432
	ds_read_b128 v[220:223], v162 offset:19456
	ds_read_b128 v[224:227], v162 offset:20480
	ds_read_b128 v[228:231], v162 offset:21504
	ds_read_b128 v[232:235], v162 offset:22528
	ds_read_b128 v[236:239], v162 offset:23552
	global_load_lds_dwordx4 v[240:241], off
	s_add_i32 m0, s73, 0x2000
	s_add_u32 s78, s18, 0x80000
	v_lshl_add_u64 v[242:243], s[18:19], 0, v[142:143]
	s_addc_u32 s79, s19, 0
	s_add_i32 s73, s76, s28
	global_load_lds_dwordx4 v[242:243], off
	v_lshl_add_u64 v[244:245], s[78:79], 0, v[146:147]
	s_mov_b32 m0, s73
	v_lshl_add_u64 v[246:247], s[42:43], 0, v[144:145]
	global_load_lds_dwordx4 v[244:245], off
	v_lshl_add_u64 v[244:245], s[78:79], 0, v[142:143]
	s_add_i32 m0, s73, 0x2000
	s_nop 0
	global_load_lds_dwordx4 v[244:245], off
	v_lshl_add_u64 v[244:245], s[42:43], 0, v[148:149]
	s_mov_b32 m0, s30
	s_nop 0
	global_load_lds_dwordx4 v[244:245], off
	s_mov_b32 m0, s34
	s_nop 0
	global_load_lds_dwordx4 v[246:247], off
	s_waitcnt vmcnt(8)
	s_waitcnt lgkmcnt(0)
	s_setprio 1
	s_barrier
; #define PG8_STAGE(bufoff, gbase, voff) do { _Pragma("unroll") for (int _i = 0; _i < 2; ++_i) \
;         __builtin_amdgcn_global_load_lds((const unsigned*)((const char*)(gbase) + (voff)[_i]), (PG8_LAS unsigned*)(lds + (bufoff) + ldsw + _i * 8192), 16, 0, 0); } while (0)
; #define PG8_LDA(dst, b, h) do { _Pragma("unroll") for (int m = 0; m < 4; ++m) _Pragma("unroll") for (int k = 0; k < 2; ++k) dst[m][k] = *(const PG8_LAS bf16x8*)(lds + PG8_SA(b, h) + aoff + m * 2048 + k * 1024); } while (0)
; #define PG8_LDB(dst, b, h) do { _Pragma("unroll") for (int n = 0; n < 2; ++n) _Pragma("unroll") for (int k = 0; k < 2; ++k) dst[n][k] = *(const PG8_LAS bf16x8*)(lds + PG8_SB(b, h) + boff + n * 2048 + k * 1024); } while (0)
; #define PG8_MMA(ai, bj, At, Bt) do { __builtin_amdgcn_s_setprio(1); _Pragma("unroll") for (int m = 0; m < 4; ++m) _Pragma("unroll") for (int n = 0; n < 2; ++n) _Pragma("unroll") for (int k = 0; k < 2; ++k) \
;         acc[ai][bj][m][n] = __builtin_amdgcn_mfma_f32_16x16x32_bf16(Bt[n][k], At[m][k], acc[ai][bj][m][n], 0, 0, 0); __builtin_amdgcn_s_setprio(0); } while (0)
; #define PG8_WAIT_V(n) asm volatile("s_waitcnt vmcnt(" #n ")" ::: "memory")
; template <class Epi, class Sched, bool ALIGN_EPI = false, bool SP2 = false>
; __device__ __forceinline__ void gemm_phase(PG8_LAS unsigned char* lds, const Gemm g, const Sched& S, const Epi& E) {
;     ...
;             PG8_LDB(B0, 0, 0); PG8_LDB(B1, 0, 1); PG8_SCHED; PG8_LDA(At, 0, 0); PG8_STAGE(PG8_SA(1, 1), a1 + hstep, voffA);
;             PG8_WAIT_V(8); PG8_WAIT_L(0); PG8_BAR; PG8_MMA(0, 0, At, B0); PG8_MMA(0, 1, At, B1); PG8_BAR; PG8_SCHED;
;             PG8_LDA(At, 0, 1); PG8_STAGE(PG8_SB(0, 0), b2, voffB); PG8_STAGE(PG8_SB(0, 1), b2 + hstep, voffB); PG8_STAGE(PG8_SA(0, 0), a2, voffA);
;             PG8_WAIT_V(8); PG8_WAIT_L(0); PG8_BAR; PG8_MMA(1, 0, At, B0); PG8_MMA(1, 1, At, B1); PG8_BAR; PG8_SCHED;
;             PG8_LDB(B0, 1, 0); PG8_LDB(B1, 1, 1); PG8_SCHED; PG8_LDA(At, 1, 0); PG8_STAGE(PG8_SA(0, 1), a2 + hstep, voffA);
;             PG8_WAIT_V(8); PG8_WAIT_L(0); PG8_BAR; PG8_MMA(0, 0, At, B0); PG8_MMA(0, 1, At, B1); PG8_BAR; PG8_SCHED;
;             PG8_LDA(At, 1, 1); PG8_STAGE(PG8_SB(1, 0), b3, voffB); PG8_STAGE(PG8_SB(1, 1), b3 + hstep, voffB); PG8_STAGE(PG8_SA(1, 0), a3, voffA);
;             PG8_WAIT_V(8); PG8_WAIT_L(0); PG8_BAR; PG8_MMA(1, 0, At, B0); PG8_MMA(1, 1, At, B1); PG8_BAR; PG8_SCHED;
	v_mfma_f32_16x16x32_bf16 v[62:65], v[156:159], v[208:211], v[62:65]
	v_mfma_f32_16x16x32_bf16 v[58:61], v[168:171], v[208:211], v[58:61]
	v_mfma_f32_16x16x32_bf16 v[46:49], v[156:159], v[216:219], v[46:49]
	v_mfma_f32_16x16x32_bf16 v[42:45], v[168:171], v[216:219], v[42:45]
	v_mfma_f32_16x16x32_bf16 v[30:33], v[156:159], v[224:227], v[30:33]
	v_mfma_f32_16x16x32_bf16 v[26:29], v[168:171], v[224:227], v[26:29]
	v_mfma_f32_16x16x32_bf16 v[14:17], v[156:159], v[232:235], v[14:17]
	v_mfma_f32_16x16x32_bf16 v[10:13], v[168:171], v[232:235], v[10:13]
	v_mfma_f32_16x16x32_bf16 v[62:65], v[164:167], v[212:215], v[62:65]
	v_mfma_f32_16x16x32_bf16 v[58:61], v[172:175], v[212:215], v[58:61]
	v_mfma_f32_16x16x32_bf16 v[46:49], v[164:167], v[220:223], v[46:49]
	v_mfma_f32_16x16x32_bf16 v[42:45], v[172:175], v[220:223], v[42:45]
	v_mfma_f32_16x16x32_bf16 v[30:33], v[164:167], v[228:231], v[30:33]
	v_mfma_f32_16x16x32_bf16 v[26:29], v[172:175], v[228:231], v[26:29]
	v_mfma_f32_16x16x32_bf16 v[14:17], v[164:167], v[236:239], v[14:17]
	v_mfma_f32_16x16x32_bf16 v[10:13], v[172:175], v[236:239], v[10:13]
	v_mfma_f32_16x16x32_bf16 v[54:57], v[176:179], v[208:211], v[54:57]
	v_mfma_f32_16x16x32_bf16 v[50:53], v[184:187], v[208:211], v[50:53]
	v_mfma_f32_16x16x32_bf16 v[38:41], v[176:179], v[216:219], v[38:41]
	v_mfma_f32_16x16x32_bf16 v[34:37], v[184:187], v[216:219], v[34:37]
	v_mfma_f32_16x16x32_bf16 v[22:25], v[176:179], v[224:227], v[22:25]
	v_mfma_f32_16x16x32_bf16 v[18:21], v[184:187], v[224:227], v[18:21]
	v_mfma_f32_16x16x32_bf16 v[6:9], v[176:179], v[232:235], v[6:9]
	v_mfma_f32_16x16x32_bf16 v[2:5], v[184:187], v[232:235], v[2:5]
	v_mfma_f32_16x16x32_bf16 v[54:57], v[180:183], v[212:215], v[54:57]
	v_mfma_f32_16x16x32_bf16 v[50:53], v[204:207], v[212:215], v[50:53]
	v_mfma_f32_16x16x32_bf16 v[38:41], v[180:183], v[220:223], v[38:41]
	v_mfma_f32_16x16x32_bf16 v[34:37], v[204:207], v[220:223], v[34:37]
	v_mfma_f32_16x16x32_bf16 v[22:25], v[180:183], v[228:231], v[22:25]
	v_mfma_f32_16x16x32_bf16 v[18:21], v[204:207], v[228:231], v[18:21]
	v_mfma_f32_16x16x32_bf16 v[6:9], v[180:183], v[236:239], v[6:9]
	v_mfma_f32_16x16x32_bf16 v[2:5], v[204:207], v[236:239], v[2:5]
	s_setprio 0
	s_barrier
	s_add_i32 s73, 0, 0x18000
	v_add_u32_e32 v163, s73, v160
	s_add_i32 s76, 0, 0x1c000
	ds_read_b128 v[156:159], v163
	ds_read_b128 v[164:167], v163 offset:1024
	ds_read_b128 v[168:171], v163 offset:2048
	ds_read_b128 v[172:175], v163 offset:3072
	v_add_u32_e32 v163, s76, v160
	ds_read_b128 v[176:179], v163
	ds_read_b128 v[180:183], v163 offset:1024
	ds_read_b128 v[184:187], v163 offset:2048
	ds_read_b128 v[204:207], v163 offset:3072
	s_add_u32 s42, s42, 0x80000
	s_addc_u32 s43, s43, 0
	s_mov_b32 m0, s44
	v_lshl_add_u64 v[248:249], s[42:43], 0, v[148:149]
	ds_read_b128 v[208:211], v162 offset:32768
	ds_read_b128 v[212:215], v162 offset:33792
	ds_read_b128 v[216:219], v162 offset:34816
	ds_read_b128 v[220:223], v162 offset:35840
	ds_read_b128 v[224:227], v162 offset:36864
	ds_read_b128 v[228:231], v162 offset:37888
	ds_read_b128 v[232:235], v162 offset:38912
	ds_read_b128 v[236:239], v162 offset:39936
	global_load_lds_dwordx4 v[248:249], off
	v_lshl_add_u64 v[248:249], s[42:43], 0, v[144:145]
	s_mov_b32 m0, s45
	s_nop 0
	global_load_lds_dwordx4 v[248:249], off
	s_waitcnt vmcnt(8)
	s_waitcnt lgkmcnt(0)
	s_setprio 1
	s_barrier
	v_mfma_f32_16x16x32_bf16 v[126:129], v[156:159], v[208:211], v[126:129]
	v_mfma_f32_16x16x32_bf16 v[122:125], v[168:171], v[208:211], v[122:125]
	v_mfma_f32_16x16x32_bf16 v[110:113], v[156:159], v[216:219], v[110:113]
	v_mfma_f32_16x16x32_bf16 v[106:109], v[168:171], v[216:219], v[106:109]
	v_mfma_f32_16x16x32_bf16 v[94:97], v[156:159], v[224:227], v[94:97]
	v_mfma_f32_16x16x32_bf16 v[90:93], v[168:171], v[224:227], v[90:93]
	v_mfma_f32_16x16x32_bf16 v[78:81], v[156:159], v[232:235], v[78:81]
	v_mfma_f32_16x16x32_bf16 v[74:77], v[168:171], v[232:235], v[74:77]
	s_setprio 0
	s_setprio 1
	v_mfma_f32_16x16x32_bf16 v[126:129], v[164:167], v[212:215], v[126:129]
	v_mfma_f32_16x16x32_bf16 v[122:125], v[172:175], v[212:215], v[122:125]
	v_mfma_f32_16x16x32_bf16 v[110:113], v[164:167], v[220:223], v[110:113]
	v_mfma_f32_16x16x32_bf16 v[106:109], v[172:175], v[220:223], v[106:109]
	v_mfma_f32_16x16x32_bf16 v[94:97], v[164:167], v[228:231], v[94:97]
	v_mfma_f32_16x16x32_bf16 v[90:93], v[172:175], v[228:231], v[90:93]
	v_mfma_f32_16x16x32_bf16 v[78:81], v[164:167], v[236:239], v[78:81]
	v_mfma_f32_16x16x32_bf16 v[74:77], v[172:175], v[236:239], v[74:77]
	s_setprio 0
	s_setprio 1
	v_mfma_f32_16x16x32_bf16 v[118:121], v[176:179], v[208:211], v[118:121]
	v_mfma_f32_16x16x32_bf16 v[114:117], v[184:187], v[208:211], v[114:117]
	v_mfma_f32_16x16x32_bf16 v[102:105], v[176:179], v[216:219], v[102:105]
	v_mfma_f32_16x16x32_bf16 v[98:101], v[184:187], v[216:219], v[98:101]
	v_mfma_f32_16x16x32_bf16 v[86:89], v[176:179], v[224:227], v[86:89]
	v_mfma_f32_16x16x32_bf16 v[82:85], v[184:187], v[224:227], v[82:85]
	v_mfma_f32_16x16x32_bf16 v[70:73], v[176:179], v[232:235], v[70:73]
	v_mfma_f32_16x16x32_bf16 v[66:69], v[184:187], v[232:235], v[66:69]
	s_setprio 0
	s_setprio 1
	v_mfma_f32_16x16x32_bf16 v[118:121], v[180:183], v[212:215], v[118:121]
	v_mfma_f32_16x16x32_bf16 v[114:117], v[204:207], v[212:215], v[114:117]
	v_mfma_f32_16x16x32_bf16 v[102:105], v[180:183], v[220:223], v[102:105]
	v_mfma_f32_16x16x32_bf16 v[98:101], v[204:207], v[220:223], v[98:101]
	v_mfma_f32_16x16x32_bf16 v[86:89], v[180:183], v[228:231], v[86:89]
	v_mfma_f32_16x16x32_bf16 v[82:85], v[204:207], v[228:231], v[82:85]
	v_mfma_f32_16x16x32_bf16 v[70:73], v[180:183], v[236:239], v[70:73]
	v_mfma_f32_16x16x32_bf16 v[66:69], v[204:207], v[236:239], v[66:69]
	s_setprio 0
	s_barrier
; #define PG8_STAGE(bufoff, gbase, voff) do { _Pragma("unroll") for (int _i = 0; _i < 2; ++_i) \
;         __builtin_amdgcn_global_load_lds((const unsigned*)((const char*)(gbase) + (voff)[_i]), (PG8_LAS unsigned*)(lds + (bufoff) + ldsw + _i * 8192), 16, 0, 0); } while (0)
; #define PG8_LDA(dst, b, h) do { _Pragma("unroll") for (int m = 0; m < 4; ++m) _Pragma("unroll") for (int k = 0; k < 2; ++k) dst[m][k] = *(const PG8_LAS bf16x8*)(lds + PG8_SA(b, h) + aoff + m * 2048 + k * 1024); } while (0)
; #define PG8_MMA(ai, bj, At, Bt) do { __builtin_amdgcn_s_setprio(1); _Pragma("unroll") for (int m = 0; m < 4; ++m) _Pragma("unroll") for (int n = 0; n < 2; ++n) _Pragma("unroll") for (int k = 0; k < 2; ++k) \
;         acc[ai][bj][m][n] = __builtin_amdgcn_mfma_f32_16x16x32_bf16(Bt[n][k], At[m][k], acc[ai][bj][m][n], 0, 0, 0); __builtin_amdgcn_s_setprio(0); } while (0)
; #define PG8_WAIT_V(n) asm volatile("s_waitcnt vmcnt(" #n ")" ::: "memory")
; #define PG8_WAIT_L(n) asm volatile("s_waitcnt lgkmcnt(" #n ")" ::: "memory")
; #define PG8_BAR __builtin_amdgcn_s_barrier()
; #define PG8_SCHED __builtin_amdgcn_sched_barrier(0)
;     __device__ __forceinline__ void operator()(const f32x4 (&acc)[2][2][4][2], const Unit& u, int wr, int wc, int fr, int fq) const {
;     ...
;         if (u.pn >= 30) {
; template <class Epi, class Sched, bool ALIGN_EPI = false, bool SP2 = false>
; __device__ __forceinline__ void gemm_phase(PG8_LAS unsigned char* lds, const Gemm g, const Sched& S, const Epi& E) {
;     ...
;             PG8_WAIT_V(8); PG8_WAIT_L(0); PG8_BAR; PG8_MMA(0, 0, At, B0); PG8_MMA(0, 1, At, B1); PG8_BAR; PG8_SCHED;
;             PG8_LDA(At, 1, 1); PG8_STAGE(PG8_SB(1, 0), b3, voffB); PG8_STAGE(PG8_SB(1, 1), b3 + hstep, voffB); PG8_STAGE(PG8_SA(1, 0), a3, voffA);
;             PG8_WAIT_V(8); PG8_WAIT_L(0); PG8_BAR; PG8_MMA(1, 0, At, B0); PG8_MMA(1, 1, At, B1); PG8_BAR; PG8_SCHED;
;     ...
;         if constexpr (ALIGN_EPI) { if (wr == 0) PG8_BAR; }
;         if constexpr (!Epi::AFTER_DRAIN) { E(acc, cur, wr, wc, fr, fq); S.done(cur); }
	s_add_i32 s42, s73, s28
	v_lshl_add_u64 v[240:241], v[240:241], 0, s[68:69]
	s_mov_b32 m0, s42
	ds_read_b128 v[208:211], v162 offset:49152
	ds_read_b128 v[212:215], v162 offset:50176
	ds_read_b128 v[216:219], v162 offset:51200
	ds_read_b128 v[220:223], v162 offset:52224
	ds_read_b128 v[224:227], v162 offset:53248
	ds_read_b128 v[228:231], v162 offset:54272
	ds_read_b128 v[232:235], v162 offset:55296
	ds_read_b128 v[236:239], v162 offset:56320
	global_load_lds_dwordx4 v[240:241], off
	s_add_i32 m0, s42, 0x2000
	s_add_u32 s18, s18, 0x80080
	v_lshl_add_u64 v[240:241], v[242:243], 0, s[68:69]
	s_addc_u32 s19, s19, 0
	s_add_i32 s42, s76, s28
	global_load_lds_dwordx4 v[240:241], off
	v_lshl_add_u64 v[240:241], s[18:19], 0, v[146:147]
	s_mov_b32 m0, s42
	s_nop 0
	global_load_lds_dwordx4 v[240:241], off
	v_lshl_add_u64 v[240:241], s[18:19], 0, v[142:143]
	s_add_i32 m0, s42, 0x2000
	s_nop 0
	global_load_lds_dwordx4 v[240:241], off
	v_lshl_add_u64 v[240:241], v[244:245], 0, s[68:69]
	s_mov_b32 m0, s46
	s_nop 0
	global_load_lds_dwordx4 v[240:241], off
	v_lshl_add_u64 v[240:241], v[246:247], 0, s[68:69]
	s_mov_b32 m0, s47
	s_nop 0
	global_load_lds_dwordx4 v[240:241], off
	s_nop 0
	s_waitcnt vmcnt(8)
	s_waitcnt lgkmcnt(0)
	s_setprio 1
	s_barrier
	v_mfma_f32_16x16x32_bf16 v[62:65], v[156:159], v[208:211], v[62:65]
	v_mfma_f32_16x16x32_bf16 v[58:61], v[168:171], v[208:211], v[58:61]
	v_mfma_f32_16x16x32_bf16 v[46:49], v[156:159], v[216:219], v[46:49]
	v_mfma_f32_16x16x32_bf16 v[42:45], v[168:171], v[216:219], v[42:45]
	v_mfma_f32_16x16x32_bf16 v[30:33], v[156:159], v[224:227], v[30:33]
	v_mfma_f32_16x16x32_bf16 v[26:29], v[168:171], v[224:227], v[26:29]
	v_mfma_f32_16x16x32_bf16 v[14:17], v[156:159], v[232:235], v[14:17]
	v_mfma_f32_16x16x32_bf16 v[10:13], v[168:171], v[232:235], v[10:13]
	v_mfma_f32_16x16x32_bf16 v[62:65], v[164:167], v[212:215], v[62:65]
	v_mfma_f32_16x16x32_bf16 v[58:61], v[172:175], v[212:215], v[58:61]
	v_mfma_f32_16x16x32_bf16 v[46:49], v[164:167], v[220:223], v[46:49]
	v_mfma_f32_16x16x32_bf16 v[42:45], v[172:175], v[220:223], v[42:45]
	v_mfma_f32_16x16x32_bf16 v[30:33], v[164:167], v[228:231], v[30:33]
	v_mfma_f32_16x16x32_bf16 v[26:29], v[172:175], v[228:231], v[26:29]
	v_mfma_f32_16x16x32_bf16 v[14:17], v[164:167], v[236:239], v[14:17]
	v_mfma_f32_16x16x32_bf16 v[10:13], v[172:175], v[236:239], v[10:13]
	v_mfma_f32_16x16x32_bf16 v[54:57], v[176:179], v[208:211], v[54:57]
	v_mfma_f32_16x16x32_bf16 v[50:53], v[184:187], v[208:211], v[50:53]
	v_mfma_f32_16x16x32_bf16 v[38:41], v[176:179], v[216:219], v[38:41]
	v_mfma_f32_16x16x32_bf16 v[34:37], v[184:187], v[216:219], v[34:37]
	v_mfma_f32_16x16x32_bf16 v[22:25], v[176:179], v[224:227], v[22:25]
	v_mfma_f32_16x16x32_bf16 v[18:21], v[184:187], v[224:227], v[18:21]
	v_mfma_f32_16x16x32_bf16 v[6:9], v[176:179], v[232:235], v[6:9]
	v_mfma_f32_16x16x32_bf16 v[2:5], v[184:187], v[232:235], v[2:5]
	v_mfma_f32_16x16x32_bf16 v[54:57], v[180:183], v[212:215], v[54:57]
	v_mfma_f32_16x16x32_bf16 v[50:53], v[204:207], v[212:215], v[50:53]
	v_mfma_f32_16x16x32_bf16 v[38:41], v[180:183], v[220:223], v[38:41]
	v_mfma_f32_16x16x32_bf16 v[34:37], v[204:207], v[220:223], v[34:37]
	v_mfma_f32_16x16x32_bf16 v[22:25], v[180:183], v[228:231], v[22:25]
	v_mfma_f32_16x16x32_bf16 v[18:21], v[204:207], v[228:231], v[18:21]
	v_mfma_f32_16x16x32_bf16 v[6:9], v[180:183], v[236:239], v[6:9]
	v_mfma_f32_16x16x32_bf16 v[2:5], v[204:207], v[236:239], v[2:5]
	s_setprio 0
	s_barrier
	s_add_i32 s67, s67, 2
	s_add_u32 s36, s36, 0x100
	s_addc_u32 s37, s37, 0
	s_add_u32 s62, s62, 0x100
	s_addc_u32 s63, s63, 0
	s_cmp_gt_u32 s67, 29
	s_cbranch_scc0 .LBB0_281
	s_cmp_lg_u64 s[4:5], 0
	s_cselect_b32 s32, 3, 1
	s_and_b64 vcc, exec, s[4:5]
	s_cbranch_vccnz .LBB0_286
	s_cmp_lt_i32 s57, 30
	s_mov_b64 s[18:19], -1
	s_cbranch_scc1 .LBB0_287

; __device__ __forceinline__ unsigned cvt_pk_bf16(float lo, float hi) { const f32x2c_t v = {lo, hi}; const bf16x2c_t b = __builtin_convertvector(v, bf16x2c_t); return __builtin_bit_cast(unsigned, b); }
;     __device__ __forceinline__ void operator()(const f32x4 (&acc)[2][2][4][2], const Unit& u, int wr, int wc, int fr, int fq) const {
;     ...
;         const bool qs = u.pn < 6;
; #pragma unroll
;         for (int ai = 0; ai < 2; ++ai)
; #pragma unroll
;             for (int m = 0; m < 4; ++m) { bf16_t* rowp = Z + (size_t)(row0 + ai * HALF + m * 16) * DIN + col0;
; #pragma unroll
;                 for (int bj = 0; bj < 2; ++bj) { f32x4 v0 = acc[ai][bj][m][0], v1 = acc[ai][bj][m][1];
;                     if (qs) { v0 = v0 * QSCALE; v1 = v1 * QSCALE; }
;                     u32x4 w; w.x = cvt_pk_bf16(v0[0], v0[1]); w.y = cvt_pk_bf16(v0[2], v0[3]); w.z = cvt_pk_bf16(v1[0], v1[1]); w.w = cvt_pk_bf16(v1[2], v1[3]);
;                     *(u32x4*)(rowp + bj * HALF) = w; } }
.LBB0_286:
	s_cmp_lt_i32 s57, 30
	s_mov_b64 s[18:19], -1
	s_cbranch_scc0 .LBB0_284
.LBB0_287:
	v_lshl_or_b32 v158, s57, 8, v161
	v_lshl_add_u32 v163, s58, 8, v1
	v_ashrrev_i32_e32 v159, 31, v158
	v_mov_b64_e32 v[156:157], s[92:93]
	s_cmp_lt_i32 s57, 6
	v_mad_i64_i32 v[164:165], s[18:19], v163, s27, v[156:157]
	v_lshlrev_b64 v[158:159], 1, v[158:159]
	v_lshl_add_u64 v[168:169], v[164:165], 0, v[158:159]
	v_pk_mul_f32 v[164:165], v[128:129], s[48:49] op_sel_hi:[1,0]
	v_pk_mul_f32 v[166:167], v[126:127], s[48:49] op_sel_hi:[1,0]
	v_pk_mul_f32 v[170:171], v[124:125], s[48:49] op_sel_hi:[1,0]
	v_pk_mul_f32 v[172:173], v[122:123], s[48:49] op_sel_hi:[1,0]
	s_cselect_b64 vcc, -1, 0
	v_cndmask_b32_e32 v165, v129, v165, vcc
	v_cndmask_b32_e32 v174, v128, v164, vcc
	v_cndmask_b32_e32 v164, v127, v167, vcc
	v_cndmask_b32_e32 v166, v126, v166, vcc
	v_cndmask_b32_e32 v167, v125, v171, vcc
	v_cndmask_b32_e32 v170, v124, v170, vcc
	v_cndmask_b32_e32 v171, v123, v173, vcc
	v_cndmask_b32_e32 v172, v122, v172, vcc
	v_cvt_pk_bf16_f32 v164, v166, v164
	v_cvt_pk_bf16_f32 v165, v174, v165
	v_cvt_pk_bf16_f32 v166, v172, v171
	v_cvt_pk_bf16_f32 v167, v170, v167
	global_store_dwordx4 v[168:169], v[164:167], off
	v_pk_mul_f32 v[170:171], v[116:117], s[48:49] op_sel_hi:[1,0]
	v_pk_mul_f32 v[172:173], v[114:115], s[48:49] op_sel_hi:[1,0]
	v_pk_mul_f32 v[164:165], v[120:121], s[48:49] op_sel_hi:[1,0]
	v_pk_mul_f32 v[166:167], v[118:119], s[48:49] op_sel_hi:[1,0]
	v_cndmask_b32_e32 v165, v121, v165, vcc
	v_cndmask_b32_e32 v174, v120, v164, vcc
	v_cndmask_b32_e32 v164, v119, v167, vcc
	v_cndmask_b32_e32 v166, v118, v166, vcc
	v_cndmask_b32_e32 v167, v117, v171, vcc
	v_cndmask_b32_e32 v170, v116, v170, vcc
	v_cndmask_b32_e32 v171, v115, v173, vcc
	v_cndmask_b32_e32 v172, v114, v172, vcc
	v_cvt_pk_bf16_f32 v164, v166, v164
	v_cvt_pk_bf16_f32 v165, v174, v165
	v_cvt_pk_bf16_f32 v166, v172, v171
	v_cvt_pk_bf16_f32 v167, v170, v167
	global_store_dwordx4 v[168:169], v[164:167], off offset:256
	s_bitcmp1_b32 s32, 1
	s_cbranch_scc0 .Lalign281n
	s_barrier
.Lalign281n:
	v_pk_mul_f32 v[170:171], v[108:109], s[48:49] op_sel_hi:[1,0]
	v_pk_mul_f32 v[172:173], v[106:107], s[48:49] op_sel_hi:[1,0]
	v_or_b32_e32 v164, 16, v163
	v_mad_i64_i32 v[164:165], s[18:19], v164, s27, v[156:157]
	v_lshl_add_u64 v[168:169], v[164:165], 0, v[158:159]
	v_pk_mul_f32 v[164:165], v[112:113], s[48:49] op_sel_hi:[1,0]
	v_pk_mul_f32 v[166:167], v[110:111], s[48:49] op_sel_hi:[1,0]
	v_cndmask_b32_e32 v165, v113, v165, vcc
	v_cndmask_b32_e32 v174, v112, v164, vcc
	v_cndmask_b32_e32 v164, v111, v167, vcc
	v_cndmask_b32_e32 v166, v110, v166, vcc
	v_cndmask_b32_e32 v167, v109, v171, vcc
	v_cndmask_b32_e32 v170, v108, v170, vcc
	v_cndmask_b32_e32 v171, v107, v173, vcc
	v_cndmask_b32_e32 v172, v106, v172, vcc
	v_cvt_pk_bf16_f32 v164, v166, v164
	v_cvt_pk_bf16_f32 v165, v174, v165
	v_cvt_pk_bf16_f32 v166, v172, v171
	v_cvt_pk_bf16_f32 v167, v170, v167
	global_store_dwordx4 v[168:169], v[164:167], off
	v_pk_mul_f32 v[170:171], v[100:101], s[48:49] op_sel_hi:[1,0]
	v_pk_mul_f32 v[172:173], v[98:99], s[48:49] op_sel_hi:[1,0]
	v_pk_mul_f32 v[164:165], v[104:105], s[48:49] op_sel_hi:[1,0]
	v_pk_mul_f32 v[166:167], v[102:103], s[48:49] op_sel_hi:[1,0]
	v_cndmask_b32_e32 v165, v105, v165, vcc
	v_cndmask_b32_e32 v174, v104, v164, vcc
	v_cndmask_b32_e32 v164, v103, v167, vcc
	v_cndmask_b32_e32 v166, v102, v166, vcc
	v_cndmask_b32_e32 v167, v101, v171, vcc
	v_cndmask_b32_e32 v170, v100, v170, vcc
	v_cndmask_b32_e32 v171, v99, v173, vcc
	v_cndmask_b32_e32 v172, v98, v172, vcc
	v_cvt_pk_bf16_f32 v164, v166, v164
	v_cvt_pk_bf16_f32 v165, v174, v165
	v_cvt_pk_bf16_f32 v166, v172, v171
	v_cvt_pk_bf16_f32 v167, v170, v167
	global_store_dwordx4 v[168:169], v[164:167], off offset:256
	v_pk_mul_f32 v[170:171], v[92:93], s[48:49] op_sel_hi:[1,0]
	v_pk_mul_f32 v[172:173], v[90:91], s[48:49] op_sel_hi:[1,0]
	v_or_b32_e32 v164, 32, v163
	v_mad_i64_i32 v[164:165], s[18:19], v164, s27, v[156:157]
	v_lshl_add_u64 v[168:169], v[164:165], 0, v[158:159]
	v_pk_mul_f32 v[164:165], v[96:97], s[48:49] op_sel_hi:[1,0]
	v_pk_mul_f32 v[166:167], v[94:95], s[48:49] op_sel_hi:[1,0]
	v_cndmask_b32_e32 v165, v97, v165, vcc
	v_cndmask_b32_e32 v174, v96, v164, vcc
	v_cndmask_b32_e32 v164, v95, v167, vcc
	v_cndmask_b32_e32 v166, v94, v166, vcc
	v_cndmask_b32_e32 v167, v93, v171, vcc
	v_cndmask_b32_e32 v170, v92, v170, vcc
	v_cndmask_b32_e32 v171, v91, v173, vcc
	v_cndmask_b32_e32 v172, v90, v172, vcc
	v_cvt_pk_bf16_f32 v164, v166, v164
	v_cvt_pk_bf16_f32 v165, v174, v165
	v_cvt_pk_bf16_f32 v166, v172, v171
	v_cvt_pk_bf16_f32 v167, v170, v167
	global_store_dwordx4 v[168:169], v[164:167], off
	v_pk_mul_f32 v[170:171], v[84:85], s[48:49] op_sel_hi:[1,0]
	v_pk_mul_f32 v[172:173], v[82:83], s[48:49] op_sel_hi:[1,0]
	v_pk_mul_f32 v[164:165], v[88:89], s[48:49] op_sel_hi:[1,0]
	v_pk_mul_f32 v[166:167], v[86:87], s[48:49] op_sel_hi:[1,0]
	v_cndmask_b32_e32 v165, v89, v165, vcc
	v_cndmask_b32_e32 v174, v88, v164, vcc
	v_cndmask_b32_e32 v164, v87, v167, vcc
	v_cndmask_b32_e32 v166, v86, v166, vcc
	v_cndmask_b32_e32 v167, v85, v171, vcc
	v_cndmask_b32_e32 v170, v84, v170, vcc
	v_cndmask_b32_e32 v171, v83, v173, vcc
	v_cndmask_b32_e32 v172, v82, v172, vcc
	v_cvt_pk_bf16_f32 v164, v166, v164
	v_cvt_pk_bf16_f32 v165, v174, v165
	v_cvt_pk_bf16_f32 v166, v172, v171
	v_cvt_pk_bf16_f32 v167, v170, v167
	global_store_dwordx4 v[168:169], v[164:167], off offset:256
	v_pk_mul_f32 v[170:171], v[76:77], s[48:49] op_sel_hi:[1,0]
	v_pk_mul_f32 v[172:173], v[74:75], s[48:49] op_sel_hi:[1,0]
	v_or_b32_e32 v164, 48, v163
	v_mad_i64_i32 v[164:165], s[18:19], v164, s27, v[156:157]
; __device__ __forceinline__ unsigned cvt_pk_bf16(float lo, float hi) { const f32x2c_t v = {lo, hi}; const bf16x2c_t b = __builtin_convertvector(v, bf16x2c_t); return __builtin_bit_cast(unsigned, b); }
;     __device__ __forceinline__ void operator()(const f32x4 (&acc)[2][2][4][2], const Unit& u, int wr, int wc, int fr, int fq) const {
;     ...
;         for (int ai = 0; ai < 2; ++ai)
; #pragma unroll
;             for (int m = 0; m < 4; ++m) { bf16_t* rowp = Z + (size_t)(row0 + ai * HALF + m * 16) * DIN + col0;
; #pragma unroll
;                 for (int bj = 0; bj < 2; ++bj) { f32x4 v0 = acc[ai][bj][m][0], v1 = acc[ai][bj][m][1];
;                     if (qs) { v0 = v0 * QSCALE; v1 = v1 * QSCALE; }
;                     u32x4 w; w.x = cvt_pk_bf16(v0[0], v0[1]); w.y = cvt_pk_bf16(v0[2], v0[3]); w.z = cvt_pk_bf16(v1[0], v1[1]); w.w = cvt_pk_bf16(v1[2], v1[3]);
;                     *(u32x4*)(rowp + bj * HALF) = w; } }
	v_lshl_add_u64 v[168:169], v[164:165], 0, v[158:159]
	v_pk_mul_f32 v[164:165], v[80:81], s[48:49] op_sel_hi:[1,0]
	v_pk_mul_f32 v[166:167], v[78:79], s[48:49] op_sel_hi:[1,0]
	v_cndmask_b32_e32 v165, v81, v165, vcc
	v_cndmask_b32_e32 v174, v80, v164, vcc
	v_cndmask_b32_e32 v164, v79, v167, vcc
	v_cndmask_b32_e32 v166, v78, v166, vcc
	v_cndmask_b32_e32 v167, v77, v171, vcc
	v_cndmask_b32_e32 v170, v76, v170, vcc
	v_cndmask_b32_e32 v171, v75, v173, vcc
	v_cndmask_b32_e32 v172, v74, v172, vcc
	v_cvt_pk_bf16_f32 v164, v166, v164
	v_cvt_pk_bf16_f32 v165, v174, v165
	v_cvt_pk_bf16_f32 v166, v172, v171
	v_cvt_pk_bf16_f32 v167, v170, v167
	global_store_dwordx4 v[168:169], v[164:167], off
	v_pk_mul_f32 v[170:171], v[68:69], s[48:49] op_sel_hi:[1,0]
	v_pk_mul_f32 v[172:173], v[66:67], s[48:49] op_sel_hi:[1,0]
	v_pk_mul_f32 v[164:165], v[72:73], s[48:49] op_sel_hi:[1,0]
	v_pk_mul_f32 v[166:167], v[70:71], s[48:49] op_sel_hi:[1,0]
	v_cndmask_b32_e32 v165, v73, v165, vcc
	v_cndmask_b32_e32 v174, v72, v164, vcc
	v_cndmask_b32_e32 v164, v71, v167, vcc
	v_cndmask_b32_e32 v166, v70, v166, vcc
	v_cndmask_b32_e32 v167, v69, v171, vcc
	v_cndmask_b32_e32 v170, v68, v170, vcc
	v_cndmask_b32_e32 v171, v67, v173, vcc
	v_cndmask_b32_e32 v172, v66, v172, vcc
	v_cvt_pk_bf16_f32 v164, v166, v164
	v_cvt_pk_bf16_f32 v165, v174, v165
	v_cvt_pk_bf16_f32 v166, v172, v171
	v_cvt_pk_bf16_f32 v167, v170, v167
	global_store_dwordx4 v[168:169], v[164:167], off offset:256
	v_pk_mul_f32 v[170:171], v[60:61], s[48:49] op_sel_hi:[1,0]
	v_pk_mul_f32 v[172:173], v[58:59], s[48:49] op_sel_hi:[1,0]
	v_add_u32_e32 v164, 0x80, v163
	v_mad_i64_i32 v[164:165], s[18:19], v164, s27, v[156:157]
	v_lshl_add_u64 v[168:169], v[164:165], 0, v[158:159]
	v_pk_mul_f32 v[164:165], v[64:65], s[48:49] op_sel_hi:[1,0]
	v_pk_mul_f32 v[166:167], v[62:63], s[48:49] op_sel_hi:[1,0]
	v_cndmask_b32_e32 v165, v65, v165, vcc
	v_cndmask_b32_e32 v174, v64, v164, vcc
	v_cndmask_b32_e32 v164, v63, v167, vcc
	v_cndmask_b32_e32 v166, v62, v166, vcc
	v_cndmask_b32_e32 v167, v61, v171, vcc
	v_cndmask_b32_e32 v170, v60, v170, vcc
	v_cndmask_b32_e32 v171, v59, v173, vcc
	v_cndmask_b32_e32 v172, v58, v172, vcc
	v_cvt_pk_bf16_f32 v164, v166, v164
	v_cvt_pk_bf16_f32 v165, v174, v165
	v_cvt_pk_bf16_f32 v166, v172, v171
	v_cvt_pk_bf16_f32 v167, v170, v167
	global_store_dwordx4 v[168:169], v[164:167], off
	v_pk_mul_f32 v[170:171], v[52:53], s[48:49] op_sel_hi:[1,0]
	v_pk_mul_f32 v[172:173], v[50:51], s[48:49] op_sel_hi:[1,0]
	v_pk_mul_f32 v[164:165], v[56:57], s[48:49] op_sel_hi:[1,0]
	v_pk_mul_f32 v[166:167], v[54:55], s[48:49] op_sel_hi:[1,0]
	v_cndmask_b32_e32 v165, v57, v165, vcc
	v_cndmask_b32_e32 v174, v56, v164, vcc
	v_cndmask_b32_e32 v164, v55, v167, vcc
	v_cndmask_b32_e32 v166, v54, v166, vcc
	v_cndmask_b32_e32 v167, v53, v171, vcc
	v_cndmask_b32_e32 v170, v52, v170, vcc
	v_cndmask_b32_e32 v171, v51, v173, vcc
	v_cndmask_b32_e32 v172, v50, v172, vcc
	v_cvt_pk_bf16_f32 v164, v166, v164
	v_cvt_pk_bf16_f32 v165, v174, v165
	v_cvt_pk_bf16_f32 v166, v172, v171
	v_cvt_pk_bf16_f32 v167, v170, v167
	global_store_dwordx4 v[168:169], v[164:167], off offset:256
	v_pk_mul_f32 v[170:171], v[44:45], s[48:49] op_sel_hi:[1,0]
	v_pk_mul_f32 v[172:173], v[42:43], s[48:49] op_sel_hi:[1,0]
	v_add_u32_e32 v164, 0x90, v163
	v_mad_i64_i32 v[164:165], s[18:19], v164, s27, v[156:157]
	v_lshl_add_u64 v[168:169], v[164:165], 0, v[158:159]
	v_pk_mul_f32 v[164:165], v[48:49], s[48:49] op_sel_hi:[1,0]
	v_pk_mul_f32 v[166:167], v[46:47], s[48:49] op_sel_hi:[1,0]
	v_cndmask_b32_e32 v165, v49, v165, vcc
	v_cndmask_b32_e32 v174, v48, v164, vcc
	v_cndmask_b32_e32 v164, v47, v167, vcc
	v_cndmask_b32_e32 v166, v46, v166, vcc
	v_cndmask_b32_e32 v167, v45, v171, vcc
	v_cndmask_b32_e32 v170, v44, v170, vcc
	v_cndmask_b32_e32 v171, v43, v173, vcc
	v_cndmask_b32_e32 v172, v42, v172, vcc
	v_cvt_pk_bf16_f32 v164, v166, v164
	v_cvt_pk_bf16_f32 v165, v174, v165
	v_cvt_pk_bf16_f32 v166, v172, v171
	v_cvt_pk_bf16_f32 v167, v170, v167
	global_store_dwordx4 v[168:169], v[164:167], off
	v_pk_mul_f32 v[170:171], v[36:37], s[48:49] op_sel_hi:[1,0]
	v_pk_mul_f32 v[172:173], v[34:35], s[48:49] op_sel_hi:[1,0]
	v_pk_mul_f32 v[164:165], v[40:41], s[48:49] op_sel_hi:[1,0]
	v_pk_mul_f32 v[166:167], v[38:39], s[48:49] op_sel_hi:[1,0]
	v_cndmask_b32_e32 v165, v41, v165, vcc
	v_cndmask_b32_e32 v174, v40, v164, vcc
	v_cndmask_b32_e32 v164, v39, v167, vcc
	v_cndmask_b32_e32 v166, v38, v166, vcc
	v_cndmask_b32_e32 v167, v37, v171, vcc
	v_cndmask_b32_e32 v170, v36, v170, vcc
	v_cndmask_b32_e32 v171, v35, v173, vcc
	v_cndmask_b32_e32 v172, v34, v172, vcc
	v_cvt_pk_bf16_f32 v164, v166, v164
	v_cvt_pk_bf16_f32 v165, v174, v165
	v_cvt_pk_bf16_f32 v166, v172, v171
	v_cvt_pk_bf16_f32 v167, v170, v167
	global_store_dwordx4 v[168:169], v[164:167], off offset:256
	v_pk_mul_f32 v[170:171], v[28:29], s[48:49] op_sel_hi:[1,0]
	v_pk_mul_f32 v[172:173], v[26:27], s[48:49] op_sel_hi:[1,0]
	v_add_u32_e32 v164, 0xa0, v163
	v_mad_i64_i32 v[164:165], s[18:19], v164, s27, v[156:157]
	v_lshl_add_u64 v[168:169], v[164:165], 0, v[158:159]
	v_pk_mul_f32 v[164:165], v[32:33], s[48:49] op_sel_hi:[1,0]
	v_pk_mul_f32 v[166:167], v[30:31], s[48:49] op_sel_hi:[1,0]
	v_cndmask_b32_e32 v165, v33, v165, vcc
	v_cndmask_b32_e32 v174, v32, v164, vcc
	v_cndmask_b32_e32 v164, v31, v167, vcc
	v_cndmask_b32_e32 v166, v30, v166, vcc
	v_cndmask_b32_e32 v167, v29, v171, vcc
	v_cndmask_b32_e32 v170, v28, v170, vcc
	v_cndmask_b32_e32 v171, v27, v173, vcc
	v_cndmask_b32_e32 v172, v26, v172, vcc
	v_cvt_pk_bf16_f32 v164, v166, v164
	v_cvt_pk_bf16_f32 v165, v174, v165
	v_cvt_pk_bf16_f32 v166, v172, v171
	v_cvt_pk_bf16_f32 v167, v170, v167
; __device__ __forceinline__ unsigned cvt_pk_bf16(float lo, float hi) { const f32x2c_t v = {lo, hi}; const bf16x2c_t b = __builtin_convertvector(v, bf16x2c_t); return __builtin_bit_cast(unsigned, b); }
; __device__ __forceinline__ float sigmoidf_fast(float x) { return __builtin_amdgcn_rcpf(1.0f + __builtin_amdgcn_exp2f(-1.4426950408889634f * x)); }
;     __device__ __forceinline__ void operator()(const f32x4 (&acc)[2][2][4][2], const Unit& u, int wr, int wc, int fr, int fq) const {
;     ...
;         if (u.pn >= 30) {
;             const int tidn = (wr * 4 + wc) * 64 + fq * 16 + fr;
;             u32x4* gp = (u32x4*)G8 + (size_t)(u.pm * 16 + (u.pn - 30)) * 8 * 512 + tidn;
; #pragma unroll
;             for (int ai = 0; ai < 2; ++ai)
; #pragma unroll
;                 for (int m = 0; m < 4; ++m) { unsigned q[16];
; #pragma unroll
;                     for (int bj = 0; bj < 2; ++bj) { const f32x4 v0 = acc[ai][bj][m][0], v1 = acc[ai][bj][m][1];
; #pragma unroll
;                         for (int e = 0; e < 4; ++e) { q[8 * bj + e] = (unsigned)fmaf(sigmoidf_fast(v0[e]), 255.0f, 0.5f); q[8 * bj + 4 + e] = (unsigned)fmaf(sigmoidf_fast(v1[e]), 255.0f, 0.5f); } }
;                     u32x4 w; w.x = q[0] | (q[1] << 8) | (q[2] << 16) | (q[3] << 24); w.y = q[4] | (q[5] << 8) | (q[6] << 16) | (q[7] << 24);
;                     w.z = q[8] | (q[9] << 8) | (q[10] << 16) | (q[11] << 24); w.w = q[12] | (q[13] << 8) | (q[14] << 16) | (q[15] << 24);
;     ...
;         for (int ai = 0; ai < 2; ++ai)
; #pragma unroll
;             for (int m = 0; m < 4; ++m) { bf16_t* rowp = Z + (size_t)(row0 + ai * HALF + m * 16) * DIN + col0;
; #pragma unroll
;                 for (int bj = 0; bj < 2; ++bj) { f32x4 v0 = acc[ai][bj][m][0], v1 = acc[ai][bj][m][1];
;                     if (qs) { v0 = v0 * QSCALE; v1 = v1 * QSCALE; }
;                     u32x4 w; w.x = cvt_pk_bf16(v0[0], v0[1]); w.y = cvt_pk_bf16(v0[2], v0[3]); w.z = cvt_pk_bf16(v1[0], v1[1]); w.w = cvt_pk_bf16(v1[2], v1[3]);
;                     *(u32x4*)(rowp + bj * HALF) = w; } }
	global_store_dwordx4 v[168:169], v[164:167], off
	v_pk_mul_f32 v[170:171], v[20:21], s[48:49] op_sel_hi:[1,0]
	v_pk_mul_f32 v[172:173], v[18:19], s[48:49] op_sel_hi:[1,0]
	v_pk_mul_f32 v[164:165], v[24:25], s[48:49] op_sel_hi:[1,0]
	v_pk_mul_f32 v[166:167], v[22:23], s[48:49] op_sel_hi:[1,0]
	v_cndmask_b32_e32 v165, v25, v165, vcc
	v_cndmask_b32_e32 v174, v24, v164, vcc
	v_cndmask_b32_e32 v164, v23, v167, vcc
	v_cndmask_b32_e32 v166, v22, v166, vcc
	v_cndmask_b32_e32 v167, v21, v171, vcc
	v_cndmask_b32_e32 v170, v20, v170, vcc
	v_cndmask_b32_e32 v171, v19, v173, vcc
	v_cndmask_b32_e32 v172, v18, v172, vcc
	v_add_u32_e32 v163, 0xb0, v163
	v_cvt_pk_bf16_f32 v164, v166, v164
	v_cvt_pk_bf16_f32 v165, v174, v165
	v_cvt_pk_bf16_f32 v166, v172, v171
	v_cvt_pk_bf16_f32 v167, v170, v167
	v_mad_i64_i32 v[156:157], s[18:19], v163, s27, v[156:157]
	global_store_dwordx4 v[168:169], v[164:167], off offset:256
	v_pk_mul_f32 v[168:169], v[10:11], s[48:49] op_sel_hi:[1,0]
	s_nop 0
	v_lshl_add_u64 v[164:165], v[156:157], 0, v[158:159]
	v_pk_mul_f32 v[156:157], v[16:17], s[48:49] op_sel_hi:[1,0]
	v_pk_mul_f32 v[158:159], v[14:15], s[48:49] op_sel_hi:[1,0]
	v_pk_mul_f32 v[166:167], v[12:13], s[48:49] op_sel_hi:[1,0]
	v_cndmask_b32_e32 v157, v17, v157, vcc
	v_cndmask_b32_e32 v163, v16, v156, vcc
	v_cndmask_b32_e32 v156, v15, v159, vcc
	v_cndmask_b32_e32 v158, v14, v158, vcc
	v_cndmask_b32_e32 v159, v13, v167, vcc
	v_cndmask_b32_e32 v166, v12, v166, vcc
	v_cndmask_b32_e32 v167, v11, v169, vcc
	v_cndmask_b32_e32 v168, v10, v168, vcc
	v_cvt_pk_bf16_f32 v156, v158, v156
	v_cvt_pk_bf16_f32 v157, v163, v157
	v_cvt_pk_bf16_f32 v158, v168, v167
	v_cvt_pk_bf16_f32 v159, v166, v159
	global_store_dwordx4 v[164:165], v[156:159], off
	v_pk_mul_f32 v[166:167], v[4:5], s[48:49] op_sel_hi:[1,0]
	v_pk_mul_f32 v[168:169], v[2:3], s[48:49] op_sel_hi:[1,0]
	v_pk_mul_f32 v[156:157], v[8:9], s[48:49] op_sel_hi:[1,0]
	v_pk_mul_f32 v[158:159], v[6:7], s[48:49] op_sel_hi:[1,0]
	v_cndmask_b32_e32 v157, v9, v157, vcc
	v_cndmask_b32_e32 v163, v8, v156, vcc
	v_cndmask_b32_e32 v156, v7, v159, vcc
	v_cndmask_b32_e32 v158, v6, v158, vcc
	v_cndmask_b32_e32 v159, v5, v167, vcc
	v_cndmask_b32_e32 v166, v4, v166, vcc
	v_cndmask_b32_e32 v167, v3, v169, vcc
	v_cndmask_b32_e32 v168, v2, v168, vcc
	v_cvt_pk_bf16_f32 v156, v158, v156
	v_cvt_pk_bf16_f32 v157, v163, v157
	v_cvt_pk_bf16_f32 v158, v168, v167
	v_cvt_pk_bf16_f32 v159, v166, v159
	global_store_dwordx4 v[164:165], v[156:159], off offset:256
	s_cbranch_execnz .LBB0_285
.LBB0_288:
	v_mul_f32_e32 v126, 0xbfb8aa3b, v126
	v_mul_f32_e32 v122, 0xbfb8aa3b, v122
	v_exp_f32_e32 v126, v126
	v_exp_f32_e32 v158, v122
	v_mul_f32_e32 v127, 0xbfb8aa3b, v127
	v_mul_f32_e32 v123, 0xbfb8aa3b, v123
	v_add_f32_e32 v122, 1.0, v126
	v_add_f32_e32 v126, 1.0, v158
	v_exp_f32_e32 v127, v127
	v_exp_f32_e32 v158, v123
	v_mul_f32_e32 v128, 0xbfb8aa3b, v128
	v_mul_f32_e32 v124, 0xbfb8aa3b, v124
	v_rcp_f32_e32 v123, v126
	v_add_f32_e32 v126, 1.0, v127
	v_add_f32_e32 v127, 1.0, v158
	v_exp_f32_e32 v128, v128
	v_exp_f32_e32 v158, v124
	v_mul_f32_e32 v129, 0xbfb8aa3b, v129
	v_mul_f32_e32 v125, 0xbfb8aa3b, v125
	v_add_f32_e32 v124, 1.0, v128
	v_add_f32_e32 v128, 1.0, v158
	v_exp_f32_e32 v129, v129
	v_exp_f32_e32 v158, v125
	v_mul_f32_e32 v118, 0xbfb8aa3b, v118
	v_mul_f32_e32 v114, 0xbfb8aa3b, v114
	v_rcp_f32_e32 v125, v128
	v_add_f32_e32 v128, 1.0, v129
	v_add_f32_e32 v129, 1.0, v158
	v_exp_f32_e32 v118, v118
	v_exp_f32_e32 v158, v114
	v_mul_f32_e32 v119, 0xbfb8aa3b, v119
	v_mul_f32_e32 v115, 0xbfb8aa3b, v115
	v_add_f32_e32 v114, 1.0, v118
	v_add_f32_e32 v118, 1.0, v158
	v_exp_f32_e32 v119, v119
	v_exp_f32_e32 v158, v115
	v_mul_f32_e32 v120, 0xbfb8aa3b, v120
	v_mul_f32_e32 v116, 0xbfb8aa3b, v116
	v_rcp_f32_e32 v115, v118
	v_add_f32_e32 v118, 1.0, v119
	v_add_f32_e32 v119, 1.0, v158
	v_exp_f32_e32 v120, v120
	v_exp_f32_e32 v158, v116
	v_rcp_f32_e32 v114, v114
	v_rcp_f32_e32 v118, v118
	v_rcp_f32_e32 v119, v119
	v_mul_f32_e32 v121, 0xbfb8aa3b, v121
	v_mul_f32_e32 v117, 0xbfb8aa3b, v117
	v_rcp_f32_e32 v122, v122
	v_rcp_f32_e32 v126, v126
	v_rcp_f32_e32 v127, v127
	v_add_f32_e32 v116, 1.0, v120
	v_add_f32_e32 v120, 1.0, v158
	v_exp_f32_e32 v121, v121
	v_exp_f32_e32 v158, v117
	v_pk_fma_f32 v[118:119], v[118:119], s[16:17], 0.5 op_sel_hi:[1,0,0]
	v_pk_fma_f32 v[114:115], v[114:115], s[16:17], 0.5 op_sel_hi:[1,0,0]
	v_rcp_f32_e32 v124, v124
	v_rcp_f32_e32 v116, v116
	v_rcp_f32_e32 v117, v120
	v_add_f32_e32 v120, 1.0, v121
	v_add_f32_e32 v121, 1.0, v158
	v_pk_fma_f32 v[126:127], v[126:127], s[16:17], 0.5 op_sel_hi:[1,0,0]
	v_cvt_u32_f32_e32 v158, v119
	v_cvt_u32_f32_e32 v159, v118
	v_pk_fma_f32 v[118:119], v[122:123], s[16:17], 0.5 op_sel_hi:[1,0,0]
	v_cvt_u32_f32_e32 v114, v114
	v_cvt_u32_f32_e32 v115, v115
	v_rcp_f32_e32 v128, v128
	v_rcp_f32_e32 v129, v129
	v_rcp_f32_e32 v120, v120
	v_rcp_f32_e32 v121, v121
	v_cvt_u32_f32_e32 v127, v127
	v_cvt_u32_f32_e32 v126, v126
	v_cvt_u32_f32_e32 v118, v118
	v_cvt_u32_f32_e32 v119, v119
	v_lshl_or_b32 v122, v159, 8, v114
	v_lshl_or_b32 v123, v158, 8, v115
	v_pk_fma_f32 v[114:115], v[124:125], s[16:17], 0.5 op_sel_hi:[1,0,0]
	v_pk_fma_f32 v[116:117], v[116:117], s[16:17], 0.5 op_sel_hi:[1,0,0]
	s_lshl_b32 s7, s58, 4
	v_lshl_or_b32 v118, v126, 8, v118
	v_lshl_or_b32 v119, v127, 8, v119
	v_cvt_u32_f32_sdwa v124, v117 dst_sel:WORD_1 dst_unused:UNUSED_PAD src0_sel:DWORD
	v_cvt_u32_f32_sdwa v125, v116 dst_sel:WORD_1 dst_unused:UNUSED_PAD src0_sel:DWORD
	v_cvt_u32_f32_sdwa v126, v115 dst_sel:WORD_1 dst_unused:UNUSED_PAD src0_sel:DWORD
	v_cvt_u32_f32_sdwa v127, v114 dst_sel:WORD_1 dst_unused:UNUSED_PAD src0_sel:DWORD
; __device__ __forceinline__ float sigmoidf_fast(float x) { return __builtin_amdgcn_rcpf(1.0f + __builtin_amdgcn_exp2f(-1.4426950408889634f * x)); }
;     __device__ __forceinline__ void operator()(const f32x4 (&acc)[2][2][4][2], const Unit& u, int wr, int wc, int fr, int fq) const {
;     ...
;         if (u.pn >= 30) {
;             const int tidn = (wr * 4 + wc) * 64 + fq * 16 + fr;
;             u32x4* gp = (u32x4*)G8 + (size_t)(u.pm * 16 + (u.pn - 30)) * 8 * 512 + tidn;
; #pragma unroll
;             for (int ai = 0; ai < 2; ++ai)
; #pragma unroll
;                 for (int m = 0; m < 4; ++m) { unsigned q[16];
; #pragma unroll
;                     for (int bj = 0; bj < 2; ++bj) { const f32x4 v0 = acc[ai][bj][m][0], v1 = acc[ai][bj][m][1];
; #pragma unroll
;                         for (int e = 0; e < 4; ++e) { q[8 * bj + e] = (unsigned)fmaf(sigmoidf_fast(v0[e]), 255.0f, 0.5f); q[8 * bj + 4 + e] = (unsigned)fmaf(sigmoidf_fast(v1[e]), 255.0f, 0.5f); } }
;                     u32x4 w; w.x = q[0] | (q[1] << 8) | (q[2] << 16) | (q[3] << 24); w.y = q[4] | (q[5] << 8) | (q[6] << 16) | (q[7] << 24);
;                     w.z = q[8] | (q[9] << 8) | (q[10] << 16) | (q[11] << 24); w.w = q[12] | (q[13] << 8) | (q[14] << 16) | (q[15] << 24);
;                     gp[(ai * 4 + m) * 512] = w; }
	v_pk_fma_f32 v[114:115], v[128:129], s[16:17], 0.5 op_sel_hi:[1,0,0]
	v_pk_fma_f32 v[116:117], v[120:121], s[16:17], 0.5 op_sel_hi:[1,0,0]
	s_add_i32 s7, s57, s7
	v_cvt_u32_f32_sdwa v117, v117 dst_sel:BYTE_3 dst_unused:UNUSED_PAD src0_sel:DWORD
	v_cvt_u32_f32_sdwa v116, v116 dst_sel:BYTE_3 dst_unused:UNUSED_PAD src0_sel:DWORD
	v_cvt_u32_f32_sdwa v115, v115 dst_sel:BYTE_3 dst_unused:UNUSED_PAD src0_sel:DWORD
	v_cvt_u32_f32_sdwa v114, v114 dst_sel:BYTE_3 dst_unused:UNUSED_PAD src0_sel:DWORD
	s_sub_i32 s18, s7, 30
	s_ashr_i32 s19, s18, 31
	s_lshl_b64 s[18:19], s[18:19], 16
	v_mul_f32_e32 v110, 0xbfb8aa3b, v110
	v_mul_f32_e32 v106, 0xbfb8aa3b, v106
	v_lshl_add_u64 v[156:157], v[150:151], 0, s[18:19]
	v_or3_b32 v117, v123, v124, v117
	v_or3_b32 v116, v122, v125, v116
	v_or3_b32 v115, v119, v126, v115
	v_or3_b32 v114, v118, v127, v114
	v_exp_f32_e32 v110, v110
	v_exp_f32_e32 v118, v106
	v_mul_f32_e32 v111, 0xbfb8aa3b, v111
	v_mul_f32_e32 v107, 0xbfb8aa3b, v107
	global_store_dwordx4 v[156:157], v[114:117], off
	v_exp_f32_e32 v111, v111
	v_add_f32_e32 v106, 1.0, v110
	v_exp_f32_e32 v114, v107
	v_add_f32_e32 v110, 1.0, v118
	v_mul_f32_e32 v112, 0xbfb8aa3b, v112
	v_mul_f32_e32 v108, 0xbfb8aa3b, v108
	v_rcp_f32_e32 v107, v110
	v_add_f32_e32 v110, 1.0, v111
	v_add_f32_e32 v111, 1.0, v114
	v_exp_f32_e32 v112, v112
	v_exp_f32_e32 v114, v108
	v_mul_f32_e32 v113, 0xbfb8aa3b, v113
	v_mul_f32_e32 v109, 0xbfb8aa3b, v109
	v_add_f32_e32 v108, 1.0, v112
	v_add_f32_e32 v112, 1.0, v114
	v_exp_f32_e32 v113, v113
	v_exp_f32_e32 v114, v109
	v_mul_f32_e32 v102, 0xbfb8aa3b, v102
	v_mul_f32_e32 v98, 0xbfb8aa3b, v98
	v_rcp_f32_e32 v109, v112
	v_add_f32_e32 v112, 1.0, v113
	v_add_f32_e32 v113, 1.0, v114
	v_exp_f32_e32 v102, v102
	v_exp_f32_e32 v114, v98
	v_mul_f32_e32 v103, 0xbfb8aa3b, v103
	v_mul_f32_e32 v99, 0xbfb8aa3b, v99
	v_add_f32_e32 v98, 1.0, v102
	v_add_f32_e32 v102, 1.0, v114
	v_exp_f32_e32 v103, v103
	v_exp_f32_e32 v114, v99
	v_mul_f32_e32 v104, 0xbfb8aa3b, v104
	v_mul_f32_e32 v100, 0xbfb8aa3b, v100
	v_rcp_f32_e32 v99, v102
	v_add_f32_e32 v102, 1.0, v103
	v_add_f32_e32 v103, 1.0, v114
	v_exp_f32_e32 v104, v104
	v_exp_f32_e32 v114, v100
	v_rcp_f32_e32 v98, v98
	v_rcp_f32_e32 v102, v102
	v_rcp_f32_e32 v103, v103
	v_mul_f32_e32 v105, 0xbfb8aa3b, v105
	v_mul_f32_e32 v101, 0xbfb8aa3b, v101
	v_rcp_f32_e32 v106, v106
	v_rcp_f32_e32 v110, v110
	v_rcp_f32_e32 v111, v111
	v_add_f32_e32 v100, 1.0, v104
	v_add_f32_e32 v104, 1.0, v114
	v_exp_f32_e32 v105, v105
	v_exp_f32_e32 v114, v101
	v_pk_fma_f32 v[102:103], v[102:103], s[16:17], 0.5 op_sel_hi:[1,0,0]
	v_pk_fma_f32 v[98:99], v[98:99], s[16:17], 0.5 op_sel_hi:[1,0,0]
	v_rcp_f32_e32 v108, v108
	v_rcp_f32_e32 v101, v104
	v_add_f32_e32 v104, 1.0, v105
	v_add_f32_e32 v105, 1.0, v114
	v_pk_fma_f32 v[110:111], v[110:111], s[16:17], 0.5 op_sel_hi:[1,0,0]
	v_cvt_u32_f32_e32 v114, v103
	v_cvt_u32_f32_e32 v115, v102
	v_pk_fma_f32 v[102:103], v[106:107], s[16:17], 0.5 op_sel_hi:[1,0,0]
	v_cvt_u32_f32_e32 v98, v98
	v_cvt_u32_f32_e32 v99, v99
	v_rcp_f32_e32 v112, v112
	v_rcp_f32_e32 v113, v113
	v_rcp_f32_e32 v100, v100
	v_cvt_u32_f32_e32 v111, v111
	v_cvt_u32_f32_e32 v110, v110
	v_cvt_u32_f32_e32 v102, v102
	v_cvt_u32_f32_e32 v103, v103
	v_rcp_f32_e32 v104, v104
	v_rcp_f32_e32 v105, v105
	v_lshl_or_b32 v106, v115, 8, v98
	v_lshl_or_b32 v107, v114, 8, v99
	v_pk_fma_f32 v[98:99], v[108:109], s[16:17], 0.5 op_sel_hi:[1,0,0]
	v_lshl_or_b32 v102, v110, 8, v102
	v_lshl_or_b32 v103, v111, 8, v103
	v_pk_fma_f32 v[100:101], v[100:101], s[16:17], 0.5 op_sel_hi:[1,0,0]
	v_cvt_u32_f32_sdwa v110, v99 dst_sel:WORD_1 dst_unused:UNUSED_PAD src0_sel:DWORD
	v_cvt_u32_f32_sdwa v111, v98 dst_sel:WORD_1 dst_unused:UNUSED_PAD src0_sel:DWORD
	v_pk_fma_f32 v[98:99], v[112:113], s[16:17], 0.5 op_sel_hi:[1,0,0]
	v_cvt_u32_f32_sdwa v108, v101 dst_sel:WORD_1 dst_unused:UNUSED_PAD src0_sel:DWORD
	v_cvt_u32_f32_sdwa v109, v100 dst_sel:WORD_1 dst_unused:UNUSED_PAD src0_sel:DWORD
	v_pk_fma_f32 v[100:101], v[104:105], s[16:17], 0.5 op_sel_hi:[1,0,0]
	v_cvt_u32_f32_sdwa v98, v98 dst_sel:BYTE_3 dst_unused:UNUSED_PAD src0_sel:DWORD
	v_cvt_u32_f32_sdwa v101, v101 dst_sel:BYTE_3 dst_unused:UNUSED_PAD src0_sel:DWORD
	v_cvt_u32_f32_sdwa v100, v100 dst_sel:BYTE_3 dst_unused:UNUSED_PAD src0_sel:DWORD
	v_cvt_u32_f32_sdwa v99, v99 dst_sel:BYTE_3 dst_unused:UNUSED_PAD src0_sel:DWORD
	s_movk_i32 s7, 0x2000
	v_or3_b32 v98, v102, v111, v98
	v_add_co_u32_e32 v102, vcc, s7, v156
	v_mul_f32_e32 v94, 0xbfb8aa3b, v94
	v_mul_f32_e32 v90, 0xbfb8aa3b, v90
	v_or3_b32 v101, v107, v108, v101
	v_or3_b32 v100, v106, v109, v100
	v_or3_b32 v99, v103, v110, v99
	v_addc_co_u32_e32 v103, vcc, 0, v157, vcc
	v_exp_f32_e32 v94, v94
	v_exp_f32_e32 v104, v90
	v_mul_f32_e32 v95, 0xbfb8aa3b, v95
	v_mul_f32_e32 v91, 0xbfb8aa3b, v91
	global_store_dwordx4 v[102:103], v[98:101], off
	s_bitcmp1_b32 s32, 1
	s_cbranch_scc0 .Lalign281g
	s_barrier
; __device__ __forceinline__ float sigmoidf_fast(float x) { return __builtin_amdgcn_rcpf(1.0f + __builtin_amdgcn_exp2f(-1.4426950408889634f * x)); }
;     __device__ __forceinline__ void operator()(const f32x4 (&acc)[2][2][4][2], const Unit& u, int wr, int wc, int fr, int fq) const {
;     ...
;                 for (int m = 0; m < 4; ++m) { unsigned q[16];
; #pragma unroll
;                     for (int bj = 0; bj < 2; ++bj) { const f32x4 v0 = acc[ai][bj][m][0], v1 = acc[ai][bj][m][1];
; #pragma unroll
;                         for (int e = 0; e < 4; ++e) { q[8 * bj + e] = (unsigned)fmaf(sigmoidf_fast(v0[e]), 255.0f, 0.5f); q[8 * bj + 4 + e] = (unsigned)fmaf(sigmoidf_fast(v1[e]), 255.0f, 0.5f); } }
;                     u32x4 w; w.x = q[0] | (q[1] << 8) | (q[2] << 16) | (q[3] << 24); w.y = q[4] | (q[5] << 8) | (q[6] << 16) | (q[7] << 24);
;                     w.z = q[8] | (q[9] << 8) | (q[10] << 16) | (q[11] << 24); w.w = q[12] | (q[13] << 8) | (q[14] << 16) | (q[15] << 24);
;                     gp[(ai * 4 + m) * 512] = w; }
.Lalign281g:
	v_exp_f32_e32 v95, v95
	v_add_f32_e32 v90, 1.0, v94
	v_exp_f32_e32 v98, v91
	v_add_f32_e32 v94, 1.0, v104
	v_mul_f32_e32 v96, 0xbfb8aa3b, v96
	v_mul_f32_e32 v92, 0xbfb8aa3b, v92
	v_rcp_f32_e32 v91, v94
	v_add_f32_e32 v94, 1.0, v95
	v_add_f32_e32 v95, 1.0, v98
	v_exp_f32_e32 v96, v96
	v_exp_f32_e32 v98, v92
	v_mul_f32_e32 v97, 0xbfb8aa3b, v97
	v_mul_f32_e32 v93, 0xbfb8aa3b, v93
	v_add_f32_e32 v92, 1.0, v96
	v_add_f32_e32 v96, 1.0, v98
	v_exp_f32_e32 v97, v97
	v_exp_f32_e32 v98, v93
	v_mul_f32_e32 v86, 0xbfb8aa3b, v86
	v_mul_f32_e32 v82, 0xbfb8aa3b, v82
	v_rcp_f32_e32 v93, v96
	v_add_f32_e32 v96, 1.0, v97
	v_add_f32_e32 v97, 1.0, v98
	v_exp_f32_e32 v86, v86
	v_exp_f32_e32 v98, v82
	v_mul_f32_e32 v87, 0xbfb8aa3b, v87
	v_mul_f32_e32 v83, 0xbfb8aa3b, v83
	v_add_f32_e32 v82, 1.0, v86
	v_add_f32_e32 v86, 1.0, v98
	v_exp_f32_e32 v87, v87
	v_exp_f32_e32 v98, v83
	v_mul_f32_e32 v88, 0xbfb8aa3b, v88
	v_mul_f32_e32 v84, 0xbfb8aa3b, v84
	v_rcp_f32_e32 v83, v86
	v_add_f32_e32 v86, 1.0, v87
	v_add_f32_e32 v87, 1.0, v98
	v_exp_f32_e32 v88, v88
	v_exp_f32_e32 v98, v84
	v_rcp_f32_e32 v82, v82
	v_rcp_f32_e32 v86, v86
	v_rcp_f32_e32 v87, v87
	v_mul_f32_e32 v89, 0xbfb8aa3b, v89
	v_mul_f32_e32 v85, 0xbfb8aa3b, v85
	v_rcp_f32_e32 v90, v90
	v_rcp_f32_e32 v94, v94
	v_rcp_f32_e32 v95, v95
	v_add_f32_e32 v84, 1.0, v88
	v_add_f32_e32 v88, 1.0, v98
	v_exp_f32_e32 v89, v89
	v_exp_f32_e32 v98, v85
	v_pk_fma_f32 v[86:87], v[86:87], s[16:17], 0.5 op_sel_hi:[1,0,0]
	v_pk_fma_f32 v[82:83], v[82:83], s[16:17], 0.5 op_sel_hi:[1,0,0]
	v_rcp_f32_e32 v92, v92
	v_rcp_f32_e32 v85, v88
	v_add_f32_e32 v88, 1.0, v89
	v_add_f32_e32 v89, 1.0, v98
	v_pk_fma_f32 v[94:95], v[94:95], s[16:17], 0.5 op_sel_hi:[1,0,0]
	v_cvt_u32_f32_e32 v98, v87
	v_cvt_u32_f32_e32 v99, v86
	v_pk_fma_f32 v[86:87], v[90:91], s[16:17], 0.5 op_sel_hi:[1,0,0]
	v_cvt_u32_f32_e32 v82, v82
	v_cvt_u32_f32_e32 v83, v83
	v_rcp_f32_e32 v96, v96
	v_rcp_f32_e32 v97, v97
	v_rcp_f32_e32 v84, v84
	v_cvt_u32_f32_e32 v95, v95
	v_cvt_u32_f32_e32 v94, v94
	v_cvt_u32_f32_e32 v86, v86
	v_cvt_u32_f32_e32 v87, v87
	v_rcp_f32_e32 v88, v88
	v_rcp_f32_e32 v89, v89
	v_lshl_or_b32 v90, v99, 8, v82
	v_lshl_or_b32 v91, v98, 8, v83
	v_pk_fma_f32 v[82:83], v[92:93], s[16:17], 0.5 op_sel_hi:[1,0,0]
	v_lshl_or_b32 v86, v94, 8, v86
	v_lshl_or_b32 v87, v95, 8, v87
	v_pk_fma_f32 v[84:85], v[84:85], s[16:17], 0.5 op_sel_hi:[1,0,0]
	v_cvt_u32_f32_sdwa v94, v83 dst_sel:WORD_1 dst_unused:UNUSED_PAD src0_sel:DWORD
	v_cvt_u32_f32_sdwa v95, v82 dst_sel:WORD_1 dst_unused:UNUSED_PAD src0_sel:DWORD
	v_pk_fma_f32 v[82:83], v[96:97], s[16:17], 0.5 op_sel_hi:[1,0,0]
	v_cvt_u32_f32_sdwa v92, v85 dst_sel:WORD_1 dst_unused:UNUSED_PAD src0_sel:DWORD
	v_cvt_u32_f32_sdwa v93, v84 dst_sel:WORD_1 dst_unused:UNUSED_PAD src0_sel:DWORD
	v_pk_fma_f32 v[84:85], v[88:89], s[16:17], 0.5 op_sel_hi:[1,0,0]
	v_cvt_u32_f32_sdwa v82, v82 dst_sel:BYTE_3 dst_unused:UNUSED_PAD src0_sel:DWORD
	v_cvt_u32_f32_sdwa v85, v85 dst_sel:BYTE_3 dst_unused:UNUSED_PAD src0_sel:DWORD
	v_cvt_u32_f32_sdwa v84, v84 dst_sel:BYTE_3 dst_unused:UNUSED_PAD src0_sel:DWORD
	v_cvt_u32_f32_sdwa v83, v83 dst_sel:BYTE_3 dst_unused:UNUSED_PAD src0_sel:DWORD
	v_or3_b32 v82, v86, v95, v82
	v_add_co_u32_e32 v86, vcc, s81, v156
	v_mul_f32_e32 v78, 0xbfb8aa3b, v78
	v_mul_f32_e32 v74, 0xbfb8aa3b, v74
	v_or3_b32 v85, v91, v92, v85
	v_or3_b32 v84, v90, v93, v84
	v_or3_b32 v83, v87, v94, v83
	v_addc_co_u32_e32 v87, vcc, 0, v157, vcc
	v_exp_f32_e32 v78, v78
	v_exp_f32_e32 v88, v74
	v_mul_f32_e32 v79, 0xbfb8aa3b, v79
	v_mul_f32_e32 v75, 0xbfb8aa3b, v75
	global_store_dwordx4 v[86:87], v[82:85], off
	v_exp_f32_e32 v79, v79
	v_add_f32_e32 v74, 1.0, v78
	v_exp_f32_e32 v82, v75
	v_add_f32_e32 v78, 1.0, v88
	v_mul_f32_e32 v80, 0xbfb8aa3b, v80
	v_mul_f32_e32 v76, 0xbfb8aa3b, v76
	v_rcp_f32_e32 v75, v78
	v_add_f32_e32 v78, 1.0, v79
	v_add_f32_e32 v79, 1.0, v82
	v_exp_f32_e32 v80, v80
	v_exp_f32_e32 v82, v76
	v_mul_f32_e32 v81, 0xbfb8aa3b, v81
	v_mul_f32_e32 v77, 0xbfb8aa3b, v77
	v_add_f32_e32 v76, 1.0, v80
	v_add_f32_e32 v80, 1.0, v82
	v_exp_f32_e32 v81, v81
	v_exp_f32_e32 v82, v77
	v_mul_f32_e32 v70, 0xbfb8aa3b, v70
	v_mul_f32_e32 v66, 0xbfb8aa3b, v66
	v_rcp_f32_e32 v77, v80
	v_add_f32_e32 v80, 1.0, v81
	v_add_f32_e32 v81, 1.0, v82
	v_exp_f32_e32 v70, v70
	v_exp_f32_e32 v82, v66
	v_mul_f32_e32 v71, 0xbfb8aa3b, v71
	v_mul_f32_e32 v67, 0xbfb8aa3b, v67
	v_add_f32_e32 v66, 1.0, v70
	v_add_f32_e32 v70, 1.0, v82
	v_exp_f32_e32 v71, v71
	v_exp_f32_e32 v82, v67
	v_mul_f32_e32 v72, 0xbfb8aa3b, v72
	v_mul_f32_e32 v68, 0xbfb8aa3b, v68
	v_rcp_f32_e32 v67, v70
	v_add_f32_e32 v70, 1.0, v71
	v_add_f32_e32 v71, 1.0, v82
	v_exp_f32_e32 v72, v72
	v_exp_f32_e32 v82, v68
	v_rcp_f32_e32 v66, v66
	v_rcp_f32_e32 v70, v70
	v_rcp_f32_e32 v71, v71
	v_mul_f32_e32 v73, 0xbfb8aa3b, v73
	v_mul_f32_e32 v69, 0xbfb8aa3b, v69
	v_rcp_f32_e32 v74, v74
	v_rcp_f32_e32 v78, v78
	v_rcp_f32_e32 v79, v79
	v_add_f32_e32 v68, 1.0, v72
	v_add_f32_e32 v72, 1.0, v82
	v_exp_f32_e32 v73, v73
	v_exp_f32_e32 v82, v69
	v_pk_fma_f32 v[70:71], v[70:71], s[16:17], 0.5 op_sel_hi:[1,0,0]
	v_pk_fma_f32 v[66:67], v[66:67], s[16:17], 0.5 op_sel_hi:[1,0,0]
	v_rcp_f32_e32 v76, v76
	v_rcp_f32_e32 v69, v72
	v_add_f32_e32 v72, 1.0, v73
	v_add_f32_e32 v73, 1.0, v82
	v_pk_fma_f32 v[78:79], v[78:79], s[16:17], 0.5 op_sel_hi:[1,0,0]
	v_cvt_u32_f32_e32 v82, v71
	v_cvt_u32_f32_e32 v83, v70
	v_pk_fma_f32 v[70:71], v[74:75], s[16:17], 0.5 op_sel_hi:[1,0,0]
	v_cvt_u32_f32_e32 v66, v66
	v_cvt_u32_f32_e32 v67, v67
	v_rcp_f32_e32 v80, v80
	v_rcp_f32_e32 v81, v81
	v_rcp_f32_e32 v68, v68
	v_cvt_u32_f32_e32 v79, v79
	v_cvt_u32_f32_e32 v78, v78
	v_cvt_u32_f32_e32 v70, v70
	v_cvt_u32_f32_e32 v71, v71
; __device__ __forceinline__ float sigmoidf_fast(float x) { return __builtin_amdgcn_rcpf(1.0f + __builtin_amdgcn_exp2f(-1.4426950408889634f * x)); }
;     __device__ __forceinline__ void operator()(const f32x4 (&acc)[2][2][4][2], const Unit& u, int wr, int wc, int fr, int fq) const {
;     ...
;                 for (int m = 0; m < 4; ++m) { unsigned q[16];
; #pragma unroll
;                     for (int bj = 0; bj < 2; ++bj) { const f32x4 v0 = acc[ai][bj][m][0], v1 = acc[ai][bj][m][1];
; #pragma unroll
;                         for (int e = 0; e < 4; ++e) { q[8 * bj + e] = (unsigned)fmaf(sigmoidf_fast(v0[e]), 255.0f, 0.5f); q[8 * bj + 4 + e] = (unsigned)fmaf(sigmoidf_fast(v1[e]), 255.0f, 0.5f); } }
;                     u32x4 w; w.x = q[0] | (q[1] << 8) | (q[2] << 16) | (q[3] << 24); w.y = q[4] | (q[5] << 8) | (q[6] << 16) | (q[7] << 24);
;                     w.z = q[8] | (q[9] << 8) | (q[10] << 16) | (q[11] << 24); w.w = q[12] | (q[13] << 8) | (q[14] << 16) | (q[15] << 24);
;                     gp[(ai * 4 + m) * 512] = w; }
	v_rcp_f32_e32 v72, v72
	v_rcp_f32_e32 v73, v73
	v_lshl_or_b32 v74, v83, 8, v66
	v_lshl_or_b32 v75, v82, 8, v67
	v_pk_fma_f32 v[66:67], v[76:77], s[16:17], 0.5 op_sel_hi:[1,0,0]
	v_lshl_or_b32 v70, v78, 8, v70
	v_lshl_or_b32 v71, v79, 8, v71
	v_pk_fma_f32 v[68:69], v[68:69], s[16:17], 0.5 op_sel_hi:[1,0,0]
	v_cvt_u32_f32_sdwa v78, v67 dst_sel:WORD_1 dst_unused:UNUSED_PAD src0_sel:DWORD
	v_cvt_u32_f32_sdwa v79, v66 dst_sel:WORD_1 dst_unused:UNUSED_PAD src0_sel:DWORD
	v_pk_fma_f32 v[66:67], v[80:81], s[16:17], 0.5 op_sel_hi:[1,0,0]
	v_cvt_u32_f32_sdwa v76, v69 dst_sel:WORD_1 dst_unused:UNUSED_PAD src0_sel:DWORD
	v_cvt_u32_f32_sdwa v77, v68 dst_sel:WORD_1 dst_unused:UNUSED_PAD src0_sel:DWORD
	v_pk_fma_f32 v[68:69], v[72:73], s[16:17], 0.5 op_sel_hi:[1,0,0]
	v_cvt_u32_f32_sdwa v66, v66 dst_sel:BYTE_3 dst_unused:UNUSED_PAD src0_sel:DWORD
	v_cvt_u32_f32_sdwa v69, v69 dst_sel:BYTE_3 dst_unused:UNUSED_PAD src0_sel:DWORD
	v_cvt_u32_f32_sdwa v68, v68 dst_sel:BYTE_3 dst_unused:UNUSED_PAD src0_sel:DWORD
	v_cvt_u32_f32_sdwa v67, v67 dst_sel:BYTE_3 dst_unused:UNUSED_PAD src0_sel:DWORD
	s_movk_i32 s7, 0x6000
	v_or3_b32 v66, v70, v79, v66
	v_add_co_u32_e32 v70, vcc, s7, v156
	v_mul_f32_e32 v62, 0xbfb8aa3b, v62
	v_mul_f32_e32 v58, 0xbfb8aa3b, v58
	v_or3_b32 v69, v75, v76, v69
	v_or3_b32 v68, v74, v77, v68
	v_or3_b32 v67, v71, v78, v67
	v_addc_co_u32_e32 v71, vcc, 0, v157, vcc
	v_exp_f32_e32 v62, v62
	v_exp_f32_e32 v72, v58
	v_mul_f32_e32 v63, 0xbfb8aa3b, v63
	v_mul_f32_e32 v59, 0xbfb8aa3b, v59
	global_store_dwordx4 v[70:71], v[66:69], off
	v_exp_f32_e32 v63, v63
	v_add_f32_e32 v58, 1.0, v62
	v_exp_f32_e32 v66, v59
	v_add_f32_e32 v62, 1.0, v72
	v_mul_f32_e32 v64, 0xbfb8aa3b, v64
	v_mul_f32_e32 v60, 0xbfb8aa3b, v60
	v_rcp_f32_e32 v59, v62
	v_add_f32_e32 v62, 1.0, v63
	v_add_f32_e32 v63, 1.0, v66
	v_exp_f32_e32 v64, v64
	v_exp_f32_e32 v66, v60
	v_mul_f32_e32 v65, 0xbfb8aa3b, v65
	v_mul_f32_e32 v61, 0xbfb8aa3b, v61
	v_add_f32_e32 v60, 1.0, v64
	v_add_f32_e32 v64, 1.0, v66
	v_exp_f32_e32 v65, v65
	v_exp_f32_e32 v66, v61
	v_mul_f32_e32 v54, 0xbfb8aa3b, v54
	v_mul_f32_e32 v50, 0xbfb8aa3b, v50
	v_rcp_f32_e32 v61, v64
	v_add_f32_e32 v64, 1.0, v65
	v_add_f32_e32 v65, 1.0, v66
	v_exp_f32_e32 v54, v54
	v_exp_f32_e32 v66, v50
	v_mul_f32_e32 v55, 0xbfb8aa3b, v55
	v_mul_f32_e32 v51, 0xbfb8aa3b, v51
	v_add_f32_e32 v50, 1.0, v54
	v_add_f32_e32 v54, 1.0, v66
	v_exp_f32_e32 v55, v55
	v_exp_f32_e32 v66, v51
	v_mul_f32_e32 v56, 0xbfb8aa3b, v56
	v_mul_f32_e32 v52, 0xbfb8aa3b, v52
	v_rcp_f32_e32 v51, v54
	v_add_f32_e32 v54, 1.0, v55
	v_add_f32_e32 v55, 1.0, v66
	v_exp_f32_e32 v56, v56
	v_exp_f32_e32 v66, v52
	v_rcp_f32_e32 v50, v50
	v_rcp_f32_e32 v54, v54
	v_rcp_f32_e32 v55, v55
	v_mul_f32_e32 v57, 0xbfb8aa3b, v57
	v_mul_f32_e32 v53, 0xbfb8aa3b, v53
	v_rcp_f32_e32 v58, v58
	v_rcp_f32_e32 v62, v62
	v_rcp_f32_e32 v63, v63
	v_add_f32_e32 v52, 1.0, v56
	v_add_f32_e32 v56, 1.0, v66
	v_exp_f32_e32 v57, v57
	v_exp_f32_e32 v66, v53
	v_pk_fma_f32 v[54:55], v[54:55], s[16:17], 0.5 op_sel_hi:[1,0,0]
	v_pk_fma_f32 v[50:51], v[50:51], s[16:17], 0.5 op_sel_hi:[1,0,0]
	v_rcp_f32_e32 v60, v60
	v_rcp_f32_e32 v53, v56
	v_add_f32_e32 v56, 1.0, v57
	v_add_f32_e32 v57, 1.0, v66
	v_pk_fma_f32 v[62:63], v[62:63], s[16:17], 0.5 op_sel_hi:[1,0,0]
	v_cvt_u32_f32_e32 v66, v55
	v_cvt_u32_f32_e32 v67, v54
	v_pk_fma_f32 v[54:55], v[58:59], s[16:17], 0.5 op_sel_hi:[1,0,0]
	v_cvt_u32_f32_e32 v50, v50
	v_cvt_u32_f32_e32 v51, v51
	v_rcp_f32_e32 v64, v64
	v_rcp_f32_e32 v65, v65
	v_rcp_f32_e32 v52, v52
	v_cvt_u32_f32_e32 v63, v63
	v_cvt_u32_f32_e32 v62, v62
	v_cvt_u32_f32_e32 v54, v54
	v_cvt_u32_f32_e32 v55, v55
	v_rcp_f32_e32 v56, v56
	v_rcp_f32_e32 v57, v57
	v_lshl_or_b32 v58, v67, 8, v50
	v_lshl_or_b32 v59, v66, 8, v51
	v_pk_fma_f32 v[50:51], v[60:61], s[16:17], 0.5 op_sel_hi:[1,0,0]
	v_lshl_or_b32 v54, v62, 8, v54
	v_lshl_or_b32 v55, v63, 8, v55
	v_pk_fma_f32 v[52:53], v[52:53], s[16:17], 0.5 op_sel_hi:[1,0,0]
	v_cvt_u32_f32_sdwa v62, v51 dst_sel:WORD_1 dst_unused:UNUSED_PAD src0_sel:DWORD
	v_cvt_u32_f32_sdwa v63, v50 dst_sel:WORD_1 dst_unused:UNUSED_PAD src0_sel:DWORD
	v_pk_fma_f32 v[50:51], v[64:65], s[16:17], 0.5 op_sel_hi:[1,0,0]
	v_cvt_u32_f32_sdwa v60, v53 dst_sel:WORD_1 dst_unused:UNUSED_PAD src0_sel:DWORD
	v_cvt_u32_f32_sdwa v61, v52 dst_sel:WORD_1 dst_unused:UNUSED_PAD src0_sel:DWORD
	v_pk_fma_f32 v[52:53], v[56:57], s[16:17], 0.5 op_sel_hi:[1,0,0]
	v_cvt_u32_f32_sdwa v50, v50 dst_sel:BYTE_3 dst_unused:UNUSED_PAD src0_sel:DWORD
	v_cvt_u32_f32_sdwa v53, v53 dst_sel:BYTE_3 dst_unused:UNUSED_PAD src0_sel:DWORD
	v_cvt_u32_f32_sdwa v52, v52 dst_sel:BYTE_3 dst_unused:UNUSED_PAD src0_sel:DWORD
	v_cvt_u32_f32_sdwa v51, v51 dst_sel:BYTE_3 dst_unused:UNUSED_PAD src0_sel:DWORD
	s_mov_b32 s7, 0x8000
	v_or3_b32 v50, v54, v63, v50
	v_add_co_u32_e32 v54, vcc, s7, v156
	v_mul_f32_e32 v46, 0xbfb8aa3b, v46
	v_mul_f32_e32 v42, 0xbfb8aa3b, v42
	v_or3_b32 v53, v59, v60, v53
	v_or3_b32 v52, v58, v61, v52
	v_or3_b32 v51, v55, v62, v51
	v_addc_co_u32_e32 v55, vcc, 0, v157, vcc
	v_exp_f32_e32 v46, v46
	v_exp_f32_e32 v56, v42
	v_mul_f32_e32 v47, 0xbfb8aa3b, v47
	v_mul_f32_e32 v43, 0xbfb8aa3b, v43
	global_store_dwordx4 v[54:55], v[50:53], off
	v_exp_f32_e32 v47, v47
	v_add_f32_e32 v42, 1.0, v46
	v_exp_f32_e32 v50, v43
	v_add_f32_e32 v46, 1.0, v56
	v_mul_f32_e32 v48, 0xbfb8aa3b, v48
	v_mul_f32_e32 v44, 0xbfb8aa3b, v44
	v_rcp_f32_e32 v43, v46
	v_add_f32_e32 v46, 1.0, v47
	v_add_f32_e32 v47, 1.0, v50
	v_exp_f32_e32 v48, v48
	v_exp_f32_e32 v50, v44
	v_mul_f32_e32 v49, 0xbfb8aa3b, v49
	v_mul_f32_e32 v45, 0xbfb8aa3b, v45
	v_add_f32_e32 v44, 1.0, v48
	v_add_f32_e32 v48, 1.0, v50
	v_exp_f32_e32 v49, v49
	v_exp_f32_e32 v50, v45
; __device__ __forceinline__ float sigmoidf_fast(float x) { return __builtin_amdgcn_rcpf(1.0f + __builtin_amdgcn_exp2f(-1.4426950408889634f * x)); }
;     __device__ __forceinline__ void operator()(const f32x4 (&acc)[2][2][4][2], const Unit& u, int wr, int wc, int fr, int fq) const {
;     ...
;                 for (int m = 0; m < 4; ++m) { unsigned q[16];
; #pragma unroll
;                     for (int bj = 0; bj < 2; ++bj) { const f32x4 v0 = acc[ai][bj][m][0], v1 = acc[ai][bj][m][1];
; #pragma unroll
;                         for (int e = 0; e < 4; ++e) { q[8 * bj + e] = (unsigned)fmaf(sigmoidf_fast(v0[e]), 255.0f, 0.5f); q[8 * bj + 4 + e] = (unsigned)fmaf(sigmoidf_fast(v1[e]), 255.0f, 0.5f); } }
;                     u32x4 w; w.x = q[0] | (q[1] << 8) | (q[2] << 16) | (q[3] << 24); w.y = q[4] | (q[5] << 8) | (q[6] << 16) | (q[7] << 24);
;                     w.z = q[8] | (q[9] << 8) | (q[10] << 16) | (q[11] << 24); w.w = q[12] | (q[13] << 8) | (q[14] << 16) | (q[15] << 24);
;                     gp[(ai * 4 + m) * 512] = w; }
	v_mul_f32_e32 v38, 0xbfb8aa3b, v38
	v_mul_f32_e32 v34, 0xbfb8aa3b, v34
	v_rcp_f32_e32 v45, v48
	v_add_f32_e32 v48, 1.0, v49
	v_add_f32_e32 v49, 1.0, v50
	v_exp_f32_e32 v38, v38
	v_exp_f32_e32 v50, v34
	v_mul_f32_e32 v39, 0xbfb8aa3b, v39
	v_mul_f32_e32 v35, 0xbfb8aa3b, v35
	v_add_f32_e32 v34, 1.0, v38
	v_add_f32_e32 v38, 1.0, v50
	v_exp_f32_e32 v39, v39
	v_exp_f32_e32 v50, v35
	v_mul_f32_e32 v40, 0xbfb8aa3b, v40
	v_mul_f32_e32 v36, 0xbfb8aa3b, v36
	v_rcp_f32_e32 v35, v38
	v_add_f32_e32 v38, 1.0, v39
	v_add_f32_e32 v39, 1.0, v50
	v_exp_f32_e32 v40, v40
	v_exp_f32_e32 v50, v36
	v_rcp_f32_e32 v34, v34
	v_rcp_f32_e32 v38, v38
	v_rcp_f32_e32 v39, v39
	v_mul_f32_e32 v41, 0xbfb8aa3b, v41
	v_mul_f32_e32 v37, 0xbfb8aa3b, v37
	v_rcp_f32_e32 v42, v42
	v_rcp_f32_e32 v46, v46
	v_rcp_f32_e32 v47, v47
	v_add_f32_e32 v36, 1.0, v40
	v_add_f32_e32 v40, 1.0, v50
	v_exp_f32_e32 v41, v41
	v_exp_f32_e32 v50, v37
	v_pk_fma_f32 v[38:39], v[38:39], s[16:17], 0.5 op_sel_hi:[1,0,0]
	v_pk_fma_f32 v[34:35], v[34:35], s[16:17], 0.5 op_sel_hi:[1,0,0]
	v_rcp_f32_e32 v44, v44
	v_rcp_f32_e32 v37, v40
	v_add_f32_e32 v40, 1.0, v41
	v_add_f32_e32 v41, 1.0, v50
	v_pk_fma_f32 v[46:47], v[46:47], s[16:17], 0.5 op_sel_hi:[1,0,0]
	v_cvt_u32_f32_e32 v50, v39
	v_cvt_u32_f32_e32 v51, v38
	v_pk_fma_f32 v[38:39], v[42:43], s[16:17], 0.5 op_sel_hi:[1,0,0]
	v_cvt_u32_f32_e32 v34, v34
	v_cvt_u32_f32_e32 v35, v35
	v_rcp_f32_e32 v48, v48
	v_rcp_f32_e32 v49, v49
	v_rcp_f32_e32 v36, v36
	v_cvt_u32_f32_e32 v47, v47
	v_cvt_u32_f32_e32 v46, v46
	v_cvt_u32_f32_e32 v38, v38
	v_cvt_u32_f32_e32 v39, v39
	v_rcp_f32_e32 v40, v40
	v_rcp_f32_e32 v41, v41
	v_lshl_or_b32 v42, v51, 8, v34
	v_lshl_or_b32 v43, v50, 8, v35
	v_pk_fma_f32 v[34:35], v[44:45], s[16:17], 0.5 op_sel_hi:[1,0,0]
	v_lshl_or_b32 v38, v46, 8, v38
	v_lshl_or_b32 v39, v47, 8, v39
	v_pk_fma_f32 v[36:37], v[36:37], s[16:17], 0.5 op_sel_hi:[1,0,0]
	v_cvt_u32_f32_sdwa v46, v35 dst_sel:WORD_1 dst_unused:UNUSED_PAD src0_sel:DWORD
	v_cvt_u32_f32_sdwa v47, v34 dst_sel:WORD_1 dst_unused:UNUSED_PAD src0_sel:DWORD
	v_pk_fma_f32 v[34:35], v[48:49], s[16:17], 0.5 op_sel_hi:[1,0,0]
	v_cvt_u32_f32_sdwa v44, v37 dst_sel:WORD_1 dst_unused:UNUSED_PAD src0_sel:DWORD
	v_cvt_u32_f32_sdwa v45, v36 dst_sel:WORD_1 dst_unused:UNUSED_PAD src0_sel:DWORD
	v_pk_fma_f32 v[36:37], v[40:41], s[16:17], 0.5 op_sel_hi:[1,0,0]
	v_cvt_u32_f32_sdwa v34, v34 dst_sel:BYTE_3 dst_unused:UNUSED_PAD src0_sel:DWORD
	v_cvt_u32_f32_sdwa v37, v37 dst_sel:BYTE_3 dst_unused:UNUSED_PAD src0_sel:DWORD
	v_cvt_u32_f32_sdwa v36, v36 dst_sel:BYTE_3 dst_unused:UNUSED_PAD src0_sel:DWORD
	v_cvt_u32_f32_sdwa v35, v35 dst_sel:BYTE_3 dst_unused:UNUSED_PAD src0_sel:DWORD
	s_mov_b32 s7, 0xa000
	v_or3_b32 v34, v38, v47, v34
	v_add_co_u32_e32 v38, vcc, s7, v156
	v_mul_f32_e32 v30, 0xbfb8aa3b, v30
	v_mul_f32_e32 v26, 0xbfb8aa3b, v26
	v_or3_b32 v37, v43, v44, v37
	v_or3_b32 v36, v42, v45, v36
	v_or3_b32 v35, v39, v46, v35
	v_addc_co_u32_e32 v39, vcc, 0, v157, vcc
	v_exp_f32_e32 v30, v30
	v_exp_f32_e32 v40, v26
	v_mul_f32_e32 v31, 0xbfb8aa3b, v31
	v_mul_f32_e32 v27, 0xbfb8aa3b, v27
	global_store_dwordx4 v[38:39], v[34:37], off
	v_exp_f32_e32 v31, v31
	v_add_f32_e32 v26, 1.0, v30
	v_exp_f32_e32 v34, v27
	v_add_f32_e32 v30, 1.0, v40
	v_mul_f32_e32 v32, 0xbfb8aa3b, v32
	v_mul_f32_e32 v28, 0xbfb8aa3b, v28
	v_rcp_f32_e32 v27, v30
	v_add_f32_e32 v30, 1.0, v31
	v_add_f32_e32 v31, 1.0, v34
	v_exp_f32_e32 v32, v32
	v_exp_f32_e32 v34, v28
	v_mul_f32_e32 v33, 0xbfb8aa3b, v33
	v_mul_f32_e32 v29, 0xbfb8aa3b, v29
	v_add_f32_e32 v28, 1.0, v32
	v_add_f32_e32 v32, 1.0, v34
	v_exp_f32_e32 v33, v33
	v_exp_f32_e32 v34, v29
	v_mul_f32_e32 v22, 0xbfb8aa3b, v22
	v_mul_f32_e32 v18, 0xbfb8aa3b, v18
	v_rcp_f32_e32 v29, v32
	v_add_f32_e32 v32, 1.0, v33
	v_add_f32_e32 v33, 1.0, v34
	v_exp_f32_e32 v22, v22
	v_exp_f32_e32 v34, v18
	v_mul_f32_e32 v23, 0xbfb8aa3b, v23
	v_mul_f32_e32 v19, 0xbfb8aa3b, v19
	v_add_f32_e32 v18, 1.0, v22
	v_add_f32_e32 v22, 1.0, v34
	v_exp_f32_e32 v23, v23
	v_exp_f32_e32 v34, v19
	v_mul_f32_e32 v24, 0xbfb8aa3b, v24
	v_mul_f32_e32 v20, 0xbfb8aa3b, v20
	v_rcp_f32_e32 v19, v22
	v_add_f32_e32 v22, 1.0, v23
	v_add_f32_e32 v23, 1.0, v34
	v_exp_f32_e32 v24, v24
	v_exp_f32_e32 v34, v20
	v_rcp_f32_e32 v18, v18
	v_rcp_f32_e32 v22, v22
	v_rcp_f32_e32 v23, v23
	v_mul_f32_e32 v25, 0xbfb8aa3b, v25
	v_mul_f32_e32 v21, 0xbfb8aa3b, v21
	v_rcp_f32_e32 v26, v26
	v_rcp_f32_e32 v30, v30
	v_rcp_f32_e32 v31, v31
	v_add_f32_e32 v20, 1.0, v24
	v_add_f32_e32 v24, 1.0, v34
	v_exp_f32_e32 v25, v25
	v_exp_f32_e32 v34, v21
	v_pk_fma_f32 v[22:23], v[22:23], s[16:17], 0.5 op_sel_hi:[1,0,0]
	v_pk_fma_f32 v[18:19], v[18:19], s[16:17], 0.5 op_sel_hi:[1,0,0]
	v_rcp_f32_e32 v28, v28
	v_rcp_f32_e32 v21, v24
	v_add_f32_e32 v24, 1.0, v25
	v_add_f32_e32 v25, 1.0, v34
	v_pk_fma_f32 v[30:31], v[30:31], s[16:17], 0.5 op_sel_hi:[1,0,0]
	v_cvt_u32_f32_e32 v34, v23
	v_cvt_u32_f32_e32 v35, v22
	v_pk_fma_f32 v[22:23], v[26:27], s[16:17], 0.5 op_sel_hi:[1,0,0]
	v_cvt_u32_f32_e32 v18, v18
	v_cvt_u32_f32_e32 v19, v19
	v_rcp_f32_e32 v32, v32
	v_rcp_f32_e32 v33, v33
; __device__ __forceinline__ float sigmoidf_fast(float x) { return __builtin_amdgcn_rcpf(1.0f + __builtin_amdgcn_exp2f(-1.4426950408889634f * x)); }
;     __device__ __forceinline__ void operator()(const f32x4 (&acc)[2][2][4][2], const Unit& u, int wr, int wc, int fr, int fq) const {
;     ...
;                 for (int m = 0; m < 4; ++m) { unsigned q[16];
; #pragma unroll
;                     for (int bj = 0; bj < 2; ++bj) { const f32x4 v0 = acc[ai][bj][m][0], v1 = acc[ai][bj][m][1];
; #pragma unroll
;                         for (int e = 0; e < 4; ++e) { q[8 * bj + e] = (unsigned)fmaf(sigmoidf_fast(v0[e]), 255.0f, 0.5f); q[8 * bj + 4 + e] = (unsigned)fmaf(sigmoidf_fast(v1[e]), 255.0f, 0.5f); } }
;                     u32x4 w; w.x = q[0] | (q[1] << 8) | (q[2] << 16) | (q[3] << 24); w.y = q[4] | (q[5] << 8) | (q[6] << 16) | (q[7] << 24);
;                     w.z = q[8] | (q[9] << 8) | (q[10] << 16) | (q[11] << 24); w.w = q[12] | (q[13] << 8) | (q[14] << 16) | (q[15] << 24);
;                     gp[(ai * 4 + m) * 512] = w; }
;             return;
	v_rcp_f32_e32 v20, v20
	v_cvt_u32_f32_e32 v31, v31
	v_cvt_u32_f32_e32 v30, v30
	v_cvt_u32_f32_e32 v22, v22
	v_cvt_u32_f32_e32 v23, v23
	v_rcp_f32_e32 v24, v24
	v_rcp_f32_e32 v25, v25
	v_lshl_or_b32 v26, v35, 8, v18
	v_lshl_or_b32 v27, v34, 8, v19
	v_pk_fma_f32 v[18:19], v[28:29], s[16:17], 0.5 op_sel_hi:[1,0,0]
	v_lshl_or_b32 v22, v30, 8, v22
	v_lshl_or_b32 v23, v31, 8, v23
	v_pk_fma_f32 v[20:21], v[20:21], s[16:17], 0.5 op_sel_hi:[1,0,0]
	v_cvt_u32_f32_sdwa v30, v19 dst_sel:WORD_1 dst_unused:UNUSED_PAD src0_sel:DWORD
	v_cvt_u32_f32_sdwa v31, v18 dst_sel:WORD_1 dst_unused:UNUSED_PAD src0_sel:DWORD
	v_pk_fma_f32 v[18:19], v[32:33], s[16:17], 0.5 op_sel_hi:[1,0,0]
	v_cvt_u32_f32_sdwa v28, v21 dst_sel:WORD_1 dst_unused:UNUSED_PAD src0_sel:DWORD
	v_cvt_u32_f32_sdwa v29, v20 dst_sel:WORD_1 dst_unused:UNUSED_PAD src0_sel:DWORD
	v_pk_fma_f32 v[20:21], v[24:25], s[16:17], 0.5 op_sel_hi:[1,0,0]
	v_cvt_u32_f32_sdwa v18, v18 dst_sel:BYTE_3 dst_unused:UNUSED_PAD src0_sel:DWORD
	v_cvt_u32_f32_sdwa v21, v21 dst_sel:BYTE_3 dst_unused:UNUSED_PAD src0_sel:DWORD
	v_cvt_u32_f32_sdwa v20, v20 dst_sel:BYTE_3 dst_unused:UNUSED_PAD src0_sel:DWORD
	v_cvt_u32_f32_sdwa v19, v19 dst_sel:BYTE_3 dst_unused:UNUSED_PAD src0_sel:DWORD
	s_mov_b32 s7, 0xc000
	v_or3_b32 v18, v22, v31, v18
	v_add_co_u32_e32 v22, vcc, s7, v156
	v_mul_f32_e32 v14, 0xbfb8aa3b, v14
	v_mul_f32_e32 v10, 0xbfb8aa3b, v10
	v_or3_b32 v21, v27, v28, v21
	v_or3_b32 v20, v26, v29, v20
	v_or3_b32 v19, v23, v30, v19
	v_addc_co_u32_e32 v23, vcc, 0, v157, vcc
	v_exp_f32_e32 v14, v14
	v_exp_f32_e32 v24, v10
	v_mul_f32_e32 v15, 0xbfb8aa3b, v15
	v_mul_f32_e32 v11, 0xbfb8aa3b, v11
	global_store_dwordx4 v[22:23], v[18:21], off
	v_exp_f32_e32 v15, v15
	v_add_f32_e32 v10, 1.0, v14
	v_exp_f32_e32 v18, v11
	v_add_f32_e32 v14, 1.0, v24
	v_mul_f32_e32 v16, 0xbfb8aa3b, v16
	v_mul_f32_e32 v12, 0xbfb8aa3b, v12
	v_rcp_f32_e32 v11, v14
	v_add_f32_e32 v14, 1.0, v15
	v_add_f32_e32 v15, 1.0, v18
	v_exp_f32_e32 v16, v16
	v_exp_f32_e32 v18, v12
	v_mul_f32_e32 v17, 0xbfb8aa3b, v17
	v_mul_f32_e32 v13, 0xbfb8aa3b, v13
	v_add_f32_e32 v12, 1.0, v16
	v_add_f32_e32 v16, 1.0, v18
	v_exp_f32_e32 v17, v17
	v_exp_f32_e32 v18, v13
	v_mul_f32_e32 v6, 0xbfb8aa3b, v6
	v_mul_f32_e32 v2, 0xbfb8aa3b, v2
	v_rcp_f32_e32 v13, v16
	v_add_f32_e32 v16, 1.0, v17
	v_add_f32_e32 v17, 1.0, v18
	v_exp_f32_e32 v6, v6
	v_exp_f32_e32 v18, v2
	v_mul_f32_e32 v7, 0xbfb8aa3b, v7
	v_mul_f32_e32 v3, 0xbfb8aa3b, v3
	v_add_f32_e32 v2, 1.0, v6
	v_add_f32_e32 v6, 1.0, v18
	v_exp_f32_e32 v7, v7
	v_exp_f32_e32 v18, v3
	v_mul_f32_e32 v8, 0xbfb8aa3b, v8
	v_mul_f32_e32 v4, 0xbfb8aa3b, v4
	v_rcp_f32_e32 v3, v6
	v_add_f32_e32 v6, 1.0, v7
	v_add_f32_e32 v7, 1.0, v18
	v_exp_f32_e32 v8, v8
	v_exp_f32_e32 v18, v4
	v_rcp_f32_e32 v2, v2
	v_rcp_f32_e32 v6, v6
	v_rcp_f32_e32 v7, v7
	v_mul_f32_e32 v9, 0xbfb8aa3b, v9
	v_mul_f32_e32 v5, 0xbfb8aa3b, v5
	v_rcp_f32_e32 v10, v10
	v_rcp_f32_e32 v14, v14
	v_rcp_f32_e32 v15, v15
	v_add_f32_e32 v4, 1.0, v8
	v_add_f32_e32 v8, 1.0, v18
	v_exp_f32_e32 v9, v9
	v_exp_f32_e32 v18, v5
	v_pk_fma_f32 v[6:7], v[6:7], s[16:17], 0.5 op_sel_hi:[1,0,0]
	v_pk_fma_f32 v[2:3], v[2:3], s[16:17], 0.5 op_sel_hi:[1,0,0]
	v_rcp_f32_e32 v12, v12
	v_rcp_f32_e32 v5, v8
	v_add_f32_e32 v8, 1.0, v9
	v_add_f32_e32 v9, 1.0, v18
	v_pk_fma_f32 v[14:15], v[14:15], s[16:17], 0.5 op_sel_hi:[1,0,0]
	v_cvt_u32_f32_e32 v18, v7
	v_cvt_u32_f32_e32 v19, v6
	v_pk_fma_f32 v[6:7], v[10:11], s[16:17], 0.5 op_sel_hi:[1,0,0]
	v_cvt_u32_f32_e32 v2, v2
	v_cvt_u32_f32_e32 v3, v3
	v_rcp_f32_e32 v16, v16
	v_rcp_f32_e32 v17, v17
	v_rcp_f32_e32 v4, v4
	v_cvt_u32_f32_e32 v15, v15
	v_cvt_u32_f32_e32 v14, v14
	v_cvt_u32_f32_e32 v6, v6
	v_cvt_u32_f32_e32 v7, v7
	v_rcp_f32_e32 v8, v8
	v_rcp_f32_e32 v9, v9
	v_lshl_or_b32 v10, v19, 8, v2
	v_lshl_or_b32 v11, v18, 8, v3
	v_pk_fma_f32 v[2:3], v[12:13], s[16:17], 0.5 op_sel_hi:[1,0,0]
	v_lshl_or_b32 v6, v14, 8, v6
	v_lshl_or_b32 v7, v15, 8, v7
	v_pk_fma_f32 v[4:5], v[4:5], s[16:17], 0.5 op_sel_hi:[1,0,0]
	v_cvt_u32_f32_sdwa v14, v3 dst_sel:WORD_1 dst_unused:UNUSED_PAD src0_sel:DWORD
	v_cvt_u32_f32_sdwa v15, v2 dst_sel:WORD_1 dst_unused:UNUSED_PAD src0_sel:DWORD
	v_pk_fma_f32 v[2:3], v[16:17], s[16:17], 0.5 op_sel_hi:[1,0,0]
	v_cvt_u32_f32_sdwa v12, v5 dst_sel:WORD_1 dst_unused:UNUSED_PAD src0_sel:DWORD
	v_cvt_u32_f32_sdwa v13, v4 dst_sel:WORD_1 dst_unused:UNUSED_PAD src0_sel:DWORD
	v_pk_fma_f32 v[4:5], v[8:9], s[16:17], 0.5 op_sel_hi:[1,0,0]
	v_cvt_u32_f32_sdwa v2, v2 dst_sel:BYTE_3 dst_unused:UNUSED_PAD src0_sel:DWORD
	v_cvt_u32_f32_sdwa v5, v5 dst_sel:BYTE_3 dst_unused:UNUSED_PAD src0_sel:DWORD
	v_cvt_u32_f32_sdwa v4, v4 dst_sel:BYTE_3 dst_unused:UNUSED_PAD src0_sel:DWORD
	v_cvt_u32_f32_sdwa v3, v3 dst_sel:BYTE_3 dst_unused:UNUSED_PAD src0_sel:DWORD
	v_or3_b32 v2, v6, v15, v2
	v_add_co_u32_e32 v6, vcc, 0xe000, v156
	v_or3_b32 v5, v11, v12, v5
	v_or3_b32 v4, v10, v13, v4
	v_or3_b32 v3, v7, v14, v3
	v_addc_co_u32_e32 v7, vcc, 0, v157, vcc
	global_store_dwordx4 v[6:7], v[2:5], off
	s_andn2_b64 vcc, exec, s[40:41]
	s_mov_b64 s[18:19], -1
	s_cbranch_vccnz .LBB0_277
